# peel first K-iteration (srcC=0, no acc zeroing) + snake MFMA order in GEMM loops
# speedup vs baseline: 1.0074x; 1.0074x over previous
; #define PG8_STAGE(bufoff, gbase, V0, V1) do { \
;         __builtin_amdgcn_global_load_lds((const unsigned*)((const char*)(gbase) + (V0)), (LAS unsigned*)(lds + (bufoff) + ldsw), 16, 0, 0); \
;         __builtin_amdgcn_global_load_lds((const unsigned*)((const char*)(gbase) + (V1)), (LAS unsigned*)(lds + (bufoff) + ldsw + 8192), 16, 0, 0); } while (0)
; #define PG8_LDA(dst, b, h) do { _Pragma("unroll") for (int m = 0; m < 4; ++m) _Pragma("unroll") for (int k = 0; k < 2; ++k) dst[m][k] = *(const LAS bf16x8*)(lds + PG8_SA(b, h) + aoff + m * 2048 + k * 1024); } while (0)
; #define PG8_LDB(dst, b, h) do { _Pragma("unroll") for (int n = 0; n < 2; ++n) _Pragma("unroll") for (int k = 0; k < 2; ++k) dst[n][k] = *(const LAS bf16x8*)(lds + PG8_SB(b, h) + boff + n * 2048 + k * 1024); } while (0)
; #define PG8_WAIT_V(n) asm volatile("s_waitcnt vmcnt(" #n ")" ::: "memory")
; template <class Epi, class Sched>
; DI void gemm_phase(LAS unsigned char* lds, const int lda2, const int ldb2, const int nt, const Sched& S, const Epi& E) {
;     ...
;     f32x4 acc[2][2][4][2];
; #pragma unroll
;     for (int a = 0; a < 2; ++a)
; #pragma unroll
;         for (int b = 0; b < 2; ++b)
; #pragma unroll
;             for (int m = 0; m < 4; ++m)
; #pragma unroll
;                 for (int n = 0; n < 2; ++n) acc[a][b][m][n] = (f32x4){0.f, 0.f, 0.f, 0.f};
;     ...
;     for (;;) {
;         const bool has_next = S.next(ui + 1, nxt);
;         const char* nA = has_next ? nxt.A : cA; const char* nB = has_next ? nxt.B : cB;
;         for (int t = 0; t < nt; t += 2) {
;             const bool last = (t == nt - 2);
;             const char* a1 = cA + (size_t)(t + 1) * kstep;
;             const char* a2 = last ? nA : cA + (size_t)(t + 2) * kstep; const char* b2 = last ? nB : cB + (size_t)(t + 2) * kstep;
;             const char* a3 = a2 + kstep; const char* b3 = b2 + kstep;
;             PG8_LDB(B0, 0, 0); PG8_LDB(B1, 0, 1); PG8_SCHED; PG8_LDA(At, 0, 0); PG8_STAGE(PG8_SA(1, 1), a1 + hstepA, vA0, vA1);
;             PG8_WAIT_V(8); PG8_WAIT_L(0); PG8_BAR; PG8_MMA(0, 0, At, B0); PG8_MMA(0, 1, At, B1); PG8_BAR; PG8_SCHED;
;             PG8_LDA(At, 0, 1); PG8_STAGE(PG8_SB(0, 0), b2, vB0, vB1); PG8_STAGE(PG8_SB(0, 1), b2 + hstepB, vB0, vB1); PG8_STAGE(PG8_SA(0, 0), a2, vA0, vA1);
;             PG8_WAIT_V(8); PG8_WAIT_L(0); PG8_BAR; PG8_MMA(1, 0, At, B0); PG8_MMA(1, 1, At, B1); PG8_BAR; PG8_SCHED;
.LBB0_198:
	s_add_u32 s4, s4, 0x40080
	s_addc_u32 s5, s5, 0
	s_add_u32 s7, s22, 0x100
	s_addc_u32 s15, s23, 0
	s_mov_b32 s17, -2
	s_add_u32 s22, s4, 0xfffc0080
	s_addc_u32 s23, s5, -1
	s_add_i32 s27, 0, 0x10000
	s_cmp_eq_u32 s17, 12
	s_cselect_b32 s25, s19, s23
	s_cselect_b32 s24, s18, s22
	s_cselect_b32 s23, s21, s15
	s_cselect_b32 s22, s20, s7
	s_add_i32 s48, 0, 0x14000
	v_add_u32_e32 v152, s27, v158
	v_add_u32_e32 v172, s48, v158
	ds_read_b128 v[140:143], v152
	ds_read_b128 v[144:147], v152 offset:1024
	ds_read_b128 v[148:151], v152 offset:2048
	ds_read_b128 v[152:155], v152 offset:3072
	ds_read_b128 v[160:163], v172
	ds_read_b128 v[164:167], v172 offset:1024
	ds_read_b128 v[168:171], v172 offset:2048
	ds_read_b128 v[172:175], v172 offset:3072
	v_lshl_add_u64 v[214:215], s[4:5], 0, v[136:137]
	s_add_i32 m0, s55, 0xc000
	ds_read_b128 v[176:179], v159
	ds_read_b128 v[180:183], v159 offset:1024
	ds_read_b128 v[184:187], v159 offset:2048
	ds_read_b128 v[188:191], v159 offset:3072
	ds_read_b128 v[192:195], v159 offset:4096
	ds_read_b128 v[202:205], v159 offset:5120
	ds_read_b128 v[206:209], v159 offset:6144
	ds_read_b128 v[210:213], v159 offset:7168
	global_load_lds_dwordx4 v[214:215], off
	v_lshl_add_u64 v[214:215], s[4:5], 0, v[138:139]
	s_add_i32 m0, s55, 0xe000
	s_nop 0
	global_load_lds_dwordx4 v[214:215], off
	s_waitcnt vmcnt(8)
	s_waitcnt lgkmcnt(0)
	s_barrier
	s_setprio 1
	s_waitcnt lgkmcnt(0)
	v_mfma_f32_16x16x32_bf16 v[126:129], v[140:143], v[176:179], 0
	v_mfma_f32_16x16x32_bf16 v[122:125], v[148:151], v[176:179], 0
	v_mfma_f32_16x16x32_bf16 v[106:109], v[148:151], v[184:187], 0
	v_mfma_f32_16x16x32_bf16 v[110:113], v[140:143], v[184:187], 0
	v_mfma_f32_16x16x32_bf16 v[92:95], v[140:143], v[192:195], 0
	v_mfma_f32_16x16x32_bf16 v[88:91], v[148:151], v[192:195], 0
	v_mfma_f32_16x16x32_bf16 v[72:75], v[148:151], v[206:209], 0
	v_mfma_f32_16x16x32_bf16 v[76:79], v[140:143], v[206:209], 0
	v_mfma_f32_16x16x32_bf16 v[126:129], v[144:147], v[180:183], v[126:129]
	v_mfma_f32_16x16x32_bf16 v[122:125], v[152:155], v[180:183], v[122:125]
	v_mfma_f32_16x16x32_bf16 v[106:109], v[152:155], v[188:191], v[106:109]
	v_mfma_f32_16x16x32_bf16 v[110:113], v[144:147], v[188:191], v[110:113]
	v_mfma_f32_16x16x32_bf16 v[92:95], v[144:147], v[202:205], v[92:95]
	v_mfma_f32_16x16x32_bf16 v[88:91], v[152:155], v[202:205], v[88:91]
	v_mfma_f32_16x16x32_bf16 v[72:75], v[152:155], v[210:213], v[72:75]
	v_mfma_f32_16x16x32_bf16 v[76:79], v[144:147], v[210:213], v[76:79]
	s_setprio 0
	s_setprio 1
	v_mfma_f32_16x16x32_bf16 v[118:121], v[160:163], v[176:179], 0
	v_mfma_f32_16x16x32_bf16 v[114:117], v[168:171], v[176:179], 0
	v_mfma_f32_16x16x32_bf16 v[98:101], v[168:171], v[184:187], 0
	v_mfma_f32_16x16x32_bf16 v[102:105], v[160:163], v[184:187], 0
	v_mfma_f32_16x16x32_bf16 v[84:87], v[160:163], v[192:195], 0
	v_mfma_f32_16x16x32_bf16 v[80:83], v[168:171], v[192:195], 0
	v_mfma_f32_16x16x32_bf16 v[64:67], v[168:171], v[206:209], 0
	v_mfma_f32_16x16x32_bf16 v[68:71], v[160:163], v[206:209], 0
	v_mfma_f32_16x16x32_bf16 v[118:121], v[164:167], v[180:183], v[118:121]
	v_mfma_f32_16x16x32_bf16 v[114:117], v[172:175], v[180:183], v[114:117]
	v_mfma_f32_16x16x32_bf16 v[98:101], v[172:175], v[188:191], v[98:101]
	v_mfma_f32_16x16x32_bf16 v[102:105], v[164:167], v[188:191], v[102:105]
	v_mfma_f32_16x16x32_bf16 v[84:87], v[164:167], v[202:205], v[84:87]
	v_mfma_f32_16x16x32_bf16 v[80:83], v[172:175], v[202:205], v[80:83]
	v_mfma_f32_16x16x32_bf16 v[64:67], v[172:175], v[210:213], v[64:67]
	v_mfma_f32_16x16x32_bf16 v[68:71], v[164:167], v[210:213], v[68:71]
	s_setprio 0
	s_barrier
	s_add_i32 s27, s27, s54
	v_lshl_add_u64 v[214:215], s[22:23], 0, v[96:97]
	s_mov_b32 m0, s27
	ds_read_b128 v[176:179], v159 offset:16384
	ds_read_b128 v[180:183], v159 offset:17408
	ds_read_b128 v[184:187], v159 offset:18432
	ds_read_b128 v[188:191], v159 offset:19456
	ds_read_b128 v[192:195], v159 offset:20480
	ds_read_b128 v[202:205], v159 offset:21504
	ds_read_b128 v[206:209], v159 offset:22528
	ds_read_b128 v[210:213], v159 offset:23552
	global_load_lds_dwordx4 v[214:215], off
	s_add_i32 m0, s27, 0x2000
	s_add_u32 s28, s22, 0x40000
	v_lshl_add_u64 v[216:217], s[22:23], 0, v[130:131]
	s_addc_u32 s29, s23, 0
	s_add_i32 s27, s48, s54
	global_load_lds_dwordx4 v[216:217], off
	v_lshl_add_u64 v[218:219], s[28:29], 0, v[96:97]
	s_mov_b32 m0, s27
	v_lshl_add_u64 v[220:221], s[24:25], 0, v[134:135]
	global_load_lds_dwordx4 v[218:219], off
	v_lshl_add_u64 v[218:219], s[28:29], 0, v[130:131]
	s_add_i32 m0, s27, 0x2000
	s_nop 0
	global_load_lds_dwordx4 v[218:219], off
	v_lshl_add_u64 v[218:219], s[24:25], 0, v[132:133]
	s_mov_b32 m0, s55
	s_nop 0
	global_load_lds_dwordx4 v[218:219], off
	s_mov_b32 m0, s72
	s_nop 0
	global_load_lds_dwordx4 v[220:221], off
	s_waitcnt vmcnt(8)
	s_waitcnt lgkmcnt(0)
	s_barrier
; #define PG8_STAGE(bufoff, gbase, V0, V1) do { \
;         __builtin_amdgcn_global_load_lds((const unsigned*)((const char*)(gbase) + (V0)), (LAS unsigned*)(lds + (bufoff) + ldsw), 16, 0, 0); \
;         __builtin_amdgcn_global_load_lds((const unsigned*)((const char*)(gbase) + (V1)), (LAS unsigned*)(lds + (bufoff) + ldsw + 8192), 16, 0, 0); } while (0)
; #define PG8_LDA(dst, b, h) do { _Pragma("unroll") for (int m = 0; m < 4; ++m) _Pragma("unroll") for (int k = 0; k < 2; ++k) dst[m][k] = *(const LAS bf16x8*)(lds + PG8_SA(b, h) + aoff + m * 2048 + k * 1024); } while (0)
; #define PG8_LDB(dst, b, h) do { _Pragma("unroll") for (int n = 0; n < 2; ++n) _Pragma("unroll") for (int k = 0; k < 2; ++k) dst[n][k] = *(const LAS bf16x8*)(lds + PG8_SB(b, h) + boff + n * 2048 + k * 1024); } while (0)
; #define PG8_MMA(ai, bj, At, Bt) do { __builtin_amdgcn_s_setprio(1); _Pragma("unroll") for (int m = 0; m < 4; ++m) _Pragma("unroll") for (int n = 0; n < 2; ++n) _Pragma("unroll") for (int k = 0; k < 2; ++k) \
;         acc[ai][bj][m][n] = __builtin_amdgcn_mfma_f32_16x16x32_bf16(Bt[n][k], At[m][k], acc[ai][bj][m][n], 0, 0, 0); __builtin_amdgcn_s_setprio(0); } while (0)
; #define PG8_WAIT_V(n) asm volatile("s_waitcnt vmcnt(" #n ")" ::: "memory")
; #define PG8_WAIT_L(n) asm volatile("s_waitcnt lgkmcnt(" #n ")" ::: "memory")
; #define PG8_BAR __builtin_amdgcn_s_barrier()
; #define PG8_SCHED __builtin_amdgcn_sched_barrier(0)
; template <class Epi, class Sched>
; DI void gemm_phase(LAS unsigned char* lds, const int lda2, const int ldb2, const int nt, const Sched& S, const Epi& E) {
;     ...
;             PG8_WAIT_V(8); PG8_WAIT_L(0); PG8_BAR; PG8_MMA(0, 0, At, B0); PG8_MMA(0, 1, At, B1); PG8_BAR; PG8_SCHED;
;             PG8_LDA(At, 0, 1); PG8_STAGE(PG8_SB(0, 0), b2, vB0, vB1); PG8_STAGE(PG8_SB(0, 1), b2 + hstepB, vB0, vB1); PG8_STAGE(PG8_SA(0, 0), a2, vA0, vA1);
;             PG8_WAIT_V(8); PG8_WAIT_L(0); PG8_BAR; PG8_MMA(1, 0, At, B0); PG8_MMA(1, 1, At, B1); PG8_BAR; PG8_SCHED;
;             PG8_LDB(B0, 1, 0); PG8_LDB(B1, 1, 1); PG8_SCHED; PG8_LDA(At, 1, 0); PG8_STAGE(PG8_SA(0, 1), a2 + hstepA, vA0, vA1);
;             PG8_WAIT_V(8); PG8_WAIT_L(0); PG8_BAR; PG8_MMA(0, 0, At, B0); PG8_MMA(0, 1, At, B1); PG8_BAR; PG8_SCHED;
	s_setprio 1
	s_waitcnt lgkmcnt(0)
	v_mfma_f32_16x16x32_bf16 v[60:63], v[140:143], v[176:179], 0
	v_mfma_f32_16x16x32_bf16 v[56:59], v[148:151], v[176:179], 0
	v_mfma_f32_16x16x32_bf16 v[40:43], v[148:151], v[184:187], 0
	v_mfma_f32_16x16x32_bf16 v[44:47], v[140:143], v[184:187], 0
	v_mfma_f32_16x16x32_bf16 v[28:31], v[140:143], v[192:195], 0
	v_mfma_f32_16x16x32_bf16 v[24:27], v[148:151], v[192:195], 0
	v_mfma_f32_16x16x32_bf16 v[8:11], v[148:151], v[206:209], 0
	v_mfma_f32_16x16x32_bf16 v[12:15], v[140:143], v[206:209], 0
	v_mfma_f32_16x16x32_bf16 v[60:63], v[144:147], v[180:183], v[60:63]
	v_mfma_f32_16x16x32_bf16 v[56:59], v[152:155], v[180:183], v[56:59]
	v_mfma_f32_16x16x32_bf16 v[40:43], v[152:155], v[188:191], v[40:43]
	v_mfma_f32_16x16x32_bf16 v[44:47], v[144:147], v[188:191], v[44:47]
	v_mfma_f32_16x16x32_bf16 v[28:31], v[144:147], v[202:205], v[28:31]
	v_mfma_f32_16x16x32_bf16 v[24:27], v[152:155], v[202:205], v[24:27]
	v_mfma_f32_16x16x32_bf16 v[8:11], v[152:155], v[210:213], v[8:11]
	v_mfma_f32_16x16x32_bf16 v[12:15], v[144:147], v[210:213], v[12:15]
	s_setprio 0
	s_setprio 1
	v_mfma_f32_16x16x32_bf16 v[52:55], v[160:163], v[176:179], 0
	v_mfma_f32_16x16x32_bf16 v[48:51], v[168:171], v[176:179], 0
	v_mfma_f32_16x16x32_bf16 v[32:35], v[168:171], v[184:187], 0
	v_mfma_f32_16x16x32_bf16 v[36:39], v[160:163], v[184:187], 0
	v_mfma_f32_16x16x32_bf16 v[20:23], v[160:163], v[192:195], 0
	v_mfma_f32_16x16x32_bf16 v[16:19], v[168:171], v[192:195], 0
	v_mfma_f32_16x16x32_bf16 v[0:3], v[168:171], v[206:209], 0
	v_mfma_f32_16x16x32_bf16 v[4:7], v[160:163], v[206:209], 0
	v_mfma_f32_16x16x32_bf16 v[52:55], v[164:167], v[180:183], v[52:55]
	v_mfma_f32_16x16x32_bf16 v[48:51], v[172:175], v[180:183], v[48:51]
	v_mfma_f32_16x16x32_bf16 v[32:35], v[172:175], v[188:191], v[32:35]
	v_mfma_f32_16x16x32_bf16 v[36:39], v[164:167], v[188:191], v[36:39]
	v_mfma_f32_16x16x32_bf16 v[20:23], v[164:167], v[202:205], v[20:23]
	v_mfma_f32_16x16x32_bf16 v[16:19], v[172:175], v[202:205], v[16:19]
	v_mfma_f32_16x16x32_bf16 v[0:3], v[172:175], v[210:213], v[0:3]
	v_mfma_f32_16x16x32_bf16 v[4:7], v[164:167], v[210:213], v[4:7]
	s_setprio 0
	s_barrier
	s_add_i32 s27, 0, 0x18000
	s_add_i32 s28, 0, 0x1c000
	v_add_u32_e32 v152, s27, v158
	v_add_u32_e32 v172, s28, v158
	ds_read_b128 v[140:143], v152
	ds_read_b128 v[144:147], v152 offset:1024
	ds_read_b128 v[148:151], v152 offset:2048
	ds_read_b128 v[152:155], v152 offset:3072
	ds_read_b128 v[160:163], v172
	ds_read_b128 v[164:167], v172 offset:1024
	ds_read_b128 v[168:171], v172 offset:2048
	ds_read_b128 v[172:175], v172 offset:3072
	s_add_u32 s24, s24, 0x40000
	s_addc_u32 s25, s25, 0
	s_mov_b32 m0, s73
	v_lshl_add_u64 v[222:223], s[24:25], 0, v[132:133]
	ds_read_b128 v[176:179], v159 offset:32768
	ds_read_b128 v[180:183], v159 offset:33792
	ds_read_b128 v[184:187], v159 offset:34816
	ds_read_b128 v[188:191], v159 offset:35840
	ds_read_b128 v[192:195], v159 offset:36864
	ds_read_b128 v[202:205], v159 offset:37888
	ds_read_b128 v[206:209], v159 offset:38912
	ds_read_b128 v[210:213], v159 offset:39936
	global_load_lds_dwordx4 v[222:223], off
	v_lshl_add_u64 v[222:223], s[24:25], 0, v[134:135]
	s_mov_b32 m0, s74
	s_nop 0
	global_load_lds_dwordx4 v[222:223], off
	s_waitcnt vmcnt(8)
	s_waitcnt lgkmcnt(0)
	s_barrier
	s_setprio 1
	s_waitcnt lgkmcnt(0)
	v_mfma_f32_16x16x32_bf16 v[126:129], v[140:143], v[176:179], v[126:129]
	v_mfma_f32_16x16x32_bf16 v[122:125], v[148:151], v[176:179], v[122:125]
	v_mfma_f32_16x16x32_bf16 v[106:109], v[148:151], v[184:187], v[106:109]
	v_mfma_f32_16x16x32_bf16 v[110:113], v[140:143], v[184:187], v[110:113]
	v_mfma_f32_16x16x32_bf16 v[92:95], v[140:143], v[192:195], v[92:95]
	v_mfma_f32_16x16x32_bf16 v[88:91], v[148:151], v[192:195], v[88:91]
	v_mfma_f32_16x16x32_bf16 v[72:75], v[148:151], v[206:209], v[72:75]
	v_mfma_f32_16x16x32_bf16 v[76:79], v[140:143], v[206:209], v[76:79]
	v_mfma_f32_16x16x32_bf16 v[126:129], v[144:147], v[180:183], v[126:129]
	v_mfma_f32_16x16x32_bf16 v[122:125], v[152:155], v[180:183], v[122:125]
	v_mfma_f32_16x16x32_bf16 v[106:109], v[152:155], v[188:191], v[106:109]
	v_mfma_f32_16x16x32_bf16 v[110:113], v[144:147], v[188:191], v[110:113]
	v_mfma_f32_16x16x32_bf16 v[92:95], v[144:147], v[202:205], v[92:95]
	v_mfma_f32_16x16x32_bf16 v[88:91], v[152:155], v[202:205], v[88:91]
	v_mfma_f32_16x16x32_bf16 v[72:75], v[152:155], v[210:213], v[72:75]
	v_mfma_f32_16x16x32_bf16 v[76:79], v[144:147], v[210:213], v[76:79]
	s_setprio 0
	s_setprio 1
	v_mfma_f32_16x16x32_bf16 v[118:121], v[160:163], v[176:179], v[118:121]
	v_mfma_f32_16x16x32_bf16 v[114:117], v[168:171], v[176:179], v[114:117]
	v_mfma_f32_16x16x32_bf16 v[98:101], v[168:171], v[184:187], v[98:101]
	v_mfma_f32_16x16x32_bf16 v[102:105], v[160:163], v[184:187], v[102:105]
	v_mfma_f32_16x16x32_bf16 v[84:87], v[160:163], v[192:195], v[84:87]
	v_mfma_f32_16x16x32_bf16 v[80:83], v[168:171], v[192:195], v[80:83]
	v_mfma_f32_16x16x32_bf16 v[64:67], v[168:171], v[206:209], v[64:67]
	v_mfma_f32_16x16x32_bf16 v[68:71], v[160:163], v[206:209], v[68:71]
	v_mfma_f32_16x16x32_bf16 v[118:121], v[164:167], v[180:183], v[118:121]
	v_mfma_f32_16x16x32_bf16 v[114:117], v[172:175], v[180:183], v[114:117]
	v_mfma_f32_16x16x32_bf16 v[98:101], v[172:175], v[188:191], v[98:101]
	v_mfma_f32_16x16x32_bf16 v[102:105], v[164:167], v[188:191], v[102:105]
	v_mfma_f32_16x16x32_bf16 v[84:87], v[164:167], v[202:205], v[84:87]
	v_mfma_f32_16x16x32_bf16 v[80:83], v[172:175], v[202:205], v[80:83]
	v_mfma_f32_16x16x32_bf16 v[64:67], v[172:175], v[210:213], v[64:67]
	v_mfma_f32_16x16x32_bf16 v[68:71], v[164:167], v[210:213], v[68:71]
	s_setprio 0
	s_barrier
; #define PG8_STAGE(bufoff, gbase, V0, V1) do { \
;         __builtin_amdgcn_global_load_lds((const unsigned*)((const char*)(gbase) + (V0)), (LAS unsigned*)(lds + (bufoff) + ldsw), 16, 0, 0); \
;         __builtin_amdgcn_global_load_lds((const unsigned*)((const char*)(gbase) + (V1)), (LAS unsigned*)(lds + (bufoff) + ldsw + 8192), 16, 0, 0); } while (0)
; #define PG8_LDA(dst, b, h) do { _Pragma("unroll") for (int m = 0; m < 4; ++m) _Pragma("unroll") for (int k = 0; k < 2; ++k) dst[m][k] = *(const LAS bf16x8*)(lds + PG8_SA(b, h) + aoff + m * 2048 + k * 1024); } while (0)
; #define PG8_LDB(dst, b, h) do { _Pragma("unroll") for (int n = 0; n < 2; ++n) _Pragma("unroll") for (int k = 0; k < 2; ++k) dst[n][k] = *(const LAS bf16x8*)(lds + PG8_SB(b, h) + boff + n * 2048 + k * 1024); } while (0)
; #define PG8_WAIT_V(n) asm volatile("s_waitcnt vmcnt(" #n ")" ::: "memory")
; #define PG8_WAIT_L(n) asm volatile("s_waitcnt lgkmcnt(" #n ")" ::: "memory")
; #define PG8_BAR __builtin_amdgcn_s_barrier()
; #define PG8_SCHED __builtin_amdgcn_sched_barrier(0)
; template <class Epi, class Sched>
; DI void gemm_phase(LAS unsigned char* lds, const int lda2, const int ldb2, const int nt, const Sched& S, const Epi& E) {
;     ...
;         for (int t = 0; t < nt; t += 2) {
;             const bool last = (t == nt - 2);
;             const char* a1 = cA + (size_t)(t + 1) * kstep;
;             const char* a2 = last ? nA : cA + (size_t)(t + 2) * kstep; const char* b2 = last ? nB : cB + (size_t)(t + 2) * kstep;
;             const char* a3 = a2 + kstep; const char* b3 = b2 + kstep;
;             PG8_LDB(B0, 0, 0); PG8_LDB(B1, 0, 1); PG8_SCHED; PG8_LDA(At, 0, 0); PG8_STAGE(PG8_SA(1, 1), a1 + hstepA, vA0, vA1);
;             PG8_WAIT_V(8); PG8_WAIT_L(0); PG8_BAR; PG8_MMA(0, 0, At, B0); PG8_MMA(0, 1, At, B1); PG8_BAR; PG8_SCHED;
;     ...
;             PG8_LDB(B0, 1, 0); PG8_LDB(B1, 1, 1); PG8_SCHED; PG8_LDA(At, 1, 0); PG8_STAGE(PG8_SA(0, 1), a2 + hstepA, vA0, vA1);
;             PG8_WAIT_V(8); PG8_WAIT_L(0); PG8_BAR; PG8_MMA(0, 0, At, B0); PG8_MMA(0, 1, At, B1); PG8_BAR; PG8_SCHED;
;             PG8_LDA(At, 1, 1); PG8_STAGE(PG8_SB(1, 0), b3, vB0, vB1); PG8_STAGE(PG8_SB(1, 1), b3 + hstepB, vB0, vB1); PG8_STAGE(PG8_SA(1, 0), a3, vA0, vA1);
;             PG8_WAIT_V(8); PG8_WAIT_L(0); PG8_BAR; PG8_MMA(1, 0, At, B0); PG8_MMA(1, 1, At, B1); PG8_BAR; PG8_SCHED;
	s_add_i32 s24, s27, s54
	v_lshl_add_u64 v[214:215], v[214:215], 0, s[86:87]
	s_mov_b32 m0, s24
	ds_read_b128 v[176:179], v159 offset:49152
	ds_read_b128 v[180:183], v159 offset:50176
	ds_read_b128 v[184:187], v159 offset:51200
	ds_read_b128 v[188:191], v159 offset:52224
	ds_read_b128 v[192:195], v159 offset:53248
	ds_read_b128 v[202:205], v159 offset:54272
	ds_read_b128 v[206:209], v159 offset:55296
	ds_read_b128 v[210:213], v159 offset:56320
	global_load_lds_dwordx4 v[214:215], off
	s_add_i32 m0, s24, 0x2000
	s_add_u32 s22, s22, 0x40080
	v_lshl_add_u64 v[214:215], v[216:217], 0, s[86:87]
	s_addc_u32 s23, s23, 0
	s_add_i32 s24, s28, s54
	global_load_lds_dwordx4 v[214:215], off
	v_lshl_add_u64 v[214:215], s[22:23], 0, v[96:97]
	s_mov_b32 m0, s24
	s_nop 0
	global_load_lds_dwordx4 v[214:215], off
	v_lshl_add_u64 v[214:215], s[22:23], 0, v[130:131]
	s_add_i32 m0, s24, 0x2000
	s_nop 0
	global_load_lds_dwordx4 v[214:215], off
	v_lshl_add_u64 v[214:215], v[218:219], 0, s[86:87]
	s_mov_b32 m0, s77
	s_nop 0
	global_load_lds_dwordx4 v[214:215], off
	v_lshl_add_u64 v[214:215], v[220:221], 0, s[86:87]
	s_mov_b32 m0, s78
	s_nop 0
	global_load_lds_dwordx4 v[214:215], off
	s_waitcnt vmcnt(8)
	s_waitcnt lgkmcnt(0)
	s_barrier
	s_setprio 1
	s_waitcnt lgkmcnt(0)
	v_mfma_f32_16x16x32_bf16 v[60:63], v[140:143], v[176:179], v[60:63]
	v_mfma_f32_16x16x32_bf16 v[56:59], v[148:151], v[176:179], v[56:59]
	v_mfma_f32_16x16x32_bf16 v[40:43], v[148:151], v[184:187], v[40:43]
	v_mfma_f32_16x16x32_bf16 v[44:47], v[140:143], v[184:187], v[44:47]
	v_mfma_f32_16x16x32_bf16 v[28:31], v[140:143], v[192:195], v[28:31]
	v_mfma_f32_16x16x32_bf16 v[24:27], v[148:151], v[192:195], v[24:27]
	v_mfma_f32_16x16x32_bf16 v[8:11], v[148:151], v[206:209], v[8:11]
	v_mfma_f32_16x16x32_bf16 v[12:15], v[140:143], v[206:209], v[12:15]
	v_mfma_f32_16x16x32_bf16 v[60:63], v[144:147], v[180:183], v[60:63]
	v_mfma_f32_16x16x32_bf16 v[56:59], v[152:155], v[180:183], v[56:59]
	v_mfma_f32_16x16x32_bf16 v[40:43], v[152:155], v[188:191], v[40:43]
	v_mfma_f32_16x16x32_bf16 v[44:47], v[144:147], v[188:191], v[44:47]
	v_mfma_f32_16x16x32_bf16 v[28:31], v[144:147], v[202:205], v[28:31]
	v_mfma_f32_16x16x32_bf16 v[24:27], v[152:155], v[202:205], v[24:27]
	v_mfma_f32_16x16x32_bf16 v[8:11], v[152:155], v[210:213], v[8:11]
	v_mfma_f32_16x16x32_bf16 v[12:15], v[144:147], v[210:213], v[12:15]
	s_setprio 0
	s_setprio 1
	v_mfma_f32_16x16x32_bf16 v[52:55], v[160:163], v[176:179], v[52:55]
	v_mfma_f32_16x16x32_bf16 v[48:51], v[168:171], v[176:179], v[48:51]
	v_mfma_f32_16x16x32_bf16 v[32:35], v[168:171], v[184:187], v[32:35]
	v_mfma_f32_16x16x32_bf16 v[36:39], v[160:163], v[184:187], v[36:39]
	v_mfma_f32_16x16x32_bf16 v[20:23], v[160:163], v[192:195], v[20:23]
	v_mfma_f32_16x16x32_bf16 v[16:19], v[168:171], v[192:195], v[16:19]
	v_mfma_f32_16x16x32_bf16 v[0:3], v[168:171], v[206:209], v[0:3]
	v_mfma_f32_16x16x32_bf16 v[4:7], v[160:163], v[206:209], v[4:7]
	v_mfma_f32_16x16x32_bf16 v[52:55], v[164:167], v[180:183], v[52:55]
	v_mfma_f32_16x16x32_bf16 v[48:51], v[172:175], v[180:183], v[48:51]
	v_mfma_f32_16x16x32_bf16 v[32:35], v[172:175], v[188:191], v[32:35]
	v_mfma_f32_16x16x32_bf16 v[36:39], v[164:167], v[188:191], v[36:39]
	v_mfma_f32_16x16x32_bf16 v[20:23], v[164:167], v[202:205], v[20:23]
	v_mfma_f32_16x16x32_bf16 v[16:19], v[172:175], v[202:205], v[16:19]
	v_mfma_f32_16x16x32_bf16 v[0:3], v[172:175], v[210:213], v[0:3]
	v_mfma_f32_16x16x32_bf16 v[4:7], v[164:167], v[210:213], v[4:7]
	s_setprio 0
	s_barrier
	s_add_i32 s17, s17, 2
	s_add_u32 s4, s4, 0x100
	s_addc_u32 s5, s5, 0
	s_add_u32 s7, s7, 0x100
	s_addc_u32 s15, s15, 0
.LBB0_199:
	s_add_u32 s22, s4, 0xfffc0080
	s_addc_u32 s23, s5, -1
	s_add_i32 s27, 0, 0x10000
	s_cmp_eq_u32 s17, 12
	s_cselect_b32 s25, s19, s23
	s_cselect_b32 s24, s18, s22
	s_cselect_b32 s23, s21, s15
	s_cselect_b32 s22, s20, s7
	s_add_i32 s48, 0, 0x14000
	v_add_u32_e32 v152, s27, v158
	v_add_u32_e32 v172, s48, v158
	ds_read_b128 v[140:143], v152
	ds_read_b128 v[144:147], v152 offset:1024
	ds_read_b128 v[148:151], v152 offset:2048
	ds_read_b128 v[152:155], v152 offset:3072
	ds_read_b128 v[160:163], v172
	ds_read_b128 v[164:167], v172 offset:1024
	ds_read_b128 v[168:171], v172 offset:2048
	ds_read_b128 v[172:175], v172 offset:3072
	v_lshl_add_u64 v[214:215], s[4:5], 0, v[136:137]
	s_add_i32 m0, s55, 0xc000
	ds_read_b128 v[176:179], v159
	ds_read_b128 v[180:183], v159 offset:1024
	ds_read_b128 v[184:187], v159 offset:2048
	ds_read_b128 v[188:191], v159 offset:3072
	ds_read_b128 v[192:195], v159 offset:4096
	ds_read_b128 v[202:205], v159 offset:5120
	ds_read_b128 v[206:209], v159 offset:6144
	ds_read_b128 v[210:213], v159 offset:7168
	global_load_lds_dwordx4 v[214:215], off
	v_lshl_add_u64 v[214:215], s[4:5], 0, v[138:139]
	s_add_i32 m0, s55, 0xe000
	s_nop 0
	global_load_lds_dwordx4 v[214:215], off
	s_waitcnt vmcnt(8)
	s_waitcnt lgkmcnt(0)
	s_barrier
; #define PG8_STAGE(bufoff, gbase, V0, V1) do { \
;         __builtin_amdgcn_global_load_lds((const unsigned*)((const char*)(gbase) + (V0)), (LAS unsigned*)(lds + (bufoff) + ldsw), 16, 0, 0); \
;         __builtin_amdgcn_global_load_lds((const unsigned*)((const char*)(gbase) + (V1)), (LAS unsigned*)(lds + (bufoff) + ldsw + 8192), 16, 0, 0); } while (0)
; #define PG8_LDA(dst, b, h) do { _Pragma("unroll") for (int m = 0; m < 4; ++m) _Pragma("unroll") for (int k = 0; k < 2; ++k) dst[m][k] = *(const LAS bf16x8*)(lds + PG8_SA(b, h) + aoff + m * 2048 + k * 1024); } while (0)
; #define PG8_LDB(dst, b, h) do { _Pragma("unroll") for (int n = 0; n < 2; ++n) _Pragma("unroll") for (int k = 0; k < 2; ++k) dst[n][k] = *(const LAS bf16x8*)(lds + PG8_SB(b, h) + boff + n * 2048 + k * 1024); } while (0)
; #define PG8_MMA(ai, bj, At, Bt) do { __builtin_amdgcn_s_setprio(1); _Pragma("unroll") for (int m = 0; m < 4; ++m) _Pragma("unroll") for (int n = 0; n < 2; ++n) _Pragma("unroll") for (int k = 0; k < 2; ++k) \
;         acc[ai][bj][m][n] = __builtin_amdgcn_mfma_f32_16x16x32_bf16(Bt[n][k], At[m][k], acc[ai][bj][m][n], 0, 0, 0); __builtin_amdgcn_s_setprio(0); } while (0)
; #define PG8_WAIT_V(n) asm volatile("s_waitcnt vmcnt(" #n ")" ::: "memory")
; #define PG8_WAIT_L(n) asm volatile("s_waitcnt lgkmcnt(" #n ")" ::: "memory")
; #define PG8_BAR __builtin_amdgcn_s_barrier()
; #define PG8_SCHED __builtin_amdgcn_sched_barrier(0)
; template <class Epi, class Sched>
; DI void gemm_phase(LAS unsigned char* lds, const int lda2, const int ldb2, const int nt, const Sched& S, const Epi& E) {
;     ...
;             PG8_WAIT_V(8); PG8_WAIT_L(0); PG8_BAR; PG8_MMA(0, 0, At, B0); PG8_MMA(0, 1, At, B1); PG8_BAR; PG8_SCHED;
;             PG8_LDA(At, 0, 1); PG8_STAGE(PG8_SB(0, 0), b2, vB0, vB1); PG8_STAGE(PG8_SB(0, 1), b2 + hstepB, vB0, vB1); PG8_STAGE(PG8_SA(0, 0), a2, vA0, vA1);
;             PG8_WAIT_V(8); PG8_WAIT_L(0); PG8_BAR; PG8_MMA(1, 0, At, B0); PG8_MMA(1, 1, At, B1); PG8_BAR; PG8_SCHED;
;             PG8_LDB(B0, 1, 0); PG8_LDB(B1, 1, 1); PG8_SCHED; PG8_LDA(At, 1, 0); PG8_STAGE(PG8_SA(0, 1), a2 + hstepA, vA0, vA1);
;             PG8_WAIT_V(8); PG8_WAIT_L(0); PG8_BAR; PG8_MMA(0, 0, At, B0); PG8_MMA(0, 1, At, B1); PG8_BAR; PG8_SCHED;
	s_setprio 1
	s_waitcnt lgkmcnt(0)
	v_mfma_f32_16x16x32_bf16 v[126:129], v[140:143], v[176:179], v[126:129]
	v_mfma_f32_16x16x32_bf16 v[122:125], v[148:151], v[176:179], v[122:125]
	v_mfma_f32_16x16x32_bf16 v[106:109], v[148:151], v[184:187], v[106:109]
	v_mfma_f32_16x16x32_bf16 v[110:113], v[140:143], v[184:187], v[110:113]
	v_mfma_f32_16x16x32_bf16 v[92:95], v[140:143], v[192:195], v[92:95]
	v_mfma_f32_16x16x32_bf16 v[88:91], v[148:151], v[192:195], v[88:91]
	v_mfma_f32_16x16x32_bf16 v[72:75], v[148:151], v[206:209], v[72:75]
	v_mfma_f32_16x16x32_bf16 v[76:79], v[140:143], v[206:209], v[76:79]
	v_mfma_f32_16x16x32_bf16 v[126:129], v[144:147], v[180:183], v[126:129]
	v_mfma_f32_16x16x32_bf16 v[122:125], v[152:155], v[180:183], v[122:125]
	v_mfma_f32_16x16x32_bf16 v[106:109], v[152:155], v[188:191], v[106:109]
	v_mfma_f32_16x16x32_bf16 v[110:113], v[144:147], v[188:191], v[110:113]
	v_mfma_f32_16x16x32_bf16 v[92:95], v[144:147], v[202:205], v[92:95]
	v_mfma_f32_16x16x32_bf16 v[88:91], v[152:155], v[202:205], v[88:91]
	v_mfma_f32_16x16x32_bf16 v[72:75], v[152:155], v[210:213], v[72:75]
	v_mfma_f32_16x16x32_bf16 v[76:79], v[144:147], v[210:213], v[76:79]
	s_setprio 0
	s_setprio 1
	v_mfma_f32_16x16x32_bf16 v[118:121], v[160:163], v[176:179], v[118:121]
	v_mfma_f32_16x16x32_bf16 v[114:117], v[168:171], v[176:179], v[114:117]
	v_mfma_f32_16x16x32_bf16 v[98:101], v[168:171], v[184:187], v[98:101]
	v_mfma_f32_16x16x32_bf16 v[102:105], v[160:163], v[184:187], v[102:105]
	v_mfma_f32_16x16x32_bf16 v[84:87], v[160:163], v[192:195], v[84:87]
	v_mfma_f32_16x16x32_bf16 v[80:83], v[168:171], v[192:195], v[80:83]
	v_mfma_f32_16x16x32_bf16 v[64:67], v[168:171], v[206:209], v[64:67]
	v_mfma_f32_16x16x32_bf16 v[68:71], v[160:163], v[206:209], v[68:71]
	v_mfma_f32_16x16x32_bf16 v[118:121], v[164:167], v[180:183], v[118:121]
	v_mfma_f32_16x16x32_bf16 v[114:117], v[172:175], v[180:183], v[114:117]
	v_mfma_f32_16x16x32_bf16 v[98:101], v[172:175], v[188:191], v[98:101]
	v_mfma_f32_16x16x32_bf16 v[102:105], v[164:167], v[188:191], v[102:105]
	v_mfma_f32_16x16x32_bf16 v[84:87], v[164:167], v[202:205], v[84:87]
	v_mfma_f32_16x16x32_bf16 v[80:83], v[172:175], v[202:205], v[80:83]
	v_mfma_f32_16x16x32_bf16 v[64:67], v[172:175], v[210:213], v[64:67]
	v_mfma_f32_16x16x32_bf16 v[68:71], v[164:167], v[210:213], v[68:71]
	s_setprio 0
	s_barrier
	s_add_i32 s27, s27, s54
	v_lshl_add_u64 v[214:215], s[22:23], 0, v[96:97]
	s_mov_b32 m0, s27
	ds_read_b128 v[176:179], v159 offset:16384
	ds_read_b128 v[180:183], v159 offset:17408
	ds_read_b128 v[184:187], v159 offset:18432
	ds_read_b128 v[188:191], v159 offset:19456
	ds_read_b128 v[192:195], v159 offset:20480
	ds_read_b128 v[202:205], v159 offset:21504
	ds_read_b128 v[206:209], v159 offset:22528
	ds_read_b128 v[210:213], v159 offset:23552
	global_load_lds_dwordx4 v[214:215], off
	s_add_i32 m0, s27, 0x2000
	s_add_u32 s28, s22, 0x40000
	v_lshl_add_u64 v[216:217], s[22:23], 0, v[130:131]
	s_addc_u32 s29, s23, 0
	s_add_i32 s27, s48, s54
	global_load_lds_dwordx4 v[216:217], off
	v_lshl_add_u64 v[218:219], s[28:29], 0, v[96:97]
	s_mov_b32 m0, s27
	v_lshl_add_u64 v[220:221], s[24:25], 0, v[134:135]
	global_load_lds_dwordx4 v[218:219], off
	v_lshl_add_u64 v[218:219], s[28:29], 0, v[130:131]
	s_add_i32 m0, s27, 0x2000
	s_nop 0
	global_load_lds_dwordx4 v[218:219], off
	v_lshl_add_u64 v[218:219], s[24:25], 0, v[132:133]
	s_mov_b32 m0, s55
	s_nop 0
	global_load_lds_dwordx4 v[218:219], off
	s_mov_b32 m0, s72
	s_nop 0
	global_load_lds_dwordx4 v[220:221], off
	s_waitcnt vmcnt(8)
	s_waitcnt lgkmcnt(0)
	s_barrier
	s_setprio 1
	s_waitcnt lgkmcnt(0)
	v_mfma_f32_16x16x32_bf16 v[60:63], v[140:143], v[176:179], v[60:63]
	v_mfma_f32_16x16x32_bf16 v[56:59], v[148:151], v[176:179], v[56:59]
	v_mfma_f32_16x16x32_bf16 v[40:43], v[148:151], v[184:187], v[40:43]
	v_mfma_f32_16x16x32_bf16 v[44:47], v[140:143], v[184:187], v[44:47]
	v_mfma_f32_16x16x32_bf16 v[28:31], v[140:143], v[192:195], v[28:31]
	v_mfma_f32_16x16x32_bf16 v[24:27], v[148:151], v[192:195], v[24:27]
	v_mfma_f32_16x16x32_bf16 v[8:11], v[148:151], v[206:209], v[8:11]
	v_mfma_f32_16x16x32_bf16 v[12:15], v[140:143], v[206:209], v[12:15]
	v_mfma_f32_16x16x32_bf16 v[60:63], v[144:147], v[180:183], v[60:63]
	v_mfma_f32_16x16x32_bf16 v[56:59], v[152:155], v[180:183], v[56:59]
	v_mfma_f32_16x16x32_bf16 v[40:43], v[152:155], v[188:191], v[40:43]
	v_mfma_f32_16x16x32_bf16 v[44:47], v[144:147], v[188:191], v[44:47]
	v_mfma_f32_16x16x32_bf16 v[28:31], v[144:147], v[202:205], v[28:31]
	v_mfma_f32_16x16x32_bf16 v[24:27], v[152:155], v[202:205], v[24:27]
	v_mfma_f32_16x16x32_bf16 v[8:11], v[152:155], v[210:213], v[8:11]
	v_mfma_f32_16x16x32_bf16 v[12:15], v[144:147], v[210:213], v[12:15]
	s_setprio 0
	s_setprio 1
	v_mfma_f32_16x16x32_bf16 v[52:55], v[160:163], v[176:179], v[52:55]
	v_mfma_f32_16x16x32_bf16 v[48:51], v[168:171], v[176:179], v[48:51]
	v_mfma_f32_16x16x32_bf16 v[32:35], v[168:171], v[184:187], v[32:35]
	v_mfma_f32_16x16x32_bf16 v[36:39], v[160:163], v[184:187], v[36:39]
	v_mfma_f32_16x16x32_bf16 v[20:23], v[160:163], v[192:195], v[20:23]
	v_mfma_f32_16x16x32_bf16 v[16:19], v[168:171], v[192:195], v[16:19]
	v_mfma_f32_16x16x32_bf16 v[0:3], v[168:171], v[206:209], v[0:3]
	v_mfma_f32_16x16x32_bf16 v[4:7], v[160:163], v[206:209], v[4:7]
	v_mfma_f32_16x16x32_bf16 v[52:55], v[164:167], v[180:183], v[52:55]
	v_mfma_f32_16x16x32_bf16 v[48:51], v[172:175], v[180:183], v[48:51]
	v_mfma_f32_16x16x32_bf16 v[32:35], v[172:175], v[188:191], v[32:35]
	v_mfma_f32_16x16x32_bf16 v[36:39], v[164:167], v[188:191], v[36:39]
	v_mfma_f32_16x16x32_bf16 v[20:23], v[164:167], v[202:205], v[20:23]
	v_mfma_f32_16x16x32_bf16 v[16:19], v[172:175], v[202:205], v[16:19]
	v_mfma_f32_16x16x32_bf16 v[0:3], v[172:175], v[210:213], v[0:3]
	v_mfma_f32_16x16x32_bf16 v[4:7], v[164:167], v[210:213], v[4:7]
	s_setprio 0
	s_barrier
; #define PG8_STAGE(bufoff, gbase, V0, V1) do { \
;         __builtin_amdgcn_global_load_lds((const unsigned*)((const char*)(gbase) + (V0)), (LAS unsigned*)(lds + (bufoff) + ldsw), 16, 0, 0); \
;         __builtin_amdgcn_global_load_lds((const unsigned*)((const char*)(gbase) + (V1)), (LAS unsigned*)(lds + (bufoff) + ldsw + 8192), 16, 0, 0); } while (0)
; #define PG8_LDA(dst, b, h) do { _Pragma("unroll") for (int m = 0; m < 4; ++m) _Pragma("unroll") for (int k = 0; k < 2; ++k) dst[m][k] = *(const LAS bf16x8*)(lds + PG8_SA(b, h) + aoff + m * 2048 + k * 1024); } while (0)
; #define PG8_LDB(dst, b, h) do { _Pragma("unroll") for (int n = 0; n < 2; ++n) _Pragma("unroll") for (int k = 0; k < 2; ++k) dst[n][k] = *(const LAS bf16x8*)(lds + PG8_SB(b, h) + boff + n * 2048 + k * 1024); } while (0)
; #define PG8_MMA(ai, bj, At, Bt) do { __builtin_amdgcn_s_setprio(1); _Pragma("unroll") for (int m = 0; m < 4; ++m) _Pragma("unroll") for (int n = 0; n < 2; ++n) _Pragma("unroll") for (int k = 0; k < 2; ++k) \
;         acc[ai][bj][m][n] = __builtin_amdgcn_mfma_f32_16x16x32_bf16(Bt[n][k], At[m][k], acc[ai][bj][m][n], 0, 0, 0); __builtin_amdgcn_s_setprio(0); } while (0)
; #define PG8_WAIT_V(n) asm volatile("s_waitcnt vmcnt(" #n ")" ::: "memory")
; #define PG8_WAIT_L(n) asm volatile("s_waitcnt lgkmcnt(" #n ")" ::: "memory")
; #define PG8_BAR __builtin_amdgcn_s_barrier()
; #define PG8_SCHED __builtin_amdgcn_sched_barrier(0)
; template <class Epi, class Sched>
; DI void gemm_phase(LAS unsigned char* lds, const int lda2, const int ldb2, const int nt, const Sched& S, const Epi& E) {
;     ...
;             PG8_LDB(B0, 1, 0); PG8_LDB(B1, 1, 1); PG8_SCHED; PG8_LDA(At, 1, 0); PG8_STAGE(PG8_SA(0, 1), a2 + hstepA, vA0, vA1);
;             PG8_WAIT_V(8); PG8_WAIT_L(0); PG8_BAR; PG8_MMA(0, 0, At, B0); PG8_MMA(0, 1, At, B1); PG8_BAR; PG8_SCHED;
	s_add_i32 s27, 0, 0x18000
	s_add_i32 s28, 0, 0x1c000
	v_add_u32_e32 v152, s27, v158
	v_add_u32_e32 v172, s28, v158
	ds_read_b128 v[140:143], v152
	ds_read_b128 v[144:147], v152 offset:1024
	ds_read_b128 v[148:151], v152 offset:2048
	ds_read_b128 v[152:155], v152 offset:3072
	ds_read_b128 v[160:163], v172
	ds_read_b128 v[164:167], v172 offset:1024
	ds_read_b128 v[168:171], v172 offset:2048
	ds_read_b128 v[172:175], v172 offset:3072
	s_add_u32 s24, s24, 0x40000
	s_addc_u32 s25, s25, 0
	s_mov_b32 m0, s73
	v_lshl_add_u64 v[222:223], s[24:25], 0, v[132:133]
	ds_read_b128 v[176:179], v159 offset:32768
	ds_read_b128 v[180:183], v159 offset:33792
	ds_read_b128 v[184:187], v159 offset:34816
	ds_read_b128 v[188:191], v159 offset:35840
	ds_read_b128 v[192:195], v159 offset:36864
	ds_read_b128 v[202:205], v159 offset:37888
	ds_read_b128 v[206:209], v159 offset:38912
	ds_read_b128 v[210:213], v159 offset:39936
	global_load_lds_dwordx4 v[222:223], off
	v_lshl_add_u64 v[222:223], s[24:25], 0, v[134:135]
	s_mov_b32 m0, s74
	s_nop 0
	global_load_lds_dwordx4 v[222:223], off
	s_waitcnt vmcnt(8)
	s_waitcnt lgkmcnt(0)
	s_barrier
	s_setprio 1
	s_waitcnt lgkmcnt(0)
	v_mfma_f32_16x16x32_bf16 v[126:129], v[140:143], v[176:179], v[126:129]
	v_mfma_f32_16x16x32_bf16 v[122:125], v[148:151], v[176:179], v[122:125]
	v_mfma_f32_16x16x32_bf16 v[106:109], v[148:151], v[184:187], v[106:109]
	v_mfma_f32_16x16x32_bf16 v[110:113], v[140:143], v[184:187], v[110:113]
	v_mfma_f32_16x16x32_bf16 v[92:95], v[140:143], v[192:195], v[92:95]
	v_mfma_f32_16x16x32_bf16 v[88:91], v[148:151], v[192:195], v[88:91]
	v_mfma_f32_16x16x32_bf16 v[72:75], v[148:151], v[206:209], v[72:75]
	v_mfma_f32_16x16x32_bf16 v[76:79], v[140:143], v[206:209], v[76:79]
	v_mfma_f32_16x16x32_bf16 v[126:129], v[144:147], v[180:183], v[126:129]
	v_mfma_f32_16x16x32_bf16 v[122:125], v[152:155], v[180:183], v[122:125]
	v_mfma_f32_16x16x32_bf16 v[106:109], v[152:155], v[188:191], v[106:109]
	v_mfma_f32_16x16x32_bf16 v[110:113], v[144:147], v[188:191], v[110:113]
	v_mfma_f32_16x16x32_bf16 v[92:95], v[144:147], v[202:205], v[92:95]
	v_mfma_f32_16x16x32_bf16 v[88:91], v[152:155], v[202:205], v[88:91]
	v_mfma_f32_16x16x32_bf16 v[72:75], v[152:155], v[210:213], v[72:75]
	v_mfma_f32_16x16x32_bf16 v[76:79], v[144:147], v[210:213], v[76:79]
	s_setprio 0
	s_setprio 1
	v_mfma_f32_16x16x32_bf16 v[118:121], v[160:163], v[176:179], v[118:121]
	v_mfma_f32_16x16x32_bf16 v[114:117], v[168:171], v[176:179], v[114:117]
	v_mfma_f32_16x16x32_bf16 v[98:101], v[168:171], v[184:187], v[98:101]
	v_mfma_f32_16x16x32_bf16 v[102:105], v[160:163], v[184:187], v[102:105]
	v_mfma_f32_16x16x32_bf16 v[84:87], v[160:163], v[192:195], v[84:87]
	v_mfma_f32_16x16x32_bf16 v[80:83], v[168:171], v[192:195], v[80:83]
	v_mfma_f32_16x16x32_bf16 v[64:67], v[168:171], v[206:209], v[64:67]
	v_mfma_f32_16x16x32_bf16 v[68:71], v[160:163], v[206:209], v[68:71]
	v_mfma_f32_16x16x32_bf16 v[118:121], v[164:167], v[180:183], v[118:121]
	v_mfma_f32_16x16x32_bf16 v[114:117], v[172:175], v[180:183], v[114:117]
	v_mfma_f32_16x16x32_bf16 v[98:101], v[172:175], v[188:191], v[98:101]
	v_mfma_f32_16x16x32_bf16 v[102:105], v[164:167], v[188:191], v[102:105]
	v_mfma_f32_16x16x32_bf16 v[84:87], v[164:167], v[202:205], v[84:87]
	v_mfma_f32_16x16x32_bf16 v[80:83], v[172:175], v[202:205], v[80:83]
	v_mfma_f32_16x16x32_bf16 v[64:67], v[172:175], v[210:213], v[64:67]
	v_mfma_f32_16x16x32_bf16 v[68:71], v[164:167], v[210:213], v[68:71]
	s_setprio 0
	s_barrier
; #define PG8_STAGE(bufoff, gbase, V0, V1) do { \
;         __builtin_amdgcn_global_load_lds((const unsigned*)((const char*)(gbase) + (V0)), (LAS unsigned*)(lds + (bufoff) + ldsw), 16, 0, 0); \
;         __builtin_amdgcn_global_load_lds((const unsigned*)((const char*)(gbase) + (V1)), (LAS unsigned*)(lds + (bufoff) + ldsw + 8192), 16, 0, 0); } while (0)
; #define PG8_LDA(dst, b, h) do { _Pragma("unroll") for (int m = 0; m < 4; ++m) _Pragma("unroll") for (int k = 0; k < 2; ++k) dst[m][k] = *(const LAS bf16x8*)(lds + PG8_SA(b, h) + aoff + m * 2048 + k * 1024); } while (0)
; #define PG8_MMA(ai, bj, At, Bt) do { __builtin_amdgcn_s_setprio(1); _Pragma("unroll") for (int m = 0; m < 4; ++m) _Pragma("unroll") for (int n = 0; n < 2; ++n) _Pragma("unroll") for (int k = 0; k < 2; ++k) \
;         acc[ai][bj][m][n] = __builtin_amdgcn_mfma_f32_16x16x32_bf16(Bt[n][k], At[m][k], acc[ai][bj][m][n], 0, 0, 0); __builtin_amdgcn_s_setprio(0); } while (0)
; #define PG8_WAIT_V(n) asm volatile("s_waitcnt vmcnt(" #n ")" ::: "memory")
; #define PG8_WAIT_L(n) asm volatile("s_waitcnt lgkmcnt(" #n ")" ::: "memory")
; #define PG8_BAR __builtin_amdgcn_s_barrier()
; #define PG8_SCHED __builtin_amdgcn_sched_barrier(0)
; template <class Epi, class Sched>
; DI void gemm_phase(LAS unsigned char* lds, const int lda2, const int ldb2, const int nt, const Sched& S, const Epi& E) {
;     ...
;             PG8_LDA(At, 1, 1); PG8_STAGE(PG8_SB(1, 0), b3, vB0, vB1); PG8_STAGE(PG8_SB(1, 1), b3 + hstepB, vB0, vB1); PG8_STAGE(PG8_SA(1, 0), a3, vA0, vA1);
;             PG8_WAIT_V(8); PG8_WAIT_L(0); PG8_BAR; PG8_MMA(1, 0, At, B0); PG8_MMA(1, 1, At, B1); PG8_BAR; PG8_SCHED;
;         }
;         if (wr == 0) PG8_BAR;
	s_add_i32 s24, s27, s54
	v_lshl_add_u64 v[214:215], v[214:215], 0, s[86:87]
	s_mov_b32 m0, s24
	ds_read_b128 v[176:179], v159 offset:49152
	ds_read_b128 v[180:183], v159 offset:50176
	ds_read_b128 v[184:187], v159 offset:51200
	ds_read_b128 v[188:191], v159 offset:52224
	ds_read_b128 v[192:195], v159 offset:53248
	ds_read_b128 v[202:205], v159 offset:54272
	ds_read_b128 v[206:209], v159 offset:55296
	ds_read_b128 v[210:213], v159 offset:56320
	global_load_lds_dwordx4 v[214:215], off
	s_add_i32 m0, s24, 0x2000
	s_add_u32 s22, s22, 0x40080
	v_lshl_add_u64 v[214:215], v[216:217], 0, s[86:87]
	s_addc_u32 s23, s23, 0
	s_add_i32 s24, s28, s54
	global_load_lds_dwordx4 v[214:215], off
	v_lshl_add_u64 v[214:215], s[22:23], 0, v[96:97]
	s_mov_b32 m0, s24
	s_nop 0
	global_load_lds_dwordx4 v[214:215], off
	v_lshl_add_u64 v[214:215], s[22:23], 0, v[130:131]
	s_add_i32 m0, s24, 0x2000
	s_nop 0
	global_load_lds_dwordx4 v[214:215], off
	v_lshl_add_u64 v[214:215], v[218:219], 0, s[86:87]
	s_mov_b32 m0, s77
	s_nop 0
	global_load_lds_dwordx4 v[214:215], off
	v_lshl_add_u64 v[214:215], v[220:221], 0, s[86:87]
	s_mov_b32 m0, s78
	s_nop 0
	global_load_lds_dwordx4 v[214:215], off
	s_waitcnt vmcnt(8)
	s_waitcnt lgkmcnt(0)
	s_barrier
	s_setprio 1
	s_waitcnt lgkmcnt(0)
	v_mfma_f32_16x16x32_bf16 v[60:63], v[140:143], v[176:179], v[60:63]
	v_mfma_f32_16x16x32_bf16 v[56:59], v[148:151], v[176:179], v[56:59]
	v_mfma_f32_16x16x32_bf16 v[40:43], v[148:151], v[184:187], v[40:43]
	v_mfma_f32_16x16x32_bf16 v[44:47], v[140:143], v[184:187], v[44:47]
	v_mfma_f32_16x16x32_bf16 v[28:31], v[140:143], v[192:195], v[28:31]
	v_mfma_f32_16x16x32_bf16 v[24:27], v[148:151], v[192:195], v[24:27]
	v_mfma_f32_16x16x32_bf16 v[8:11], v[148:151], v[206:209], v[8:11]
	v_mfma_f32_16x16x32_bf16 v[12:15], v[140:143], v[206:209], v[12:15]
	v_mfma_f32_16x16x32_bf16 v[60:63], v[144:147], v[180:183], v[60:63]
	v_mfma_f32_16x16x32_bf16 v[56:59], v[152:155], v[180:183], v[56:59]
	v_mfma_f32_16x16x32_bf16 v[40:43], v[152:155], v[188:191], v[40:43]
	v_mfma_f32_16x16x32_bf16 v[44:47], v[144:147], v[188:191], v[44:47]
	v_mfma_f32_16x16x32_bf16 v[28:31], v[144:147], v[202:205], v[28:31]
	v_mfma_f32_16x16x32_bf16 v[24:27], v[152:155], v[202:205], v[24:27]
	v_mfma_f32_16x16x32_bf16 v[8:11], v[152:155], v[210:213], v[8:11]
	v_mfma_f32_16x16x32_bf16 v[12:15], v[144:147], v[210:213], v[12:15]
	s_setprio 0
	s_setprio 1
	v_mfma_f32_16x16x32_bf16 v[52:55], v[160:163], v[176:179], v[52:55]
	v_mfma_f32_16x16x32_bf16 v[48:51], v[168:171], v[176:179], v[48:51]
	v_mfma_f32_16x16x32_bf16 v[32:35], v[168:171], v[184:187], v[32:35]
	v_mfma_f32_16x16x32_bf16 v[36:39], v[160:163], v[184:187], v[36:39]
	v_mfma_f32_16x16x32_bf16 v[20:23], v[160:163], v[192:195], v[20:23]
	v_mfma_f32_16x16x32_bf16 v[16:19], v[168:171], v[192:195], v[16:19]
	v_mfma_f32_16x16x32_bf16 v[0:3], v[168:171], v[206:209], v[0:3]
	v_mfma_f32_16x16x32_bf16 v[4:7], v[160:163], v[206:209], v[4:7]
	v_mfma_f32_16x16x32_bf16 v[52:55], v[164:167], v[180:183], v[52:55]
	v_mfma_f32_16x16x32_bf16 v[48:51], v[172:175], v[180:183], v[48:51]
	v_mfma_f32_16x16x32_bf16 v[32:35], v[172:175], v[188:191], v[32:35]
	v_mfma_f32_16x16x32_bf16 v[36:39], v[164:167], v[188:191], v[36:39]
	v_mfma_f32_16x16x32_bf16 v[20:23], v[164:167], v[202:205], v[20:23]
	v_mfma_f32_16x16x32_bf16 v[16:19], v[172:175], v[202:205], v[16:19]
	v_mfma_f32_16x16x32_bf16 v[0:3], v[172:175], v[210:213], v[0:3]
	v_mfma_f32_16x16x32_bf16 v[4:7], v[164:167], v[210:213], v[4:7]
	s_setprio 0
	s_barrier
	s_add_i32 s17, s17, 2
	s_add_u32 s4, s4, 0x100
	s_addc_u32 s5, s5, 0
	s_add_u32 s7, s7, 0x100
	s_addc_u32 s15, s15, 0
	s_cmp_gt_u32 s17, 13
	s_cbranch_scc0 .LBB0_199
	s_and_b64 vcc, exec, s[12:13]
	s_cbranch_vccz .LBB0_202
	s_barrier

; #define PG8_STAGE(bufoff, gbase, V0, V1) do { \
;         __builtin_amdgcn_global_load_lds((const unsigned*)((const char*)(gbase) + (V0)), (LAS unsigned*)(lds + (bufoff) + ldsw), 16, 0, 0); \
;         __builtin_amdgcn_global_load_lds((const unsigned*)((const char*)(gbase) + (V1)), (LAS unsigned*)(lds + (bufoff) + ldsw + 8192), 16, 0, 0); } while (0)
; #define PG8_LDA(dst, b, h) do { _Pragma("unroll") for (int m = 0; m < 4; ++m) _Pragma("unroll") for (int k = 0; k < 2; ++k) dst[m][k] = *(const LAS bf16x8*)(lds + PG8_SA(b, h) + aoff + m * 2048 + k * 1024); } while (0)
; #define PG8_LDB(dst, b, h) do { _Pragma("unroll") for (int n = 0; n < 2; ++n) _Pragma("unroll") for (int k = 0; k < 2; ++k) dst[n][k] = *(const LAS bf16x8*)(lds + PG8_SB(b, h) + boff + n * 2048 + k * 1024); } while (0)
; #define PG8_MMA(ai, bj, At, Bt) do { __builtin_amdgcn_s_setprio(1); _Pragma("unroll") for (int m = 0; m < 4; ++m) _Pragma("unroll") for (int n = 0; n < 2; ++n) _Pragma("unroll") for (int k = 0; k < 2; ++k) \
;         acc[ai][bj][m][n] = __builtin_amdgcn_mfma_f32_16x16x32_bf16(Bt[n][k], At[m][k], acc[ai][bj][m][n], 0, 0, 0); __builtin_amdgcn_s_setprio(0); } while (0)
; #define PG8_WAIT_V(n) asm volatile("s_waitcnt vmcnt(" #n ")" ::: "memory")
; #define PG8_WAIT_L(n) asm volatile("s_waitcnt lgkmcnt(" #n ")" ::: "memory")
; #define PG8_BAR __builtin_amdgcn_s_barrier()
; #define PG8_SCHED __builtin_amdgcn_sched_barrier(0)
; template <class Epi, class Sched>
; DI void gemm_phase(LAS unsigned char* lds, const int lda2, const int ldb2, const int nt, const Sched& S, const Epi& E) {
;     ...
;             PG8_LDB(B0, 0, 0); PG8_LDB(B1, 0, 1); PG8_SCHED; PG8_LDA(At, 0, 0); PG8_STAGE(PG8_SA(1, 1), a1 + hstepA, vA0, vA1);
;             PG8_WAIT_V(8); PG8_WAIT_L(0); PG8_BAR; PG8_MMA(0, 0, At, B0); PG8_MMA(0, 1, At, B1); PG8_BAR; PG8_SCHED;
;             PG8_LDA(At, 0, 1); PG8_STAGE(PG8_SB(0, 0), b2, vB0, vB1); PG8_STAGE(PG8_SB(0, 1), b2 + hstepB, vB0, vB1); PG8_STAGE(PG8_SA(0, 0), a2, vA0, vA1);
;             PG8_WAIT_V(8); PG8_WAIT_L(0); PG8_BAR; PG8_MMA(1, 0, At, B0); PG8_MMA(1, 1, At, B1); PG8_BAR; PG8_SCHED;
.LBB0_680:
	s_add_u32 s24, s6, 0xffe90080
	s_addc_u32 s25, s7, -1
	s_add_i32 s51, 0, 0x10000
	s_cmp_eq_u32 s50, 4
	s_cselect_b32 s27, s21, s25
	s_cselect_b32 s26, s20, s24
	v_add_u32_e32 v96, s51, v238
	s_cselect_b32 s25, s23, s49
	s_cselect_b32 s24, s22, s5
	s_add_i32 s85, 0, 0x14000
	ds_read_b128 v[132:135], v96
	ds_read_b128 v[136:139], v96 offset:1024
	ds_read_b128 v[140:143], v96 offset:2048
	ds_read_b128 v[144:147], v96 offset:3072
	v_add_u32_e32 v96, s85, v238
	ds_read_b128 v[148:151], v96
	ds_read_b128 v[152:155], v96 offset:1024
	ds_read_b128 v[156:159], v96 offset:2048
	ds_read_b128 v[160:163], v96 offset:3072
	v_lshl_add_u64 v[98:99], s[6:7], 0, v[210:211]
	s_add_i32 m0, s52, 0xc000
	ds_read_b128 v[164:167], v239
	ds_read_b128 v[168:171], v239 offset:1024
	ds_read_b128 v[172:175], v239 offset:2048
	ds_read_b128 v[176:179], v239 offset:3072
	ds_read_b128 v[180:183], v239 offset:4096
	ds_read_b128 v[184:187], v239 offset:5120
	ds_read_b128 v[188:191], v239 offset:6144
	ds_read_b128 v[192:195], v239 offset:7168
	global_load_lds_dwordx4 v[98:99], off
	v_lshl_add_u64 v[98:99], s[6:7], 0, v[212:213]
	s_add_i32 m0, s52, 0xe000
	s_nop 0
	global_load_lds_dwordx4 v[98:99], off
	s_waitcnt vmcnt(8)
	s_waitcnt lgkmcnt(0)
	s_barrier
	s_setprio 1
	s_waitcnt lgkmcnt(0)
	v_mfma_f32_16x16x32_bf16 v[128:131], v[132:135], v[164:167], v[128:131]
	v_mfma_f32_16x16x32_bf16 v[124:127], v[140:143], v[164:167], v[124:127]
	v_mfma_f32_16x16x32_bf16 v[116:119], v[140:143], v[172:175], v[116:119]
	v_mfma_f32_16x16x32_bf16 v[120:123], v[132:135], v[172:175], v[120:123]
	v_mfma_f32_16x16x32_bf16 v[112:115], v[132:135], v[180:183], v[112:115]
	v_mfma_f32_16x16x32_bf16 v[108:111], v[140:143], v[180:183], v[108:111]
	v_mfma_f32_16x16x32_bf16 v[98:101], v[140:143], v[188:191], v[100:103]
	v_mfma_f32_16x16x32_bf16 v[104:107], v[132:135], v[188:191], v[104:107]
	v_mfma_f32_16x16x32_bf16 v[128:131], v[136:139], v[168:171], v[128:131]
	v_mfma_f32_16x16x32_bf16 v[124:127], v[144:147], v[168:171], v[124:127]
	v_mfma_f32_16x16x32_bf16 v[116:119], v[144:147], v[176:179], v[116:119]
	v_mfma_f32_16x16x32_bf16 v[120:123], v[136:139], v[176:179], v[120:123]
	v_mfma_f32_16x16x32_bf16 v[112:115], v[136:139], v[184:187], v[112:115]
	v_mfma_f32_16x16x32_bf16 v[108:111], v[144:147], v[184:187], v[108:111]
	v_mfma_f32_16x16x32_bf16 v[98:101], v[144:147], v[192:195], v[98:101]
	v_mfma_f32_16x16x32_bf16 v[104:107], v[136:139], v[192:195], v[104:107]
	s_setprio 0
	s_setprio 1
	v_mfma_f32_16x16x32_bf16 v[92:95], v[148:151], v[164:167], v[92:95]
	v_mfma_f32_16x16x32_bf16 v[88:91], v[156:159], v[164:167], v[88:91]
	v_mfma_f32_16x16x32_bf16 v[80:83], v[156:159], v[172:175], v[80:83]
	v_mfma_f32_16x16x32_bf16 v[84:87], v[148:151], v[172:175], v[84:87]
	v_mfma_f32_16x16x32_bf16 v[76:79], v[148:151], v[180:183], v[76:79]
	v_mfma_f32_16x16x32_bf16 v[72:75], v[156:159], v[180:183], v[72:75]
	v_mfma_f32_16x16x32_bf16 v[64:67], v[156:159], v[188:191], v[64:67]
	v_mfma_f32_16x16x32_bf16 v[68:71], v[148:151], v[188:191], v[68:71]
	v_mfma_f32_16x16x32_bf16 v[92:95], v[152:155], v[168:171], v[92:95]
	v_mfma_f32_16x16x32_bf16 v[88:91], v[160:163], v[168:171], v[88:91]
	v_mfma_f32_16x16x32_bf16 v[80:83], v[160:163], v[176:179], v[80:83]
	v_mfma_f32_16x16x32_bf16 v[84:87], v[152:155], v[176:179], v[84:87]
	v_mfma_f32_16x16x32_bf16 v[76:79], v[152:155], v[184:187], v[76:79]
	v_mfma_f32_16x16x32_bf16 v[72:75], v[160:163], v[184:187], v[72:75]
	v_mfma_f32_16x16x32_bf16 v[64:67], v[160:163], v[192:195], v[64:67]
	v_mfma_f32_16x16x32_bf16 v[68:71], v[152:155], v[192:195], v[68:71]
	s_setprio 0
	s_barrier
	s_add_i32 s51, s51, s47
	v_lshl_add_u64 v[214:215], s[24:25], 0, v[202:203]
	s_mov_b32 m0, s51
	ds_read_b128 v[164:167], v239 offset:16384
	ds_read_b128 v[168:171], v239 offset:17408
	ds_read_b128 v[172:175], v239 offset:18432
	ds_read_b128 v[176:179], v239 offset:19456
	ds_read_b128 v[180:183], v239 offset:20480
	ds_read_b128 v[184:187], v239 offset:21504
	ds_read_b128 v[188:191], v239 offset:22528
	ds_read_b128 v[192:195], v239 offset:23552
	global_load_lds_dwordx4 v[214:215], off
	s_add_i32 m0, s51, 0x2000
	s_add_u32 s56, s24, 0x60000
	v_lshl_add_u64 v[216:217], s[24:25], 0, v[204:205]
	s_addc_u32 s57, s25, 0
	s_add_i32 s51, s85, s47
	global_load_lds_dwordx4 v[216:217], off
	v_lshl_add_u64 v[102:103], s[56:57], 0, v[202:203]
	s_mov_b32 m0, s51
	v_lshl_add_u64 v[218:219], s[26:27], 0, v[206:207]
	global_load_lds_dwordx4 v[102:103], off
	v_lshl_add_u64 v[102:103], s[56:57], 0, v[204:205]
	s_add_i32 m0, s51, 0x2000
	v_lshl_add_u64 v[220:221], s[26:27], 0, v[208:209]
	global_load_lds_dwordx4 v[102:103], off
	s_mov_b32 m0, s52
	s_nop 0
	global_load_lds_dwordx4 v[218:219], off
	s_mov_b32 m0, s53
	s_nop 0
	global_load_lds_dwordx4 v[220:221], off
	s_waitcnt vmcnt(8)
	s_waitcnt lgkmcnt(0)
	s_barrier
; #define PG8_STAGE(bufoff, gbase, V0, V1) do { \
;         __builtin_amdgcn_global_load_lds((const unsigned*)((const char*)(gbase) + (V0)), (LAS unsigned*)(lds + (bufoff) + ldsw), 16, 0, 0); \
;         __builtin_amdgcn_global_load_lds((const unsigned*)((const char*)(gbase) + (V1)), (LAS unsigned*)(lds + (bufoff) + ldsw + 8192), 16, 0, 0); } while (0)
; #define PG8_LDA(dst, b, h) do { _Pragma("unroll") for (int m = 0; m < 4; ++m) _Pragma("unroll") for (int k = 0; k < 2; ++k) dst[m][k] = *(const LAS bf16x8*)(lds + PG8_SA(b, h) + aoff + m * 2048 + k * 1024); } while (0)
; #define PG8_LDB(dst, b, h) do { _Pragma("unroll") for (int n = 0; n < 2; ++n) _Pragma("unroll") for (int k = 0; k < 2; ++k) dst[n][k] = *(const LAS bf16x8*)(lds + PG8_SB(b, h) + boff + n * 2048 + k * 1024); } while (0)
; #define PG8_MMA(ai, bj, At, Bt) do { __builtin_amdgcn_s_setprio(1); _Pragma("unroll") for (int m = 0; m < 4; ++m) _Pragma("unroll") for (int n = 0; n < 2; ++n) _Pragma("unroll") for (int k = 0; k < 2; ++k) \
;         acc[ai][bj][m][n] = __builtin_amdgcn_mfma_f32_16x16x32_bf16(Bt[n][k], At[m][k], acc[ai][bj][m][n], 0, 0, 0); __builtin_amdgcn_s_setprio(0); } while (0)
; #define PG8_WAIT_V(n) asm volatile("s_waitcnt vmcnt(" #n ")" ::: "memory")
; #define PG8_WAIT_L(n) asm volatile("s_waitcnt lgkmcnt(" #n ")" ::: "memory")
; #define PG8_BAR __builtin_amdgcn_s_barrier()
; #define PG8_SCHED __builtin_amdgcn_sched_barrier(0)
; template <class Epi, class Sched>
; DI void gemm_phase(LAS unsigned char* lds, const int lda2, const int ldb2, const int nt, const Sched& S, const Epi& E) {
;     ...
;             PG8_WAIT_V(8); PG8_WAIT_L(0); PG8_BAR; PG8_MMA(0, 0, At, B0); PG8_MMA(0, 1, At, B1); PG8_BAR; PG8_SCHED;
;             PG8_LDA(At, 0, 1); PG8_STAGE(PG8_SB(0, 0), b2, vB0, vB1); PG8_STAGE(PG8_SB(0, 1), b2 + hstepB, vB0, vB1); PG8_STAGE(PG8_SA(0, 0), a2, vA0, vA1);
;             PG8_WAIT_V(8); PG8_WAIT_L(0); PG8_BAR; PG8_MMA(1, 0, At, B0); PG8_MMA(1, 1, At, B1); PG8_BAR; PG8_SCHED;
;             PG8_LDB(B0, 1, 0); PG8_LDB(B1, 1, 1); PG8_SCHED; PG8_LDA(At, 1, 0); PG8_STAGE(PG8_SA(0, 1), a2 + hstepA, vA0, vA1);
;             PG8_WAIT_V(8); PG8_WAIT_L(0); PG8_BAR; PG8_MMA(0, 0, At, B0); PG8_MMA(0, 1, At, B1); PG8_BAR; PG8_SCHED;
	s_setprio 1
	s_waitcnt lgkmcnt(0)
	v_mfma_f32_16x16x32_bf16 v[60:63], v[132:135], v[164:167], v[60:63]
	v_mfma_f32_16x16x32_bf16 v[56:59], v[140:143], v[164:167], v[56:59]
	v_mfma_f32_16x16x32_bf16 v[48:51], v[140:143], v[172:175], v[48:51]
	v_mfma_f32_16x16x32_bf16 v[52:55], v[132:135], v[172:175], v[52:55]
	v_mfma_f32_16x16x32_bf16 v[44:47], v[132:135], v[180:183], v[44:47]
	v_mfma_f32_16x16x32_bf16 v[40:43], v[140:143], v[180:183], v[40:43]
	v_mfma_f32_16x16x32_bf16 v[32:35], v[140:143], v[188:191], v[32:35]
	v_mfma_f32_16x16x32_bf16 v[36:39], v[132:135], v[188:191], v[36:39]
	v_mfma_f32_16x16x32_bf16 v[60:63], v[136:139], v[168:171], v[60:63]
	v_mfma_f32_16x16x32_bf16 v[56:59], v[144:147], v[168:171], v[56:59]
	v_mfma_f32_16x16x32_bf16 v[48:51], v[144:147], v[176:179], v[48:51]
	v_mfma_f32_16x16x32_bf16 v[52:55], v[136:139], v[176:179], v[52:55]
	v_mfma_f32_16x16x32_bf16 v[44:47], v[136:139], v[184:187], v[44:47]
	v_mfma_f32_16x16x32_bf16 v[40:43], v[144:147], v[184:187], v[40:43]
	v_mfma_f32_16x16x32_bf16 v[32:35], v[144:147], v[192:195], v[32:35]
	v_mfma_f32_16x16x32_bf16 v[36:39], v[136:139], v[192:195], v[36:39]
	s_setprio 0
	s_setprio 1
	v_mfma_f32_16x16x32_bf16 v[28:31], v[148:151], v[164:167], v[28:31]
	v_mfma_f32_16x16x32_bf16 v[24:27], v[156:159], v[164:167], v[24:27]
	v_mfma_f32_16x16x32_bf16 v[16:19], v[156:159], v[172:175], v[16:19]
	v_mfma_f32_16x16x32_bf16 v[20:23], v[148:151], v[172:175], v[20:23]
	v_mfma_f32_16x16x32_bf16 v[12:15], v[148:151], v[180:183], v[12:15]
	v_mfma_f32_16x16x32_bf16 v[8:11], v[156:159], v[180:183], v[8:11]
	v_mfma_f32_16x16x32_bf16 v[0:3], v[156:159], v[188:191], v[0:3]
	v_mfma_f32_16x16x32_bf16 v[4:7], v[148:151], v[188:191], v[4:7]
	v_mfma_f32_16x16x32_bf16 v[28:31], v[152:155], v[168:171], v[28:31]
	v_mfma_f32_16x16x32_bf16 v[24:27], v[160:163], v[168:171], v[24:27]
	v_mfma_f32_16x16x32_bf16 v[16:19], v[160:163], v[176:179], v[16:19]
	v_mfma_f32_16x16x32_bf16 v[20:23], v[152:155], v[176:179], v[20:23]
	v_mfma_f32_16x16x32_bf16 v[12:15], v[152:155], v[184:187], v[12:15]
	v_mfma_f32_16x16x32_bf16 v[8:11], v[160:163], v[184:187], v[8:11]
	v_mfma_f32_16x16x32_bf16 v[0:3], v[160:163], v[192:195], v[0:3]
	v_mfma_f32_16x16x32_bf16 v[4:7], v[152:155], v[192:195], v[4:7]
	s_setprio 0
	s_barrier
	s_add_i32 s51, 0, 0x18000
	v_add_u32_e32 v96, s51, v238
	s_add_i32 s56, 0, 0x1c000
	ds_read_b128 v[132:135], v96
	ds_read_b128 v[136:139], v96 offset:1024
	ds_read_b128 v[140:143], v96 offset:2048
	ds_read_b128 v[144:147], v96 offset:3072
	v_add_u32_e32 v96, s56, v238
	ds_read_b128 v[148:151], v96
	ds_read_b128 v[152:155], v96 offset:1024
	ds_read_b128 v[156:159], v96 offset:2048
	ds_read_b128 v[160:163], v96 offset:3072
	s_add_u32 s26, s26, 0x170000
	s_addc_u32 s27, s27, 0
	s_mov_b32 m0, s55
	v_lshl_add_u64 v[102:103], s[26:27], 0, v[206:207]
	ds_read_b128 v[164:167], v239 offset:32768
	ds_read_b128 v[168:171], v239 offset:33792
	ds_read_b128 v[172:175], v239 offset:34816
	ds_read_b128 v[176:179], v239 offset:35840
	ds_read_b128 v[180:183], v239 offset:36864
	ds_read_b128 v[184:187], v239 offset:37888
	ds_read_b128 v[188:191], v239 offset:38912
	ds_read_b128 v[192:195], v239 offset:39936
	global_load_lds_dwordx4 v[102:103], off
	v_lshl_add_u64 v[102:103], s[26:27], 0, v[208:209]
	s_mov_b32 m0, s72
	s_nop 0
	global_load_lds_dwordx4 v[102:103], off
	s_waitcnt vmcnt(8)
	s_waitcnt lgkmcnt(0)
	s_barrier
	s_setprio 1
	s_waitcnt lgkmcnt(0)
	v_mfma_f32_16x16x32_bf16 v[128:131], v[132:135], v[164:167], v[128:131]
	v_mfma_f32_16x16x32_bf16 v[124:127], v[140:143], v[164:167], v[124:127]
	v_mfma_f32_16x16x32_bf16 v[116:119], v[140:143], v[172:175], v[116:119]
	v_mfma_f32_16x16x32_bf16 v[120:123], v[132:135], v[172:175], v[120:123]
	v_mfma_f32_16x16x32_bf16 v[112:115], v[132:135], v[180:183], v[112:115]
	v_mfma_f32_16x16x32_bf16 v[108:111], v[140:143], v[180:183], v[108:111]
	v_mfma_f32_16x16x32_bf16 v[98:101], v[140:143], v[188:191], v[98:101]
	v_mfma_f32_16x16x32_bf16 v[102:105], v[132:135], v[188:191], v[104:107]
	v_mfma_f32_16x16x32_bf16 v[128:131], v[136:139], v[168:171], v[128:131]
	v_mfma_f32_16x16x32_bf16 v[124:127], v[144:147], v[168:171], v[124:127]
	v_mfma_f32_16x16x32_bf16 v[116:119], v[144:147], v[176:179], v[116:119]
	v_mfma_f32_16x16x32_bf16 v[120:123], v[136:139], v[176:179], v[120:123]
	v_mfma_f32_16x16x32_bf16 v[112:115], v[136:139], v[184:187], v[112:115]
	v_mfma_f32_16x16x32_bf16 v[108:111], v[144:147], v[184:187], v[108:111]
	v_mfma_f32_16x16x32_bf16 v[100:103], v[144:147], v[192:195], v[98:101]
	v_mfma_f32_16x16x32_bf16 v[104:107], v[136:139], v[192:195], v[102:105]
	s_setprio 0
	s_setprio 1
	v_mfma_f32_16x16x32_bf16 v[92:95], v[148:151], v[164:167], v[92:95]
	v_mfma_f32_16x16x32_bf16 v[88:91], v[156:159], v[164:167], v[88:91]
	v_mfma_f32_16x16x32_bf16 v[80:83], v[156:159], v[172:175], v[80:83]
	v_mfma_f32_16x16x32_bf16 v[84:87], v[148:151], v[172:175], v[84:87]
	v_mfma_f32_16x16x32_bf16 v[76:79], v[148:151], v[180:183], v[76:79]
	v_mfma_f32_16x16x32_bf16 v[72:75], v[156:159], v[180:183], v[72:75]
	v_mfma_f32_16x16x32_bf16 v[64:67], v[156:159], v[188:191], v[64:67]
	v_mfma_f32_16x16x32_bf16 v[68:71], v[148:151], v[188:191], v[68:71]
	v_mfma_f32_16x16x32_bf16 v[92:95], v[152:155], v[168:171], v[92:95]
	v_mfma_f32_16x16x32_bf16 v[88:91], v[160:163], v[168:171], v[88:91]
	v_mfma_f32_16x16x32_bf16 v[80:83], v[160:163], v[176:179], v[80:83]
	v_mfma_f32_16x16x32_bf16 v[84:87], v[152:155], v[176:179], v[84:87]
	v_mfma_f32_16x16x32_bf16 v[76:79], v[152:155], v[184:187], v[76:79]
	v_mfma_f32_16x16x32_bf16 v[72:75], v[160:163], v[184:187], v[72:75]
	v_mfma_f32_16x16x32_bf16 v[64:67], v[160:163], v[192:195], v[64:67]
	v_mfma_f32_16x16x32_bf16 v[68:71], v[152:155], v[192:195], v[68:71]
	s_setprio 0
	s_barrier
; #define PG8_STAGE(bufoff, gbase, V0, V1) do { \
;         __builtin_amdgcn_global_load_lds((const unsigned*)((const char*)(gbase) + (V0)), (LAS unsigned*)(lds + (bufoff) + ldsw), 16, 0, 0); \
;         __builtin_amdgcn_global_load_lds((const unsigned*)((const char*)(gbase) + (V1)), (LAS unsigned*)(lds + (bufoff) + ldsw + 8192), 16, 0, 0); } while (0)
; #define PG8_LDA(dst, b, h) do { _Pragma("unroll") for (int m = 0; m < 4; ++m) _Pragma("unroll") for (int k = 0; k < 2; ++k) dst[m][k] = *(const LAS bf16x8*)(lds + PG8_SA(b, h) + aoff + m * 2048 + k * 1024); } while (0)
; #define PG8_MMA(ai, bj, At, Bt) do { __builtin_amdgcn_s_setprio(1); _Pragma("unroll") for (int m = 0; m < 4; ++m) _Pragma("unroll") for (int n = 0; n < 2; ++n) _Pragma("unroll") for (int k = 0; k < 2; ++k) \
;         acc[ai][bj][m][n] = __builtin_amdgcn_mfma_f32_16x16x32_bf16(Bt[n][k], At[m][k], acc[ai][bj][m][n], 0, 0, 0); __builtin_amdgcn_s_setprio(0); } while (0)
; #define PG8_WAIT_V(n) asm volatile("s_waitcnt vmcnt(" #n ")" ::: "memory")
; #define PG8_WAIT_L(n) asm volatile("s_waitcnt lgkmcnt(" #n ")" ::: "memory")
; #define PG8_BAR __builtin_amdgcn_s_barrier()
; #define PG8_SCHED __builtin_amdgcn_sched_barrier(0)
; template <class Epi, class Sched>
; DI void gemm_phase(LAS unsigned char* lds, const int lda2, const int ldb2, const int nt, const Sched& S, const Epi& E) {
;     ...
;             PG8_LDA(At, 1, 1); PG8_STAGE(PG8_SB(1, 0), b3, vB0, vB1); PG8_STAGE(PG8_SB(1, 1), b3 + hstepB, vB0, vB1); PG8_STAGE(PG8_SA(1, 0), a3, vA0, vA1);
;             PG8_WAIT_V(8); PG8_WAIT_L(0); PG8_BAR; PG8_MMA(1, 0, At, B0); PG8_MMA(1, 1, At, B1); PG8_BAR; PG8_SCHED;
;         }
	s_add_i32 s26, s51, s47
	v_lshl_add_u64 v[98:99], v[214:215], 0, s[86:87]
	s_mov_b32 m0, s26
	ds_read_b128 v[164:167], v239 offset:49152
	ds_read_b128 v[168:171], v239 offset:50176
	ds_read_b128 v[172:175], v239 offset:51200
	ds_read_b128 v[176:179], v239 offset:52224
	ds_read_b128 v[180:183], v239 offset:53248
	ds_read_b128 v[184:187], v239 offset:54272
	ds_read_b128 v[188:191], v239 offset:55296
	ds_read_b128 v[192:195], v239 offset:56320
	global_load_lds_dwordx4 v[98:99], off
	s_add_i32 m0, s26, 0x2000
	s_add_u32 s24, s24, 0x60080
	v_lshl_add_u64 v[98:99], v[216:217], 0, s[86:87]
	s_addc_u32 s25, s25, 0
	s_add_i32 s26, s56, s47
	global_load_lds_dwordx4 v[98:99], off
	v_lshl_add_u64 v[98:99], s[24:25], 0, v[202:203]
	s_mov_b32 m0, s26
	s_nop 0
	global_load_lds_dwordx4 v[98:99], off
	v_lshl_add_u64 v[98:99], s[24:25], 0, v[204:205]
	s_add_i32 m0, s26, 0x2000
	s_nop 0
	global_load_lds_dwordx4 v[98:99], off
	v_lshl_add_u64 v[98:99], v[218:219], 0, s[86:87]
	s_mov_b32 m0, s75
	s_nop 0
	global_load_lds_dwordx4 v[98:99], off
	v_lshl_add_u64 v[98:99], v[220:221], 0, s[86:87]
	s_mov_b32 m0, s76
	s_nop 0
	global_load_lds_dwordx4 v[98:99], off
	s_waitcnt vmcnt(8)
	s_waitcnt lgkmcnt(0)
	s_barrier
	s_setprio 1
	s_waitcnt lgkmcnt(0)
	v_mfma_f32_16x16x32_bf16 v[60:63], v[132:135], v[164:167], v[60:63]
	v_mfma_f32_16x16x32_bf16 v[56:59], v[140:143], v[164:167], v[56:59]
	v_mfma_f32_16x16x32_bf16 v[48:51], v[140:143], v[172:175], v[48:51]
	v_mfma_f32_16x16x32_bf16 v[52:55], v[132:135], v[172:175], v[52:55]
	v_mfma_f32_16x16x32_bf16 v[44:47], v[132:135], v[180:183], v[44:47]
	v_mfma_f32_16x16x32_bf16 v[40:43], v[140:143], v[180:183], v[40:43]
	v_mfma_f32_16x16x32_bf16 v[32:35], v[140:143], v[188:191], v[32:35]
	v_mfma_f32_16x16x32_bf16 v[36:39], v[132:135], v[188:191], v[36:39]
	v_mfma_f32_16x16x32_bf16 v[60:63], v[136:139], v[168:171], v[60:63]
	v_mfma_f32_16x16x32_bf16 v[56:59], v[144:147], v[168:171], v[56:59]
	v_mfma_f32_16x16x32_bf16 v[48:51], v[144:147], v[176:179], v[48:51]
	v_mfma_f32_16x16x32_bf16 v[52:55], v[136:139], v[176:179], v[52:55]
	v_mfma_f32_16x16x32_bf16 v[44:47], v[136:139], v[184:187], v[44:47]
	v_mfma_f32_16x16x32_bf16 v[40:43], v[144:147], v[184:187], v[40:43]
	v_mfma_f32_16x16x32_bf16 v[32:35], v[144:147], v[192:195], v[32:35]
	v_mfma_f32_16x16x32_bf16 v[36:39], v[136:139], v[192:195], v[36:39]
	s_setprio 0
	s_setprio 1
	v_mfma_f32_16x16x32_bf16 v[28:31], v[148:151], v[164:167], v[28:31]
	v_mfma_f32_16x16x32_bf16 v[24:27], v[156:159], v[164:167], v[24:27]
	v_mfma_f32_16x16x32_bf16 v[16:19], v[156:159], v[172:175], v[16:19]
	v_mfma_f32_16x16x32_bf16 v[20:23], v[148:151], v[172:175], v[20:23]
	v_mfma_f32_16x16x32_bf16 v[12:15], v[148:151], v[180:183], v[12:15]
	v_mfma_f32_16x16x32_bf16 v[8:11], v[156:159], v[180:183], v[8:11]
	v_mfma_f32_16x16x32_bf16 v[0:3], v[156:159], v[188:191], v[0:3]
	v_mfma_f32_16x16x32_bf16 v[4:7], v[148:151], v[188:191], v[4:7]
	v_mfma_f32_16x16x32_bf16 v[28:31], v[152:155], v[168:171], v[28:31]
	v_mfma_f32_16x16x32_bf16 v[24:27], v[160:163], v[168:171], v[24:27]
	v_mfma_f32_16x16x32_bf16 v[16:19], v[160:163], v[176:179], v[16:19]
	v_mfma_f32_16x16x32_bf16 v[20:23], v[152:155], v[176:179], v[20:23]
	v_mfma_f32_16x16x32_bf16 v[12:15], v[152:155], v[184:187], v[12:15]
	v_mfma_f32_16x16x32_bf16 v[8:11], v[160:163], v[184:187], v[8:11]
	v_mfma_f32_16x16x32_bf16 v[0:3], v[160:163], v[192:195], v[0:3]
	v_mfma_f32_16x16x32_bf16 v[4:7], v[152:155], v[192:195], v[4:7]
	s_setprio 0
	s_barrier
	s_add_i32 s50, s50, 2
	s_add_u32 s6, s6, 0x100
	s_addc_u32 s7, s7, 0
	s_add_u32 s5, s5, 0x100
	s_addc_u32 s49, s49, 0
	s_cmp_gt_u32 s50, 5
	s_cbranch_scc0 .LBB0_680
	s_and_b64 vcc, exec, s[18:19]
	s_cbranch_vccz .LBB0_683
	s_barrier

; #define PG8_STAGE(bufoff, gbase, V0, V1) do { \
;         __builtin_amdgcn_global_load_lds((const unsigned*)((const char*)(gbase) + (V0)), (LAS unsigned*)(lds + (bufoff) + ldsw), 16, 0, 0); \
;         __builtin_amdgcn_global_load_lds((const unsigned*)((const char*)(gbase) + (V1)), (LAS unsigned*)(lds + (bufoff) + ldsw + 8192), 16, 0, 0); } while (0)
; #define PG8_LDA(dst, b, h) do { _Pragma("unroll") for (int m = 0; m < 4; ++m) _Pragma("unroll") for (int k = 0; k < 2; ++k) dst[m][k] = *(const LAS bf16x8*)(lds + PG8_SA(b, h) + aoff + m * 2048 + k * 1024); } while (0)
; #define PG8_LDB(dst, b, h) do { _Pragma("unroll") for (int n = 0; n < 2; ++n) _Pragma("unroll") for (int k = 0; k < 2; ++k) dst[n][k] = *(const LAS bf16x8*)(lds + PG8_SB(b, h) + boff + n * 2048 + k * 1024); } while (0)
; #define PG8_WAIT_V(n) asm volatile("s_waitcnt vmcnt(" #n ")" ::: "memory")
; template <class Epi, class Sched>
; DI void gemm_phase(LAS unsigned char* lds, const int lda2, const int ldb2, const int nt, const Sched& S, const Epi& E) {
;     ...
;     f32x4 acc[2][2][4][2];
; #pragma unroll
;     for (int a = 0; a < 2; ++a)
; #pragma unroll
;         for (int b = 0; b < 2; ++b)
; #pragma unroll
;             for (int m = 0; m < 4; ++m)
; #pragma unroll
;                 for (int n = 0; n < 2; ++n) acc[a][b][m][n] = (f32x4){0.f, 0.f, 0.f, 0.f};
;     ...
;     for (;;) {
;         const bool has_next = S.next(ui + 1, nxt);
;         const char* nA = has_next ? nxt.A : cA; const char* nB = has_next ? nxt.B : cB;
;         for (int t = 0; t < nt; t += 2) {
;             const bool last = (t == nt - 2);
;             const char* a1 = cA + (size_t)(t + 1) * kstep;
;             const char* a2 = last ? nA : cA + (size_t)(t + 2) * kstep; const char* b2 = last ? nB : cB + (size_t)(t + 2) * kstep;
;             const char* a3 = a2 + kstep; const char* b3 = b2 + kstep;
;             PG8_LDB(B0, 0, 0); PG8_LDB(B1, 0, 1); PG8_SCHED; PG8_LDA(At, 0, 0); PG8_STAGE(PG8_SA(1, 1), a1 + hstepA, vA0, vA1);
;             PG8_WAIT_V(8); PG8_WAIT_L(0); PG8_BAR; PG8_MMA(0, 0, At, B0); PG8_MMA(0, 1, At, B1); PG8_BAR; PG8_SCHED;
;             PG8_LDA(At, 0, 1); PG8_STAGE(PG8_SB(0, 0), b2, vB0, vB1); PG8_STAGE(PG8_SB(0, 1), b2 + hstepB, vB0, vB1); PG8_STAGE(PG8_SA(0, 0), a2, vA0, vA1);
;             PG8_WAIT_V(8); PG8_WAIT_L(0); PG8_BAR; PG8_MMA(1, 0, At, B0); PG8_MMA(1, 1, At, B1); PG8_BAR; PG8_SCHED;
.LBB0_905:
	s_add_u32 s26, s26, 0x170080
	s_addc_u32 s27, s27, 0
	s_add_u32 s1, s28, 0x100
	s_addc_u32 s10, s29, 0
	s_mov_b32 s21, -2
	s_waitcnt lgkmcnt(0)
	s_add_u32 s28, s26, 0xffe90080
	s_addc_u32 s29, s27, -1
	s_add_i32 s56, 0, 0x10000
	s_cmp_eq_u32 s21, 12
	s_cselect_b32 s31, s23, s29
	s_cselect_b32 s30, s22, s28
	v_add_u32_e32 v144, s56, v148
	s_cselect_b32 s29, s25, s10
	s_cselect_b32 s28, s24, s1
	s_add_i32 vcc_lo, 0, 0x14000
	ds_read_b128 v[140:143], v144
	ds_read_b128 v[150:153], v144 offset:1024
	ds_read_b128 v[154:157], v144 offset:2048
	ds_read_b128 v[158:161], v144 offset:3072
	v_add_u32_e32 v144, vcc_lo, v148
	ds_read_b128 v[162:165], v144
	ds_read_b128 v[166:169], v144 offset:1024
	ds_read_b128 v[170:173], v144 offset:2048
	ds_read_b128 v[174:177], v144 offset:3072
	v_lshl_add_u64 v[144:145], s[26:27], 0, v[136:137]
	s_add_i32 m0, s74, 0xc000
	ds_read_b128 v[178:181], v149
	ds_read_b128 v[182:185], v149 offset:1024
	ds_read_b128 v[186:189], v149 offset:2048
	ds_read_b128 v[190:193], v149 offset:3072
	ds_read_b128 v[202:205], v149 offset:4096
	ds_read_b128 v[206:209], v149 offset:5120
	ds_read_b128 v[210:213], v149 offset:6144
	ds_read_b128 v[214:217], v149 offset:7168
	global_load_lds_dwordx4 v[144:145], off
	v_lshl_add_u64 v[144:145], s[26:27], 0, v[138:139]
	s_add_i32 m0, s74, 0xe000
	s_nop 0
	global_load_lds_dwordx4 v[144:145], off
	s_waitcnt vmcnt(8)
	s_waitcnt lgkmcnt(0)
	s_barrier
	s_setprio 1
	s_waitcnt lgkmcnt(0)
	v_mfma_f32_16x16x32_bf16 v[126:129], v[140:143], v[178:181], 0
	v_mfma_f32_16x16x32_bf16 v[122:125], v[154:157], v[178:181], 0
	v_mfma_f32_16x16x32_bf16 v[106:109], v[154:157], v[186:189], 0
	v_mfma_f32_16x16x32_bf16 v[110:113], v[140:143], v[186:189], 0
	v_mfma_f32_16x16x32_bf16 v[92:95], v[140:143], v[202:205], 0
	v_mfma_f32_16x16x32_bf16 v[88:91], v[154:157], v[202:205], 0
	v_mfma_f32_16x16x32_bf16 v[72:75], v[154:157], v[210:213], 0
	v_mfma_f32_16x16x32_bf16 v[76:79], v[140:143], v[210:213], 0
	v_mfma_f32_16x16x32_bf16 v[126:129], v[150:153], v[182:185], v[126:129]
	v_mfma_f32_16x16x32_bf16 v[122:125], v[158:161], v[182:185], v[122:125]
	v_mfma_f32_16x16x32_bf16 v[106:109], v[158:161], v[190:193], v[106:109]
	v_mfma_f32_16x16x32_bf16 v[110:113], v[150:153], v[190:193], v[110:113]
	v_mfma_f32_16x16x32_bf16 v[92:95], v[150:153], v[206:209], v[92:95]
	v_mfma_f32_16x16x32_bf16 v[88:91], v[158:161], v[206:209], v[88:91]
	v_mfma_f32_16x16x32_bf16 v[72:75], v[158:161], v[214:217], v[72:75]
	v_mfma_f32_16x16x32_bf16 v[76:79], v[150:153], v[214:217], v[76:79]
	s_setprio 0
	s_setprio 1
	v_mfma_f32_16x16x32_bf16 v[118:121], v[162:165], v[178:181], 0
	v_mfma_f32_16x16x32_bf16 v[114:117], v[170:173], v[178:181], 0
	v_mfma_f32_16x16x32_bf16 v[98:101], v[170:173], v[186:189], 0
	v_mfma_f32_16x16x32_bf16 v[102:105], v[162:165], v[186:189], 0
	v_mfma_f32_16x16x32_bf16 v[84:87], v[162:165], v[202:205], 0
	v_mfma_f32_16x16x32_bf16 v[80:83], v[170:173], v[202:205], 0
	v_mfma_f32_16x16x32_bf16 v[64:67], v[170:173], v[210:213], 0
	v_mfma_f32_16x16x32_bf16 v[68:71], v[162:165], v[210:213], 0
	v_mfma_f32_16x16x32_bf16 v[118:121], v[166:169], v[182:185], v[118:121]
	v_mfma_f32_16x16x32_bf16 v[114:117], v[174:177], v[182:185], v[114:117]
	v_mfma_f32_16x16x32_bf16 v[98:101], v[174:177], v[190:193], v[98:101]
	v_mfma_f32_16x16x32_bf16 v[102:105], v[166:169], v[190:193], v[102:105]
	v_mfma_f32_16x16x32_bf16 v[84:87], v[166:169], v[206:209], v[84:87]
	v_mfma_f32_16x16x32_bf16 v[80:83], v[174:177], v[206:209], v[80:83]
	v_mfma_f32_16x16x32_bf16 v[64:67], v[174:177], v[214:217], v[64:67]
	v_mfma_f32_16x16x32_bf16 v[68:71], v[166:169], v[214:217], v[68:71]
	s_setprio 0
	s_barrier
	s_add_i32 s56, s56, s73
	v_lshl_add_u64 v[144:145], s[28:29], 0, v[96:97]
	s_mov_b32 m0, s56
	ds_read_b128 v[178:181], v149 offset:16384
	ds_read_b128 v[182:185], v149 offset:17408
	ds_read_b128 v[186:189], v149 offset:18432
	ds_read_b128 v[190:193], v149 offset:19456
	ds_read_b128 v[202:205], v149 offset:20480
	ds_read_b128 v[206:209], v149 offset:21504
	ds_read_b128 v[210:213], v149 offset:22528
	ds_read_b128 v[214:217], v149 offset:23552
	global_load_lds_dwordx4 v[144:145], off
	s_add_i32 m0, s56, 0x2000
	s_add_u32 s56, s28, 0x40000
	v_lshl_add_u64 v[194:195], s[28:29], 0, v[130:131]
	s_addc_u32 s57, s29, 0
	s_add_i32 vcc_lo, vcc_lo, s73
	global_load_lds_dwordx4 v[194:195], off
	v_lshl_add_u64 v[218:219], s[56:57], 0, v[96:97]
	s_mov_b32 m0, vcc_lo
	v_lshl_add_u64 v[220:221], s[30:31], 0, v[134:135]
	global_load_lds_dwordx4 v[218:219], off
	v_lshl_add_u64 v[218:219], s[56:57], 0, v[130:131]
	s_add_i32 m0, vcc_lo, 0x2000
	s_nop 0
	global_load_lds_dwordx4 v[218:219], off
	v_lshl_add_u64 v[218:219], s[30:31], 0, v[132:133]
	s_mov_b32 m0, s74
	s_nop 0
	global_load_lds_dwordx4 v[218:219], off
	s_mov_b32 m0, s75
	s_nop 0
	global_load_lds_dwordx4 v[220:221], off
	s_waitcnt vmcnt(8)
	s_waitcnt lgkmcnt(0)
	s_barrier
; #define PG8_STAGE(bufoff, gbase, V0, V1) do { \
;         __builtin_amdgcn_global_load_lds((const unsigned*)((const char*)(gbase) + (V0)), (LAS unsigned*)(lds + (bufoff) + ldsw), 16, 0, 0); \
;         __builtin_amdgcn_global_load_lds((const unsigned*)((const char*)(gbase) + (V1)), (LAS unsigned*)(lds + (bufoff) + ldsw + 8192), 16, 0, 0); } while (0)
; #define PG8_LDA(dst, b, h) do { _Pragma("unroll") for (int m = 0; m < 4; ++m) _Pragma("unroll") for (int k = 0; k < 2; ++k) dst[m][k] = *(const LAS bf16x8*)(lds + PG8_SA(b, h) + aoff + m * 2048 + k * 1024); } while (0)
; #define PG8_LDB(dst, b, h) do { _Pragma("unroll") for (int n = 0; n < 2; ++n) _Pragma("unroll") for (int k = 0; k < 2; ++k) dst[n][k] = *(const LAS bf16x8*)(lds + PG8_SB(b, h) + boff + n * 2048 + k * 1024); } while (0)
; #define PG8_MMA(ai, bj, At, Bt) do { __builtin_amdgcn_s_setprio(1); _Pragma("unroll") for (int m = 0; m < 4; ++m) _Pragma("unroll") for (int n = 0; n < 2; ++n) _Pragma("unroll") for (int k = 0; k < 2; ++k) \
;         acc[ai][bj][m][n] = __builtin_amdgcn_mfma_f32_16x16x32_bf16(Bt[n][k], At[m][k], acc[ai][bj][m][n], 0, 0, 0); __builtin_amdgcn_s_setprio(0); } while (0)
; #define PG8_WAIT_V(n) asm volatile("s_waitcnt vmcnt(" #n ")" ::: "memory")
; #define PG8_WAIT_L(n) asm volatile("s_waitcnt lgkmcnt(" #n ")" ::: "memory")
; #define PG8_BAR __builtin_amdgcn_s_barrier()
; #define PG8_SCHED __builtin_amdgcn_sched_barrier(0)
; template <class Epi, class Sched>
; DI void gemm_phase(LAS unsigned char* lds, const int lda2, const int ldb2, const int nt, const Sched& S, const Epi& E) {
;     ...
;             PG8_WAIT_V(8); PG8_WAIT_L(0); PG8_BAR; PG8_MMA(0, 0, At, B0); PG8_MMA(0, 1, At, B1); PG8_BAR; PG8_SCHED;
;             PG8_LDA(At, 0, 1); PG8_STAGE(PG8_SB(0, 0), b2, vB0, vB1); PG8_STAGE(PG8_SB(0, 1), b2 + hstepB, vB0, vB1); PG8_STAGE(PG8_SA(0, 0), a2, vA0, vA1);
;             PG8_WAIT_V(8); PG8_WAIT_L(0); PG8_BAR; PG8_MMA(1, 0, At, B0); PG8_MMA(1, 1, At, B1); PG8_BAR; PG8_SCHED;
;             PG8_LDB(B0, 1, 0); PG8_LDB(B1, 1, 1); PG8_SCHED; PG8_LDA(At, 1, 0); PG8_STAGE(PG8_SA(0, 1), a2 + hstepA, vA0, vA1);
;             PG8_WAIT_V(8); PG8_WAIT_L(0); PG8_BAR; PG8_MMA(0, 0, At, B0); PG8_MMA(0, 1, At, B1); PG8_BAR; PG8_SCHED;
	s_setprio 1
	s_waitcnt lgkmcnt(0)
	v_mfma_f32_16x16x32_bf16 v[60:63], v[140:143], v[178:181], 0
	v_mfma_f32_16x16x32_bf16 v[56:59], v[154:157], v[178:181], 0
	v_mfma_f32_16x16x32_bf16 v[40:43], v[154:157], v[186:189], 0
	v_mfma_f32_16x16x32_bf16 v[44:47], v[140:143], v[186:189], 0
	v_mfma_f32_16x16x32_bf16 v[28:31], v[140:143], v[202:205], 0
	v_mfma_f32_16x16x32_bf16 v[24:27], v[154:157], v[202:205], 0
	v_mfma_f32_16x16x32_bf16 v[8:11], v[154:157], v[210:213], 0
	v_mfma_f32_16x16x32_bf16 v[12:15], v[140:143], v[210:213], 0
	v_mfma_f32_16x16x32_bf16 v[60:63], v[150:153], v[182:185], v[60:63]
	v_mfma_f32_16x16x32_bf16 v[56:59], v[158:161], v[182:185], v[56:59]
	v_mfma_f32_16x16x32_bf16 v[40:43], v[158:161], v[190:193], v[40:43]
	v_mfma_f32_16x16x32_bf16 v[44:47], v[150:153], v[190:193], v[44:47]
	v_mfma_f32_16x16x32_bf16 v[28:31], v[150:153], v[206:209], v[28:31]
	v_mfma_f32_16x16x32_bf16 v[24:27], v[158:161], v[206:209], v[24:27]
	v_mfma_f32_16x16x32_bf16 v[8:11], v[158:161], v[214:217], v[8:11]
	v_mfma_f32_16x16x32_bf16 v[12:15], v[150:153], v[214:217], v[12:15]
	s_setprio 0
	s_setprio 1
	v_mfma_f32_16x16x32_bf16 v[52:55], v[162:165], v[178:181], 0
	v_mfma_f32_16x16x32_bf16 v[48:51], v[170:173], v[178:181], 0
	v_mfma_f32_16x16x32_bf16 v[32:35], v[170:173], v[186:189], 0
	v_mfma_f32_16x16x32_bf16 v[36:39], v[162:165], v[186:189], 0
	v_mfma_f32_16x16x32_bf16 v[20:23], v[162:165], v[202:205], 0
	v_mfma_f32_16x16x32_bf16 v[16:19], v[170:173], v[202:205], 0
	v_mfma_f32_16x16x32_bf16 v[0:3], v[170:173], v[210:213], 0
	v_mfma_f32_16x16x32_bf16 v[4:7], v[162:165], v[210:213], 0
	v_mfma_f32_16x16x32_bf16 v[52:55], v[166:169], v[182:185], v[52:55]
	v_mfma_f32_16x16x32_bf16 v[48:51], v[174:177], v[182:185], v[48:51]
	v_mfma_f32_16x16x32_bf16 v[32:35], v[174:177], v[190:193], v[32:35]
	v_mfma_f32_16x16x32_bf16 v[36:39], v[166:169], v[190:193], v[36:39]
	v_mfma_f32_16x16x32_bf16 v[20:23], v[166:169], v[206:209], v[20:23]
	v_mfma_f32_16x16x32_bf16 v[16:19], v[174:177], v[206:209], v[16:19]
	v_mfma_f32_16x16x32_bf16 v[0:3], v[174:177], v[214:217], v[0:3]
	v_mfma_f32_16x16x32_bf16 v[4:7], v[166:169], v[214:217], v[4:7]
	s_setprio 0
	s_barrier
	s_add_i32 s56, 0, 0x18000
	s_add_i32 s57, 0, 0x1c000
	v_add_u32_e32 v158, s56, v148
	v_add_u32_e32 v174, s57, v148
	ds_read_b128 v[140:143], v158
	ds_read_b128 v[150:153], v158 offset:1024
	ds_read_b128 v[154:157], v158 offset:2048
	ds_read_b128 v[158:161], v158 offset:3072
	ds_read_b128 v[162:165], v174
	ds_read_b128 v[166:169], v174 offset:1024
	ds_read_b128 v[170:173], v174 offset:2048
	ds_read_b128 v[174:177], v174 offset:3072
	s_add_u32 s30, s30, 0x170000
	s_addc_u32 s31, s31, 0
	s_mov_b32 m0, s76
	v_lshl_add_u64 v[222:223], s[30:31], 0, v[132:133]
	ds_read_b128 v[178:181], v149 offset:32768
	ds_read_b128 v[182:185], v149 offset:33792
	ds_read_b128 v[186:189], v149 offset:34816
	ds_read_b128 v[190:193], v149 offset:35840
	ds_read_b128 v[202:205], v149 offset:36864
	ds_read_b128 v[206:209], v149 offset:37888
	ds_read_b128 v[210:213], v149 offset:38912
	ds_read_b128 v[214:217], v149 offset:39936
	global_load_lds_dwordx4 v[222:223], off
	v_lshl_add_u64 v[222:223], s[30:31], 0, v[134:135]
	s_mov_b32 m0, s77
	s_nop 0
	global_load_lds_dwordx4 v[222:223], off
	s_waitcnt vmcnt(8)
	s_waitcnt lgkmcnt(0)
	s_barrier
	s_setprio 1
	s_waitcnt lgkmcnt(0)
	v_mfma_f32_16x16x32_bf16 v[126:129], v[140:143], v[178:181], v[126:129]
	v_mfma_f32_16x16x32_bf16 v[122:125], v[154:157], v[178:181], v[122:125]
	v_mfma_f32_16x16x32_bf16 v[106:109], v[154:157], v[186:189], v[106:109]
	v_mfma_f32_16x16x32_bf16 v[110:113], v[140:143], v[186:189], v[110:113]
	v_mfma_f32_16x16x32_bf16 v[92:95], v[140:143], v[202:205], v[92:95]
	v_mfma_f32_16x16x32_bf16 v[88:91], v[154:157], v[202:205], v[88:91]
	v_mfma_f32_16x16x32_bf16 v[72:75], v[154:157], v[210:213], v[72:75]
	v_mfma_f32_16x16x32_bf16 v[76:79], v[140:143], v[210:213], v[76:79]
	v_mfma_f32_16x16x32_bf16 v[126:129], v[150:153], v[182:185], v[126:129]
	v_mfma_f32_16x16x32_bf16 v[122:125], v[158:161], v[182:185], v[122:125]
	v_mfma_f32_16x16x32_bf16 v[106:109], v[158:161], v[190:193], v[106:109]
	v_mfma_f32_16x16x32_bf16 v[110:113], v[150:153], v[190:193], v[110:113]
	v_mfma_f32_16x16x32_bf16 v[92:95], v[150:153], v[206:209], v[92:95]
	v_mfma_f32_16x16x32_bf16 v[88:91], v[158:161], v[206:209], v[88:91]
	v_mfma_f32_16x16x32_bf16 v[72:75], v[158:161], v[214:217], v[72:75]
	v_mfma_f32_16x16x32_bf16 v[76:79], v[150:153], v[214:217], v[76:79]
	s_setprio 0
	s_setprio 1
	v_mfma_f32_16x16x32_bf16 v[118:121], v[162:165], v[178:181], v[118:121]
	v_mfma_f32_16x16x32_bf16 v[114:117], v[170:173], v[178:181], v[114:117]
	v_mfma_f32_16x16x32_bf16 v[98:101], v[170:173], v[186:189], v[98:101]
	v_mfma_f32_16x16x32_bf16 v[102:105], v[162:165], v[186:189], v[102:105]
	v_mfma_f32_16x16x32_bf16 v[84:87], v[162:165], v[202:205], v[84:87]
	v_mfma_f32_16x16x32_bf16 v[80:83], v[170:173], v[202:205], v[80:83]
	v_mfma_f32_16x16x32_bf16 v[64:67], v[170:173], v[210:213], v[64:67]
	v_mfma_f32_16x16x32_bf16 v[68:71], v[162:165], v[210:213], v[68:71]
	v_mfma_f32_16x16x32_bf16 v[118:121], v[166:169], v[182:185], v[118:121]
	v_mfma_f32_16x16x32_bf16 v[114:117], v[174:177], v[182:185], v[114:117]
	v_mfma_f32_16x16x32_bf16 v[98:101], v[174:177], v[190:193], v[98:101]
	v_mfma_f32_16x16x32_bf16 v[102:105], v[166:169], v[190:193], v[102:105]
	v_mfma_f32_16x16x32_bf16 v[84:87], v[166:169], v[206:209], v[84:87]
	v_mfma_f32_16x16x32_bf16 v[80:83], v[174:177], v[206:209], v[80:83]
	v_mfma_f32_16x16x32_bf16 v[64:67], v[174:177], v[214:217], v[64:67]
	v_mfma_f32_16x16x32_bf16 v[68:71], v[166:169], v[214:217], v[68:71]
	s_setprio 0
	s_barrier
; #define PG8_STAGE(bufoff, gbase, V0, V1) do { \
;         __builtin_amdgcn_global_load_lds((const unsigned*)((const char*)(gbase) + (V0)), (LAS unsigned*)(lds + (bufoff) + ldsw), 16, 0, 0); \
;         __builtin_amdgcn_global_load_lds((const unsigned*)((const char*)(gbase) + (V1)), (LAS unsigned*)(lds + (bufoff) + ldsw + 8192), 16, 0, 0); } while (0)
; #define PG8_LDA(dst, b, h) do { _Pragma("unroll") for (int m = 0; m < 4; ++m) _Pragma("unroll") for (int k = 0; k < 2; ++k) dst[m][k] = *(const LAS bf16x8*)(lds + PG8_SA(b, h) + aoff + m * 2048 + k * 1024); } while (0)
; #define PG8_LDB(dst, b, h) do { _Pragma("unroll") for (int n = 0; n < 2; ++n) _Pragma("unroll") for (int k = 0; k < 2; ++k) dst[n][k] = *(const LAS bf16x8*)(lds + PG8_SB(b, h) + boff + n * 2048 + k * 1024); } while (0)
; #define PG8_WAIT_V(n) asm volatile("s_waitcnt vmcnt(" #n ")" ::: "memory")
; #define PG8_WAIT_L(n) asm volatile("s_waitcnt lgkmcnt(" #n ")" ::: "memory")
; #define PG8_BAR __builtin_amdgcn_s_barrier()
; #define PG8_SCHED __builtin_amdgcn_sched_barrier(0)
; template <class Epi, class Sched>
; DI void gemm_phase(LAS unsigned char* lds, const int lda2, const int ldb2, const int nt, const Sched& S, const Epi& E) {
;     ...
;         for (int t = 0; t < nt; t += 2) {
;             const bool last = (t == nt - 2);
;             const char* a1 = cA + (size_t)(t + 1) * kstep;
;             const char* a2 = last ? nA : cA + (size_t)(t + 2) * kstep; const char* b2 = last ? nB : cB + (size_t)(t + 2) * kstep;
;             const char* a3 = a2 + kstep; const char* b3 = b2 + kstep;
;             PG8_LDB(B0, 0, 0); PG8_LDB(B1, 0, 1); PG8_SCHED; PG8_LDA(At, 0, 0); PG8_STAGE(PG8_SA(1, 1), a1 + hstepA, vA0, vA1);
;             PG8_WAIT_V(8); PG8_WAIT_L(0); PG8_BAR; PG8_MMA(0, 0, At, B0); PG8_MMA(0, 1, At, B1); PG8_BAR; PG8_SCHED;
;     ...
;             PG8_LDB(B0, 1, 0); PG8_LDB(B1, 1, 1); PG8_SCHED; PG8_LDA(At, 1, 0); PG8_STAGE(PG8_SA(0, 1), a2 + hstepA, vA0, vA1);
;             PG8_WAIT_V(8); PG8_WAIT_L(0); PG8_BAR; PG8_MMA(0, 0, At, B0); PG8_MMA(0, 1, At, B1); PG8_BAR; PG8_SCHED;
;             PG8_LDA(At, 1, 1); PG8_STAGE(PG8_SB(1, 0), b3, vB0, vB1); PG8_STAGE(PG8_SB(1, 1), b3 + hstepB, vB0, vB1); PG8_STAGE(PG8_SA(1, 0), a3, vA0, vA1);
;             PG8_WAIT_V(8); PG8_WAIT_L(0); PG8_BAR; PG8_MMA(1, 0, At, B0); PG8_MMA(1, 1, At, B1); PG8_BAR; PG8_SCHED;
	s_add_i32 s30, s56, s73
	v_lshl_add_u64 v[144:145], v[144:145], 0, s[86:87]
	s_mov_b32 m0, s30
	ds_read_b128 v[178:181], v149 offset:49152
	ds_read_b128 v[182:185], v149 offset:50176
	ds_read_b128 v[186:189], v149 offset:51200
	ds_read_b128 v[190:193], v149 offset:52224
	ds_read_b128 v[202:205], v149 offset:53248
	ds_read_b128 v[206:209], v149 offset:54272
	ds_read_b128 v[210:213], v149 offset:55296
	ds_read_b128 v[214:217], v149 offset:56320
	global_load_lds_dwordx4 v[144:145], off
	s_add_i32 m0, s30, 0x2000
	s_add_u32 s28, s28, 0x40080
	v_lshl_add_u64 v[144:145], v[194:195], 0, s[86:87]
	s_addc_u32 s29, s29, 0
	s_add_i32 s30, s57, s73
	global_load_lds_dwordx4 v[144:145], off
	v_lshl_add_u64 v[144:145], s[28:29], 0, v[96:97]
	s_mov_b32 m0, s30
	s_nop 0
	global_load_lds_dwordx4 v[144:145], off
	v_lshl_add_u64 v[144:145], s[28:29], 0, v[130:131]
	s_add_i32 m0, s30, 0x2000
	s_nop 0
	global_load_lds_dwordx4 v[144:145], off
	v_lshl_add_u64 v[144:145], v[218:219], 0, s[86:87]
	s_mov_b32 m0, s81
	s_nop 0
	global_load_lds_dwordx4 v[144:145], off
	v_lshl_add_u64 v[144:145], v[220:221], 0, s[86:87]
	s_mov_b32 m0, s82
	s_nop 0
	global_load_lds_dwordx4 v[144:145], off
	s_waitcnt vmcnt(8)
	s_waitcnt lgkmcnt(0)
	s_barrier
	s_setprio 1
	s_waitcnt lgkmcnt(0)
	v_mfma_f32_16x16x32_bf16 v[60:63], v[140:143], v[178:181], v[60:63]
	v_mfma_f32_16x16x32_bf16 v[56:59], v[154:157], v[178:181], v[56:59]
	v_mfma_f32_16x16x32_bf16 v[40:43], v[154:157], v[186:189], v[40:43]
	v_mfma_f32_16x16x32_bf16 v[44:47], v[140:143], v[186:189], v[44:47]
	v_mfma_f32_16x16x32_bf16 v[28:31], v[140:143], v[202:205], v[28:31]
	v_mfma_f32_16x16x32_bf16 v[24:27], v[154:157], v[202:205], v[24:27]
	v_mfma_f32_16x16x32_bf16 v[8:11], v[154:157], v[210:213], v[8:11]
	v_mfma_f32_16x16x32_bf16 v[12:15], v[140:143], v[210:213], v[12:15]
	v_mfma_f32_16x16x32_bf16 v[60:63], v[150:153], v[182:185], v[60:63]
	v_mfma_f32_16x16x32_bf16 v[56:59], v[158:161], v[182:185], v[56:59]
	v_mfma_f32_16x16x32_bf16 v[40:43], v[158:161], v[190:193], v[40:43]
	v_mfma_f32_16x16x32_bf16 v[44:47], v[150:153], v[190:193], v[44:47]
	v_mfma_f32_16x16x32_bf16 v[28:31], v[150:153], v[206:209], v[28:31]
	v_mfma_f32_16x16x32_bf16 v[24:27], v[158:161], v[206:209], v[24:27]
	v_mfma_f32_16x16x32_bf16 v[8:11], v[158:161], v[214:217], v[8:11]
	v_mfma_f32_16x16x32_bf16 v[12:15], v[150:153], v[214:217], v[12:15]
	s_setprio 0
	s_setprio 1
	v_mfma_f32_16x16x32_bf16 v[52:55], v[162:165], v[178:181], v[52:55]
	v_mfma_f32_16x16x32_bf16 v[48:51], v[170:173], v[178:181], v[48:51]
	v_mfma_f32_16x16x32_bf16 v[32:35], v[170:173], v[186:189], v[32:35]
	v_mfma_f32_16x16x32_bf16 v[36:39], v[162:165], v[186:189], v[36:39]
	v_mfma_f32_16x16x32_bf16 v[20:23], v[162:165], v[202:205], v[20:23]
	v_mfma_f32_16x16x32_bf16 v[16:19], v[170:173], v[202:205], v[16:19]
	v_mfma_f32_16x16x32_bf16 v[0:3], v[170:173], v[210:213], v[0:3]
	v_mfma_f32_16x16x32_bf16 v[4:7], v[162:165], v[210:213], v[4:7]
	v_mfma_f32_16x16x32_bf16 v[52:55], v[166:169], v[182:185], v[52:55]
	v_mfma_f32_16x16x32_bf16 v[48:51], v[174:177], v[182:185], v[48:51]
	v_mfma_f32_16x16x32_bf16 v[32:35], v[174:177], v[190:193], v[32:35]
	v_mfma_f32_16x16x32_bf16 v[36:39], v[166:169], v[190:193], v[36:39]
	v_mfma_f32_16x16x32_bf16 v[20:23], v[166:169], v[206:209], v[20:23]
	v_mfma_f32_16x16x32_bf16 v[16:19], v[174:177], v[206:209], v[16:19]
	v_mfma_f32_16x16x32_bf16 v[0:3], v[174:177], v[214:217], v[0:3]
	v_mfma_f32_16x16x32_bf16 v[4:7], v[166:169], v[214:217], v[4:7]
	s_setprio 0
	s_barrier
	s_add_i32 s21, s21, 2
	s_add_u32 s26, s26, 0x100
	s_addc_u32 s27, s27, 0
	s_add_u32 s1, s1, 0x100
	s_addc_u32 s10, s10, 0
.LBB0_906:
	s_add_u32 s28, s26, 0xffe90080
	s_addc_u32 s29, s27, -1
	s_add_i32 s56, 0, 0x10000
	s_cmp_eq_u32 s21, 12
	s_cselect_b32 s31, s23, s29
	s_cselect_b32 s30, s22, s28
	v_add_u32_e32 v144, s56, v148
	s_cselect_b32 s29, s25, s10
	s_cselect_b32 s28, s24, s1
	s_add_i32 vcc_lo, 0, 0x14000
	ds_read_b128 v[140:143], v144
	ds_read_b128 v[150:153], v144 offset:1024
	ds_read_b128 v[154:157], v144 offset:2048
	ds_read_b128 v[158:161], v144 offset:3072
	v_add_u32_e32 v144, vcc_lo, v148
	ds_read_b128 v[162:165], v144
	ds_read_b128 v[166:169], v144 offset:1024
	ds_read_b128 v[170:173], v144 offset:2048
	ds_read_b128 v[174:177], v144 offset:3072
	v_lshl_add_u64 v[144:145], s[26:27], 0, v[136:137]
	s_add_i32 m0, s74, 0xc000
	ds_read_b128 v[178:181], v149
	ds_read_b128 v[182:185], v149 offset:1024
	ds_read_b128 v[186:189], v149 offset:2048
	ds_read_b128 v[190:193], v149 offset:3072
	ds_read_b128 v[202:205], v149 offset:4096
	ds_read_b128 v[206:209], v149 offset:5120
	ds_read_b128 v[210:213], v149 offset:6144
	ds_read_b128 v[214:217], v149 offset:7168
	global_load_lds_dwordx4 v[144:145], off
	v_lshl_add_u64 v[144:145], s[26:27], 0, v[138:139]
	s_add_i32 m0, s74, 0xe000
	s_nop 0
	global_load_lds_dwordx4 v[144:145], off
	s_waitcnt vmcnt(8)
	s_waitcnt lgkmcnt(0)
	s_barrier
; #define PG8_STAGE(bufoff, gbase, V0, V1) do { \
;         __builtin_amdgcn_global_load_lds((const unsigned*)((const char*)(gbase) + (V0)), (LAS unsigned*)(lds + (bufoff) + ldsw), 16, 0, 0); \
;         __builtin_amdgcn_global_load_lds((const unsigned*)((const char*)(gbase) + (V1)), (LAS unsigned*)(lds + (bufoff) + ldsw + 8192), 16, 0, 0); } while (0)
; #define PG8_LDA(dst, b, h) do { _Pragma("unroll") for (int m = 0; m < 4; ++m) _Pragma("unroll") for (int k = 0; k < 2; ++k) dst[m][k] = *(const LAS bf16x8*)(lds + PG8_SA(b, h) + aoff + m * 2048 + k * 1024); } while (0)
; #define PG8_LDB(dst, b, h) do { _Pragma("unroll") for (int n = 0; n < 2; ++n) _Pragma("unroll") for (int k = 0; k < 2; ++k) dst[n][k] = *(const LAS bf16x8*)(lds + PG8_SB(b, h) + boff + n * 2048 + k * 1024); } while (0)
; #define PG8_MMA(ai, bj, At, Bt) do { __builtin_amdgcn_s_setprio(1); _Pragma("unroll") for (int m = 0; m < 4; ++m) _Pragma("unroll") for (int n = 0; n < 2; ++n) _Pragma("unroll") for (int k = 0; k < 2; ++k) \
;         acc[ai][bj][m][n] = __builtin_amdgcn_mfma_f32_16x16x32_bf16(Bt[n][k], At[m][k], acc[ai][bj][m][n], 0, 0, 0); __builtin_amdgcn_s_setprio(0); } while (0)
; #define PG8_WAIT_V(n) asm volatile("s_waitcnt vmcnt(" #n ")" ::: "memory")
; #define PG8_WAIT_L(n) asm volatile("s_waitcnt lgkmcnt(" #n ")" ::: "memory")
; #define PG8_BAR __builtin_amdgcn_s_barrier()
; #define PG8_SCHED __builtin_amdgcn_sched_barrier(0)
; template <class Epi, class Sched>
; DI void gemm_phase(LAS unsigned char* lds, const int lda2, const int ldb2, const int nt, const Sched& S, const Epi& E) {
;     ...
;             PG8_WAIT_V(8); PG8_WAIT_L(0); PG8_BAR; PG8_MMA(0, 0, At, B0); PG8_MMA(0, 1, At, B1); PG8_BAR; PG8_SCHED;
;             PG8_LDA(At, 0, 1); PG8_STAGE(PG8_SB(0, 0), b2, vB0, vB1); PG8_STAGE(PG8_SB(0, 1), b2 + hstepB, vB0, vB1); PG8_STAGE(PG8_SA(0, 0), a2, vA0, vA1);
;             PG8_WAIT_V(8); PG8_WAIT_L(0); PG8_BAR; PG8_MMA(1, 0, At, B0); PG8_MMA(1, 1, At, B1); PG8_BAR; PG8_SCHED;
;             PG8_LDB(B0, 1, 0); PG8_LDB(B1, 1, 1); PG8_SCHED; PG8_LDA(At, 1, 0); PG8_STAGE(PG8_SA(0, 1), a2 + hstepA, vA0, vA1);
;             PG8_WAIT_V(8); PG8_WAIT_L(0); PG8_BAR; PG8_MMA(0, 0, At, B0); PG8_MMA(0, 1, At, B1); PG8_BAR; PG8_SCHED;
	s_setprio 1
	s_waitcnt lgkmcnt(0)
	v_mfma_f32_16x16x32_bf16 v[126:129], v[140:143], v[178:181], v[126:129]
	v_mfma_f32_16x16x32_bf16 v[122:125], v[154:157], v[178:181], v[122:125]
	v_mfma_f32_16x16x32_bf16 v[106:109], v[154:157], v[186:189], v[106:109]
	v_mfma_f32_16x16x32_bf16 v[110:113], v[140:143], v[186:189], v[110:113]
	v_mfma_f32_16x16x32_bf16 v[92:95], v[140:143], v[202:205], v[92:95]
	v_mfma_f32_16x16x32_bf16 v[88:91], v[154:157], v[202:205], v[88:91]
	v_mfma_f32_16x16x32_bf16 v[72:75], v[154:157], v[210:213], v[72:75]
	v_mfma_f32_16x16x32_bf16 v[76:79], v[140:143], v[210:213], v[76:79]
	v_mfma_f32_16x16x32_bf16 v[126:129], v[150:153], v[182:185], v[126:129]
	v_mfma_f32_16x16x32_bf16 v[122:125], v[158:161], v[182:185], v[122:125]
	v_mfma_f32_16x16x32_bf16 v[106:109], v[158:161], v[190:193], v[106:109]
	v_mfma_f32_16x16x32_bf16 v[110:113], v[150:153], v[190:193], v[110:113]
	v_mfma_f32_16x16x32_bf16 v[92:95], v[150:153], v[206:209], v[92:95]
	v_mfma_f32_16x16x32_bf16 v[88:91], v[158:161], v[206:209], v[88:91]
	v_mfma_f32_16x16x32_bf16 v[72:75], v[158:161], v[214:217], v[72:75]
	v_mfma_f32_16x16x32_bf16 v[76:79], v[150:153], v[214:217], v[76:79]
	s_setprio 0
	s_setprio 1
	v_mfma_f32_16x16x32_bf16 v[118:121], v[162:165], v[178:181], v[118:121]
	v_mfma_f32_16x16x32_bf16 v[114:117], v[170:173], v[178:181], v[114:117]
	v_mfma_f32_16x16x32_bf16 v[98:101], v[170:173], v[186:189], v[98:101]
	v_mfma_f32_16x16x32_bf16 v[102:105], v[162:165], v[186:189], v[102:105]
	v_mfma_f32_16x16x32_bf16 v[84:87], v[162:165], v[202:205], v[84:87]
	v_mfma_f32_16x16x32_bf16 v[80:83], v[170:173], v[202:205], v[80:83]
	v_mfma_f32_16x16x32_bf16 v[64:67], v[170:173], v[210:213], v[64:67]
	v_mfma_f32_16x16x32_bf16 v[68:71], v[162:165], v[210:213], v[68:71]
	v_mfma_f32_16x16x32_bf16 v[118:121], v[166:169], v[182:185], v[118:121]
	v_mfma_f32_16x16x32_bf16 v[114:117], v[174:177], v[182:185], v[114:117]
	v_mfma_f32_16x16x32_bf16 v[98:101], v[174:177], v[190:193], v[98:101]
	v_mfma_f32_16x16x32_bf16 v[102:105], v[166:169], v[190:193], v[102:105]
	v_mfma_f32_16x16x32_bf16 v[84:87], v[166:169], v[206:209], v[84:87]
	v_mfma_f32_16x16x32_bf16 v[80:83], v[174:177], v[206:209], v[80:83]
	v_mfma_f32_16x16x32_bf16 v[64:67], v[174:177], v[214:217], v[64:67]
	v_mfma_f32_16x16x32_bf16 v[68:71], v[166:169], v[214:217], v[68:71]
	s_setprio 0
	s_barrier
	s_add_i32 s56, s56, s73
	v_lshl_add_u64 v[144:145], s[28:29], 0, v[96:97]
	s_mov_b32 m0, s56
	ds_read_b128 v[178:181], v149 offset:16384
	ds_read_b128 v[182:185], v149 offset:17408
	ds_read_b128 v[186:189], v149 offset:18432
	ds_read_b128 v[190:193], v149 offset:19456
	ds_read_b128 v[202:205], v149 offset:20480
	ds_read_b128 v[206:209], v149 offset:21504
	ds_read_b128 v[210:213], v149 offset:22528
	ds_read_b128 v[214:217], v149 offset:23552
	global_load_lds_dwordx4 v[144:145], off
	s_add_i32 m0, s56, 0x2000
	s_add_u32 s56, s28, 0x40000
	v_lshl_add_u64 v[194:195], s[28:29], 0, v[130:131]
	s_addc_u32 s57, s29, 0
	s_add_i32 vcc_lo, vcc_lo, s73
	global_load_lds_dwordx4 v[194:195], off
	v_lshl_add_u64 v[218:219], s[56:57], 0, v[96:97]
	s_mov_b32 m0, vcc_lo
	v_lshl_add_u64 v[220:221], s[30:31], 0, v[134:135]
	global_load_lds_dwordx4 v[218:219], off
	v_lshl_add_u64 v[218:219], s[56:57], 0, v[130:131]
	s_add_i32 m0, vcc_lo, 0x2000
	s_nop 0
	global_load_lds_dwordx4 v[218:219], off
	v_lshl_add_u64 v[218:219], s[30:31], 0, v[132:133]
	s_mov_b32 m0, s74
	s_nop 0
	global_load_lds_dwordx4 v[218:219], off
	s_mov_b32 m0, s75
	s_nop 0
	global_load_lds_dwordx4 v[220:221], off
	s_waitcnt vmcnt(8)
	s_waitcnt lgkmcnt(0)
	s_barrier
	s_setprio 1
	s_waitcnt lgkmcnt(0)
	v_mfma_f32_16x16x32_bf16 v[60:63], v[140:143], v[178:181], v[60:63]
	v_mfma_f32_16x16x32_bf16 v[56:59], v[154:157], v[178:181], v[56:59]
	v_mfma_f32_16x16x32_bf16 v[40:43], v[154:157], v[186:189], v[40:43]
	v_mfma_f32_16x16x32_bf16 v[44:47], v[140:143], v[186:189], v[44:47]
	v_mfma_f32_16x16x32_bf16 v[28:31], v[140:143], v[202:205], v[28:31]
	v_mfma_f32_16x16x32_bf16 v[24:27], v[154:157], v[202:205], v[24:27]
	v_mfma_f32_16x16x32_bf16 v[8:11], v[154:157], v[210:213], v[8:11]
	v_mfma_f32_16x16x32_bf16 v[12:15], v[140:143], v[210:213], v[12:15]
	v_mfma_f32_16x16x32_bf16 v[60:63], v[150:153], v[182:185], v[60:63]
	v_mfma_f32_16x16x32_bf16 v[56:59], v[158:161], v[182:185], v[56:59]
	v_mfma_f32_16x16x32_bf16 v[40:43], v[158:161], v[190:193], v[40:43]
	v_mfma_f32_16x16x32_bf16 v[44:47], v[150:153], v[190:193], v[44:47]
	v_mfma_f32_16x16x32_bf16 v[28:31], v[150:153], v[206:209], v[28:31]
	v_mfma_f32_16x16x32_bf16 v[24:27], v[158:161], v[206:209], v[24:27]
	v_mfma_f32_16x16x32_bf16 v[8:11], v[158:161], v[214:217], v[8:11]
	v_mfma_f32_16x16x32_bf16 v[12:15], v[150:153], v[214:217], v[12:15]
	s_setprio 0
	s_setprio 1
	v_mfma_f32_16x16x32_bf16 v[52:55], v[162:165], v[178:181], v[52:55]
	v_mfma_f32_16x16x32_bf16 v[48:51], v[170:173], v[178:181], v[48:51]
	v_mfma_f32_16x16x32_bf16 v[32:35], v[170:173], v[186:189], v[32:35]
	v_mfma_f32_16x16x32_bf16 v[36:39], v[162:165], v[186:189], v[36:39]
	v_mfma_f32_16x16x32_bf16 v[20:23], v[162:165], v[202:205], v[20:23]
	v_mfma_f32_16x16x32_bf16 v[16:19], v[170:173], v[202:205], v[16:19]
	v_mfma_f32_16x16x32_bf16 v[0:3], v[170:173], v[210:213], v[0:3]
	v_mfma_f32_16x16x32_bf16 v[4:7], v[162:165], v[210:213], v[4:7]
	v_mfma_f32_16x16x32_bf16 v[52:55], v[166:169], v[182:185], v[52:55]
	v_mfma_f32_16x16x32_bf16 v[48:51], v[174:177], v[182:185], v[48:51]
	v_mfma_f32_16x16x32_bf16 v[32:35], v[174:177], v[190:193], v[32:35]
	v_mfma_f32_16x16x32_bf16 v[36:39], v[166:169], v[190:193], v[36:39]
	v_mfma_f32_16x16x32_bf16 v[20:23], v[166:169], v[206:209], v[20:23]
	v_mfma_f32_16x16x32_bf16 v[16:19], v[174:177], v[206:209], v[16:19]
	v_mfma_f32_16x16x32_bf16 v[0:3], v[174:177], v[214:217], v[0:3]
	v_mfma_f32_16x16x32_bf16 v[4:7], v[166:169], v[214:217], v[4:7]
	s_setprio 0
	s_barrier
; #define PG8_STAGE(bufoff, gbase, V0, V1) do { \
;         __builtin_amdgcn_global_load_lds((const unsigned*)((const char*)(gbase) + (V0)), (LAS unsigned*)(lds + (bufoff) + ldsw), 16, 0, 0); \
;         __builtin_amdgcn_global_load_lds((const unsigned*)((const char*)(gbase) + (V1)), (LAS unsigned*)(lds + (bufoff) + ldsw + 8192), 16, 0, 0); } while (0)
; #define PG8_LDA(dst, b, h) do { _Pragma("unroll") for (int m = 0; m < 4; ++m) _Pragma("unroll") for (int k = 0; k < 2; ++k) dst[m][k] = *(const LAS bf16x8*)(lds + PG8_SA(b, h) + aoff + m * 2048 + k * 1024); } while (0)
; #define PG8_LDB(dst, b, h) do { _Pragma("unroll") for (int n = 0; n < 2; ++n) _Pragma("unroll") for (int k = 0; k < 2; ++k) dst[n][k] = *(const LAS bf16x8*)(lds + PG8_SB(b, h) + boff + n * 2048 + k * 1024); } while (0)
; #define PG8_MMA(ai, bj, At, Bt) do { __builtin_amdgcn_s_setprio(1); _Pragma("unroll") for (int m = 0; m < 4; ++m) _Pragma("unroll") for (int n = 0; n < 2; ++n) _Pragma("unroll") for (int k = 0; k < 2; ++k) \
;         acc[ai][bj][m][n] = __builtin_amdgcn_mfma_f32_16x16x32_bf16(Bt[n][k], At[m][k], acc[ai][bj][m][n], 0, 0, 0); __builtin_amdgcn_s_setprio(0); } while (0)
; #define PG8_WAIT_V(n) asm volatile("s_waitcnt vmcnt(" #n ")" ::: "memory")
; #define PG8_WAIT_L(n) asm volatile("s_waitcnt lgkmcnt(" #n ")" ::: "memory")
; #define PG8_BAR __builtin_amdgcn_s_barrier()
; #define PG8_SCHED __builtin_amdgcn_sched_barrier(0)
; template <class Epi, class Sched>
; DI void gemm_phase(LAS unsigned char* lds, const int lda2, const int ldb2, const int nt, const Sched& S, const Epi& E) {
;     ...
;             PG8_LDB(B0, 1, 0); PG8_LDB(B1, 1, 1); PG8_SCHED; PG8_LDA(At, 1, 0); PG8_STAGE(PG8_SA(0, 1), a2 + hstepA, vA0, vA1);
;             PG8_WAIT_V(8); PG8_WAIT_L(0); PG8_BAR; PG8_MMA(0, 0, At, B0); PG8_MMA(0, 1, At, B1); PG8_BAR; PG8_SCHED;
	s_add_i32 s56, 0, 0x18000
	s_add_i32 s57, 0, 0x1c000
	v_add_u32_e32 v158, s56, v148
	v_add_u32_e32 v174, s57, v148
	ds_read_b128 v[140:143], v158
	ds_read_b128 v[150:153], v158 offset:1024
	ds_read_b128 v[154:157], v158 offset:2048
	ds_read_b128 v[158:161], v158 offset:3072
	ds_read_b128 v[162:165], v174
	ds_read_b128 v[166:169], v174 offset:1024
	ds_read_b128 v[170:173], v174 offset:2048
	ds_read_b128 v[174:177], v174 offset:3072
	s_add_u32 s30, s30, 0x170000
	s_addc_u32 s31, s31, 0
	s_mov_b32 m0, s76
	v_lshl_add_u64 v[222:223], s[30:31], 0, v[132:133]
	ds_read_b128 v[178:181], v149 offset:32768
	ds_read_b128 v[182:185], v149 offset:33792
	ds_read_b128 v[186:189], v149 offset:34816
	ds_read_b128 v[190:193], v149 offset:35840
	ds_read_b128 v[202:205], v149 offset:36864
	ds_read_b128 v[206:209], v149 offset:37888
	ds_read_b128 v[210:213], v149 offset:38912
	ds_read_b128 v[214:217], v149 offset:39936
	global_load_lds_dwordx4 v[222:223], off
	v_lshl_add_u64 v[222:223], s[30:31], 0, v[134:135]
	s_mov_b32 m0, s77
	s_nop 0
	global_load_lds_dwordx4 v[222:223], off
	s_waitcnt vmcnt(8)
	s_waitcnt lgkmcnt(0)
	s_barrier
	s_setprio 1
	s_waitcnt lgkmcnt(0)
	v_mfma_f32_16x16x32_bf16 v[126:129], v[140:143], v[178:181], v[126:129]
	v_mfma_f32_16x16x32_bf16 v[122:125], v[154:157], v[178:181], v[122:125]
	v_mfma_f32_16x16x32_bf16 v[106:109], v[154:157], v[186:189], v[106:109]
	v_mfma_f32_16x16x32_bf16 v[110:113], v[140:143], v[186:189], v[110:113]
	v_mfma_f32_16x16x32_bf16 v[92:95], v[140:143], v[202:205], v[92:95]
	v_mfma_f32_16x16x32_bf16 v[88:91], v[154:157], v[202:205], v[88:91]
	v_mfma_f32_16x16x32_bf16 v[72:75], v[154:157], v[210:213], v[72:75]
	v_mfma_f32_16x16x32_bf16 v[76:79], v[140:143], v[210:213], v[76:79]
	v_mfma_f32_16x16x32_bf16 v[126:129], v[150:153], v[182:185], v[126:129]
	v_mfma_f32_16x16x32_bf16 v[122:125], v[158:161], v[182:185], v[122:125]
	v_mfma_f32_16x16x32_bf16 v[106:109], v[158:161], v[190:193], v[106:109]
	v_mfma_f32_16x16x32_bf16 v[110:113], v[150:153], v[190:193], v[110:113]
	v_mfma_f32_16x16x32_bf16 v[92:95], v[150:153], v[206:209], v[92:95]
	v_mfma_f32_16x16x32_bf16 v[88:91], v[158:161], v[206:209], v[88:91]
	v_mfma_f32_16x16x32_bf16 v[72:75], v[158:161], v[214:217], v[72:75]
	v_mfma_f32_16x16x32_bf16 v[76:79], v[150:153], v[214:217], v[76:79]
	s_setprio 0
	s_setprio 1
	v_mfma_f32_16x16x32_bf16 v[118:121], v[162:165], v[178:181], v[118:121]
	v_mfma_f32_16x16x32_bf16 v[114:117], v[170:173], v[178:181], v[114:117]
	v_mfma_f32_16x16x32_bf16 v[98:101], v[170:173], v[186:189], v[98:101]
	v_mfma_f32_16x16x32_bf16 v[102:105], v[162:165], v[186:189], v[102:105]
	v_mfma_f32_16x16x32_bf16 v[84:87], v[162:165], v[202:205], v[84:87]
	v_mfma_f32_16x16x32_bf16 v[80:83], v[170:173], v[202:205], v[80:83]
	v_mfma_f32_16x16x32_bf16 v[64:67], v[170:173], v[210:213], v[64:67]
	v_mfma_f32_16x16x32_bf16 v[68:71], v[162:165], v[210:213], v[68:71]
	v_mfma_f32_16x16x32_bf16 v[118:121], v[166:169], v[182:185], v[118:121]
	v_mfma_f32_16x16x32_bf16 v[114:117], v[174:177], v[182:185], v[114:117]
	v_mfma_f32_16x16x32_bf16 v[98:101], v[174:177], v[190:193], v[98:101]
	v_mfma_f32_16x16x32_bf16 v[102:105], v[166:169], v[190:193], v[102:105]
	v_mfma_f32_16x16x32_bf16 v[84:87], v[166:169], v[206:209], v[84:87]
	v_mfma_f32_16x16x32_bf16 v[80:83], v[174:177], v[206:209], v[80:83]
	v_mfma_f32_16x16x32_bf16 v[64:67], v[174:177], v[214:217], v[64:67]
	v_mfma_f32_16x16x32_bf16 v[68:71], v[166:169], v[214:217], v[68:71]
	s_setprio 0
	s_barrier
; #define PG8_STAGE(bufoff, gbase, V0, V1) do { \
;         __builtin_amdgcn_global_load_lds((const unsigned*)((const char*)(gbase) + (V0)), (LAS unsigned*)(lds + (bufoff) + ldsw), 16, 0, 0); \
;         __builtin_amdgcn_global_load_lds((const unsigned*)((const char*)(gbase) + (V1)), (LAS unsigned*)(lds + (bufoff) + ldsw + 8192), 16, 0, 0); } while (0)
; #define PG8_LDA(dst, b, h) do { _Pragma("unroll") for (int m = 0; m < 4; ++m) _Pragma("unroll") for (int k = 0; k < 2; ++k) dst[m][k] = *(const LAS bf16x8*)(lds + PG8_SA(b, h) + aoff + m * 2048 + k * 1024); } while (0)
; #define PG8_MMA(ai, bj, At, Bt) do { __builtin_amdgcn_s_setprio(1); _Pragma("unroll") for (int m = 0; m < 4; ++m) _Pragma("unroll") for (int n = 0; n < 2; ++n) _Pragma("unroll") for (int k = 0; k < 2; ++k) \
;         acc[ai][bj][m][n] = __builtin_amdgcn_mfma_f32_16x16x32_bf16(Bt[n][k], At[m][k], acc[ai][bj][m][n], 0, 0, 0); __builtin_amdgcn_s_setprio(0); } while (0)
; #define PG8_WAIT_V(n) asm volatile("s_waitcnt vmcnt(" #n ")" ::: "memory")
; #define PG8_WAIT_L(n) asm volatile("s_waitcnt lgkmcnt(" #n ")" ::: "memory")
; #define PG8_BAR __builtin_amdgcn_s_barrier()
; #define PG8_SCHED __builtin_amdgcn_sched_barrier(0)
; template <class Epi, class Sched>
; DI void gemm_phase(LAS unsigned char* lds, const int lda2, const int ldb2, const int nt, const Sched& S, const Epi& E) {
;     ...
;             PG8_LDA(At, 1, 1); PG8_STAGE(PG8_SB(1, 0), b3, vB0, vB1); PG8_STAGE(PG8_SB(1, 1), b3 + hstepB, vB0, vB1); PG8_STAGE(PG8_SA(1, 0), a3, vA0, vA1);
;             PG8_WAIT_V(8); PG8_WAIT_L(0); PG8_BAR; PG8_MMA(1, 0, At, B0); PG8_MMA(1, 1, At, B1); PG8_BAR; PG8_SCHED;
;         }
;         if (wr == 0) PG8_BAR;
	s_add_i32 s30, s56, s73
	v_lshl_add_u64 v[144:145], v[144:145], 0, s[86:87]
	s_mov_b32 m0, s30
	ds_read_b128 v[178:181], v149 offset:49152
	ds_read_b128 v[182:185], v149 offset:50176
	ds_read_b128 v[186:189], v149 offset:51200
	ds_read_b128 v[190:193], v149 offset:52224
	ds_read_b128 v[202:205], v149 offset:53248
	ds_read_b128 v[206:209], v149 offset:54272
	ds_read_b128 v[210:213], v149 offset:55296
	ds_read_b128 v[214:217], v149 offset:56320
	global_load_lds_dwordx4 v[144:145], off
	s_add_i32 m0, s30, 0x2000
	s_add_u32 s28, s28, 0x40080
	v_lshl_add_u64 v[144:145], v[194:195], 0, s[86:87]
	s_addc_u32 s29, s29, 0
	s_add_i32 s30, s57, s73
	global_load_lds_dwordx4 v[144:145], off
	v_lshl_add_u64 v[144:145], s[28:29], 0, v[96:97]
	s_mov_b32 m0, s30
	s_nop 0
	global_load_lds_dwordx4 v[144:145], off
	v_lshl_add_u64 v[144:145], s[28:29], 0, v[130:131]
	s_add_i32 m0, s30, 0x2000
	s_nop 0
	global_load_lds_dwordx4 v[144:145], off
	v_lshl_add_u64 v[144:145], v[218:219], 0, s[86:87]
	s_mov_b32 m0, s81
	s_nop 0
	global_load_lds_dwordx4 v[144:145], off
	v_lshl_add_u64 v[144:145], v[220:221], 0, s[86:87]
	s_mov_b32 m0, s82
	s_nop 0
	global_load_lds_dwordx4 v[144:145], off
	s_waitcnt vmcnt(8)
	s_waitcnt lgkmcnt(0)
	s_barrier
	s_setprio 1
	s_waitcnt lgkmcnt(0)
	v_mfma_f32_16x16x32_bf16 v[60:63], v[140:143], v[178:181], v[60:63]
	v_mfma_f32_16x16x32_bf16 v[56:59], v[154:157], v[178:181], v[56:59]
	v_mfma_f32_16x16x32_bf16 v[40:43], v[154:157], v[186:189], v[40:43]
	v_mfma_f32_16x16x32_bf16 v[44:47], v[140:143], v[186:189], v[44:47]
	v_mfma_f32_16x16x32_bf16 v[28:31], v[140:143], v[202:205], v[28:31]
	v_mfma_f32_16x16x32_bf16 v[24:27], v[154:157], v[202:205], v[24:27]
	v_mfma_f32_16x16x32_bf16 v[8:11], v[154:157], v[210:213], v[8:11]
	v_mfma_f32_16x16x32_bf16 v[12:15], v[140:143], v[210:213], v[12:15]
	v_mfma_f32_16x16x32_bf16 v[60:63], v[150:153], v[182:185], v[60:63]
	v_mfma_f32_16x16x32_bf16 v[56:59], v[158:161], v[182:185], v[56:59]
	v_mfma_f32_16x16x32_bf16 v[40:43], v[158:161], v[190:193], v[40:43]
	v_mfma_f32_16x16x32_bf16 v[44:47], v[150:153], v[190:193], v[44:47]
	v_mfma_f32_16x16x32_bf16 v[28:31], v[150:153], v[206:209], v[28:31]
	v_mfma_f32_16x16x32_bf16 v[24:27], v[158:161], v[206:209], v[24:27]
	v_mfma_f32_16x16x32_bf16 v[8:11], v[158:161], v[214:217], v[8:11]
	v_mfma_f32_16x16x32_bf16 v[12:15], v[150:153], v[214:217], v[12:15]
	s_setprio 0
	s_setprio 1
	v_mfma_f32_16x16x32_bf16 v[52:55], v[162:165], v[178:181], v[52:55]
	v_mfma_f32_16x16x32_bf16 v[48:51], v[170:173], v[178:181], v[48:51]
	v_mfma_f32_16x16x32_bf16 v[32:35], v[170:173], v[186:189], v[32:35]
	v_mfma_f32_16x16x32_bf16 v[36:39], v[162:165], v[186:189], v[36:39]
	v_mfma_f32_16x16x32_bf16 v[20:23], v[162:165], v[202:205], v[20:23]
	v_mfma_f32_16x16x32_bf16 v[16:19], v[170:173], v[202:205], v[16:19]
	v_mfma_f32_16x16x32_bf16 v[0:3], v[170:173], v[210:213], v[0:3]
	v_mfma_f32_16x16x32_bf16 v[4:7], v[162:165], v[210:213], v[4:7]
	v_mfma_f32_16x16x32_bf16 v[52:55], v[166:169], v[182:185], v[52:55]
	v_mfma_f32_16x16x32_bf16 v[48:51], v[174:177], v[182:185], v[48:51]
	v_mfma_f32_16x16x32_bf16 v[32:35], v[174:177], v[190:193], v[32:35]
	v_mfma_f32_16x16x32_bf16 v[36:39], v[166:169], v[190:193], v[36:39]
	v_mfma_f32_16x16x32_bf16 v[20:23], v[166:169], v[206:209], v[20:23]
	v_mfma_f32_16x16x32_bf16 v[16:19], v[174:177], v[206:209], v[16:19]
	v_mfma_f32_16x16x32_bf16 v[0:3], v[174:177], v[214:217], v[0:3]
	v_mfma_f32_16x16x32_bf16 v[4:7], v[166:169], v[214:217], v[4:7]
	s_setprio 0
	s_barrier
	s_add_i32 s21, s21, 2
	s_add_u32 s26, s26, 0x100
	s_addc_u32 s27, s27, 0
	s_add_u32 s1, s1, 0x100
	s_addc_u32 s10, s10, 0
	s_cmp_gt_u32 s21, 13
	s_cbranch_scc0 .LBB0_906
	s_and_b64 vcc, exec, s[18:19]
	s_cbranch_vccz .LBB0_909
	s_barrier

; #define PG8_STAGE(bufoff, gbase, V0, V1) do { \
;         __builtin_amdgcn_global_load_lds((const unsigned*)((const char*)(gbase) + (V0)), (LAS unsigned*)(lds + (bufoff) + ldsw), 16, 0, 0); \
;         __builtin_amdgcn_global_load_lds((const unsigned*)((const char*)(gbase) + (V1)), (LAS unsigned*)(lds + (bufoff) + ldsw + 8192), 16, 0, 0); } while (0)
; #define PG8_LDA(dst, b, h) do { _Pragma("unroll") for (int m = 0; m < 4; ++m) _Pragma("unroll") for (int k = 0; k < 2; ++k) dst[m][k] = *(const LAS bf16x8*)(lds + PG8_SA(b, h) + aoff + m * 2048 + k * 1024); } while (0)
; #define PG8_LDB(dst, b, h) do { _Pragma("unroll") for (int n = 0; n < 2; ++n) _Pragma("unroll") for (int k = 0; k < 2; ++k) dst[n][k] = *(const LAS bf16x8*)(lds + PG8_SB(b, h) + boff + n * 2048 + k * 1024); } while (0)
; #define PG8_WAIT_V(n) asm volatile("s_waitcnt vmcnt(" #n ")" ::: "memory")
; template <class Epi, class Sched>
; DI void gemm_phase(LAS unsigned char* lds, const int lda2, const int ldb2, const int nt, const Sched& S, const Epi& E) {
;     ...
;     f32x4 acc[2][2][4][2];
; #pragma unroll
;     for (int a = 0; a < 2; ++a)
; #pragma unroll
;         for (int b = 0; b < 2; ++b)
; #pragma unroll
;             for (int m = 0; m < 4; ++m)
; #pragma unroll
;                 for (int n = 0; n < 2; ++n) acc[a][b][m][n] = (f32x4){0.f, 0.f, 0.f, 0.f};
;     ...
;     for (;;) {
;         const bool has_next = S.next(ui + 1, nxt);
;         const char* nA = has_next ? nxt.A : cA; const char* nB = has_next ? nxt.B : cB;
;         for (int t = 0; t < nt; t += 2) {
;             const bool last = (t == nt - 2);
;             const char* a1 = cA + (size_t)(t + 1) * kstep;
;             const char* a2 = last ? nA : cA + (size_t)(t + 2) * kstep; const char* b2 = last ? nB : cB + (size_t)(t + 2) * kstep;
;             const char* a3 = a2 + kstep; const char* b3 = b2 + kstep;
;             PG8_LDB(B0, 0, 0); PG8_LDB(B1, 0, 1); PG8_SCHED; PG8_LDA(At, 0, 0); PG8_STAGE(PG8_SA(1, 1), a1 + hstepA, vA0, vA1);
;             PG8_WAIT_V(8); PG8_WAIT_L(0); PG8_BAR; PG8_MMA(0, 0, At, B0); PG8_MMA(0, 1, At, B1); PG8_BAR; PG8_SCHED;
;             PG8_LDA(At, 0, 1); PG8_STAGE(PG8_SB(0, 0), b2, vB0, vB1); PG8_STAGE(PG8_SB(0, 1), b2 + hstepB, vB0, vB1); PG8_STAGE(PG8_SA(0, 0), a2, vA0, vA1);
;             PG8_WAIT_V(8); PG8_WAIT_L(0); PG8_BAR; PG8_MMA(1, 0, At, B0); PG8_MMA(1, 1, At, B1); PG8_BAR; PG8_SCHED;
.LBB0_1052:
	s_add_u32 s28, s28, 0x40080
	s_addc_u32 s29, s29, 0
	s_add_u32 s19, s30, 0x100
	s_addc_u32 s21, s31, 0
	s_mov_b32 s27, -2
	s_add_u32 s30, s28, 0xfffc0080
	s_addc_u32 s31, s29, -1
	s_add_i32 s50, 0, 0x10000
	s_cmp_eq_u32 s27, 12
	s_cselect_b32 s53, s23, s31
	s_cselect_b32 s52, s22, s30
	v_add_u32_e32 v140, s50, v144
	s_cselect_b32 s31, s25, s21
	s_cselect_b32 s30, s24, s19
	s_add_i32 s56, 0, 0x14000
	ds_read_b128 v[146:149], v140
	ds_read_b128 v[150:153], v140 offset:1024
	ds_read_b128 v[154:157], v140 offset:2048
	ds_read_b128 v[158:161], v140 offset:3072
	v_add_u32_e32 v140, s56, v144
	ds_read_b128 v[162:165], v140
	ds_read_b128 v[166:169], v140 offset:1024
	ds_read_b128 v[170:173], v140 offset:2048
	ds_read_b128 v[174:177], v140 offset:3072
	v_lshl_add_u64 v[140:141], s[28:29], 0, v[136:137]
	s_add_i32 m0, s79, 0xc000
	ds_read_b128 v[178:181], v145
	ds_read_b128 v[182:185], v145 offset:1024
	ds_read_b128 v[186:189], v145 offset:2048
	ds_read_b128 v[190:193], v145 offset:3072
	ds_read_b128 v[202:205], v145 offset:4096
	ds_read_b128 v[206:209], v145 offset:5120
	ds_read_b128 v[210:213], v145 offset:6144
	ds_read_b128 v[214:217], v145 offset:7168
	global_load_lds_dwordx4 v[140:141], off
	v_lshl_add_u64 v[140:141], s[28:29], 0, v[138:139]
	s_add_i32 m0, s79, 0xe000
	s_nop 0
	global_load_lds_dwordx4 v[140:141], off
	s_waitcnt vmcnt(8)
	s_waitcnt lgkmcnt(0)
	s_barrier
	s_setprio 1
	s_waitcnt lgkmcnt(0)
	v_mfma_f32_16x16x32_bf16 v[126:129], v[146:149], v[178:181], 0
	v_mfma_f32_16x16x32_bf16 v[118:121], v[154:157], v[178:181], 0
	v_mfma_f32_16x16x32_bf16 v[102:105], v[154:157], v[186:189], 0
	v_mfma_f32_16x16x32_bf16 v[110:113], v[146:149], v[186:189], 0
	v_mfma_f32_16x16x32_bf16 v[92:95], v[146:149], v[202:205], 0
	v_mfma_f32_16x16x32_bf16 v[84:87], v[154:157], v[202:205], 0
	v_mfma_f32_16x16x32_bf16 v[68:71], v[154:157], v[210:213], 0
	v_mfma_f32_16x16x32_bf16 v[76:79], v[146:149], v[210:213], 0
	v_mfma_f32_16x16x32_bf16 v[126:129], v[150:153], v[182:185], v[126:129]
	v_mfma_f32_16x16x32_bf16 v[118:121], v[158:161], v[182:185], v[118:121]
	v_mfma_f32_16x16x32_bf16 v[102:105], v[158:161], v[190:193], v[102:105]
	v_mfma_f32_16x16x32_bf16 v[110:113], v[150:153], v[190:193], v[110:113]
	v_mfma_f32_16x16x32_bf16 v[92:95], v[150:153], v[206:209], v[92:95]
	v_mfma_f32_16x16x32_bf16 v[84:87], v[158:161], v[206:209], v[84:87]
	v_mfma_f32_16x16x32_bf16 v[68:71], v[158:161], v[214:217], v[68:71]
	v_mfma_f32_16x16x32_bf16 v[76:79], v[150:153], v[214:217], v[76:79]
	s_setprio 0
	s_setprio 1
	v_mfma_f32_16x16x32_bf16 v[122:125], v[162:165], v[178:181], 0
	v_mfma_f32_16x16x32_bf16 v[114:117], v[170:173], v[178:181], 0
	v_mfma_f32_16x16x32_bf16 v[98:101], v[170:173], v[186:189], 0
	v_mfma_f32_16x16x32_bf16 v[106:109], v[162:165], v[186:189], 0
	v_mfma_f32_16x16x32_bf16 v[88:91], v[162:165], v[202:205], 0
	v_mfma_f32_16x16x32_bf16 v[80:83], v[170:173], v[202:205], 0
	v_mfma_f32_16x16x32_bf16 v[64:67], v[170:173], v[210:213], 0
	v_mfma_f32_16x16x32_bf16 v[72:75], v[162:165], v[210:213], 0
	v_mfma_f32_16x16x32_bf16 v[122:125], v[166:169], v[182:185], v[122:125]
	v_mfma_f32_16x16x32_bf16 v[114:117], v[174:177], v[182:185], v[114:117]
	v_mfma_f32_16x16x32_bf16 v[98:101], v[174:177], v[190:193], v[98:101]
	v_mfma_f32_16x16x32_bf16 v[106:109], v[166:169], v[190:193], v[106:109]
	v_mfma_f32_16x16x32_bf16 v[88:91], v[166:169], v[206:209], v[88:91]
	v_mfma_f32_16x16x32_bf16 v[80:83], v[174:177], v[206:209], v[80:83]
	v_mfma_f32_16x16x32_bf16 v[64:67], v[174:177], v[214:217], v[64:67]
	v_mfma_f32_16x16x32_bf16 v[72:75], v[166:169], v[214:217], v[72:75]
	s_setprio 0
	s_barrier
	s_add_i32 s50, s50, s75
	v_lshl_add_u64 v[140:141], s[30:31], 0, v[96:97]
	s_mov_b32 m0, s50
	ds_read_b128 v[178:181], v145 offset:16384
	ds_read_b128 v[182:185], v145 offset:17408
	ds_read_b128 v[186:189], v145 offset:18432
	ds_read_b128 v[190:193], v145 offset:19456
	ds_read_b128 v[202:205], v145 offset:20480
	ds_read_b128 v[206:209], v145 offset:21504
	ds_read_b128 v[210:213], v145 offset:22528
	ds_read_b128 v[214:217], v145 offset:23552
	global_load_lds_dwordx4 v[140:141], off
	s_add_i32 m0, s50, 0x2000
	s_add_u32 s50, s30, 0x40000
	v_lshl_add_u64 v[194:195], s[30:31], 0, v[130:131]
	s_addc_u32 s51, s31, 0
	s_add_i32 s56, s56, s75
	global_load_lds_dwordx4 v[194:195], off
	v_lshl_add_u64 v[218:219], s[50:51], 0, v[96:97]
	s_mov_b32 m0, s56
	v_lshl_add_u64 v[220:221], s[52:53], 0, v[134:135]
	global_load_lds_dwordx4 v[218:219], off
	v_lshl_add_u64 v[218:219], s[50:51], 0, v[130:131]
	s_add_i32 m0, s56, 0x2000
	s_nop 0
	global_load_lds_dwordx4 v[218:219], off
	v_lshl_add_u64 v[218:219], s[52:53], 0, v[132:133]
	s_mov_b32 m0, s79
	s_nop 0
	global_load_lds_dwordx4 v[218:219], off
	s_mov_b32 m0, s80
	s_nop 0
	global_load_lds_dwordx4 v[220:221], off
	s_waitcnt vmcnt(8)
	s_waitcnt lgkmcnt(0)
	s_barrier
; #define PG8_STAGE(bufoff, gbase, V0, V1) do { \
;         __builtin_amdgcn_global_load_lds((const unsigned*)((const char*)(gbase) + (V0)), (LAS unsigned*)(lds + (bufoff) + ldsw), 16, 0, 0); \
;         __builtin_amdgcn_global_load_lds((const unsigned*)((const char*)(gbase) + (V1)), (LAS unsigned*)(lds + (bufoff) + ldsw + 8192), 16, 0, 0); } while (0)
; #define PG8_LDA(dst, b, h) do { _Pragma("unroll") for (int m = 0; m < 4; ++m) _Pragma("unroll") for (int k = 0; k < 2; ++k) dst[m][k] = *(const LAS bf16x8*)(lds + PG8_SA(b, h) + aoff + m * 2048 + k * 1024); } while (0)
; #define PG8_LDB(dst, b, h) do { _Pragma("unroll") for (int n = 0; n < 2; ++n) _Pragma("unroll") for (int k = 0; k < 2; ++k) dst[n][k] = *(const LAS bf16x8*)(lds + PG8_SB(b, h) + boff + n * 2048 + k * 1024); } while (0)
; #define PG8_MMA(ai, bj, At, Bt) do { __builtin_amdgcn_s_setprio(1); _Pragma("unroll") for (int m = 0; m < 4; ++m) _Pragma("unroll") for (int n = 0; n < 2; ++n) _Pragma("unroll") for (int k = 0; k < 2; ++k) \
;         acc[ai][bj][m][n] = __builtin_amdgcn_mfma_f32_16x16x32_bf16(Bt[n][k], At[m][k], acc[ai][bj][m][n], 0, 0, 0); __builtin_amdgcn_s_setprio(0); } while (0)
; #define PG8_WAIT_V(n) asm volatile("s_waitcnt vmcnt(" #n ")" ::: "memory")
; #define PG8_WAIT_L(n) asm volatile("s_waitcnt lgkmcnt(" #n ")" ::: "memory")
; #define PG8_BAR __builtin_amdgcn_s_barrier()
; #define PG8_SCHED __builtin_amdgcn_sched_barrier(0)
; template <class Epi, class Sched>
; DI void gemm_phase(LAS unsigned char* lds, const int lda2, const int ldb2, const int nt, const Sched& S, const Epi& E) {
;     ...
;             PG8_WAIT_V(8); PG8_WAIT_L(0); PG8_BAR; PG8_MMA(0, 0, At, B0); PG8_MMA(0, 1, At, B1); PG8_BAR; PG8_SCHED;
;             PG8_LDA(At, 0, 1); PG8_STAGE(PG8_SB(0, 0), b2, vB0, vB1); PG8_STAGE(PG8_SB(0, 1), b2 + hstepB, vB0, vB1); PG8_STAGE(PG8_SA(0, 0), a2, vA0, vA1);
;             PG8_WAIT_V(8); PG8_WAIT_L(0); PG8_BAR; PG8_MMA(1, 0, At, B0); PG8_MMA(1, 1, At, B1); PG8_BAR; PG8_SCHED;
;             PG8_LDB(B0, 1, 0); PG8_LDB(B1, 1, 1); PG8_SCHED; PG8_LDA(At, 1, 0); PG8_STAGE(PG8_SA(0, 1), a2 + hstepA, vA0, vA1);
;             PG8_WAIT_V(8); PG8_WAIT_L(0); PG8_BAR; PG8_MMA(0, 0, At, B0); PG8_MMA(0, 1, At, B1); PG8_BAR; PG8_SCHED;
	s_setprio 1
	s_waitcnt lgkmcnt(0)
	v_mfma_f32_16x16x32_bf16 v[60:63], v[146:149], v[178:181], 0
	v_mfma_f32_16x16x32_bf16 v[52:55], v[154:157], v[178:181], 0
	v_mfma_f32_16x16x32_bf16 v[36:39], v[154:157], v[186:189], 0
	v_mfma_f32_16x16x32_bf16 v[44:47], v[146:149], v[186:189], 0
	v_mfma_f32_16x16x32_bf16 v[28:31], v[146:149], v[202:205], 0
	v_mfma_f32_16x16x32_bf16 v[20:23], v[154:157], v[202:205], 0
	v_mfma_f32_16x16x32_bf16 v[4:7], v[154:157], v[210:213], 0
	v_mfma_f32_16x16x32_bf16 v[12:15], v[146:149], v[210:213], 0
	v_mfma_f32_16x16x32_bf16 v[60:63], v[150:153], v[182:185], v[60:63]
	v_mfma_f32_16x16x32_bf16 v[52:55], v[158:161], v[182:185], v[52:55]
	v_mfma_f32_16x16x32_bf16 v[36:39], v[158:161], v[190:193], v[36:39]
	v_mfma_f32_16x16x32_bf16 v[44:47], v[150:153], v[190:193], v[44:47]
	v_mfma_f32_16x16x32_bf16 v[28:31], v[150:153], v[206:209], v[28:31]
	v_mfma_f32_16x16x32_bf16 v[20:23], v[158:161], v[206:209], v[20:23]
	v_mfma_f32_16x16x32_bf16 v[4:7], v[158:161], v[214:217], v[4:7]
	v_mfma_f32_16x16x32_bf16 v[12:15], v[150:153], v[214:217], v[12:15]
	s_setprio 0
	s_setprio 1
	v_mfma_f32_16x16x32_bf16 v[56:59], v[162:165], v[178:181], 0
	v_mfma_f32_16x16x32_bf16 v[48:51], v[170:173], v[178:181], 0
	v_mfma_f32_16x16x32_bf16 v[32:35], v[170:173], v[186:189], 0
	v_mfma_f32_16x16x32_bf16 v[40:43], v[162:165], v[186:189], 0
	v_mfma_f32_16x16x32_bf16 v[24:27], v[162:165], v[202:205], 0
	v_mfma_f32_16x16x32_bf16 v[16:19], v[170:173], v[202:205], 0
	v_mfma_f32_16x16x32_bf16 v[0:3], v[170:173], v[210:213], 0
	v_mfma_f32_16x16x32_bf16 v[8:11], v[162:165], v[210:213], 0
	v_mfma_f32_16x16x32_bf16 v[56:59], v[166:169], v[182:185], v[56:59]
	v_mfma_f32_16x16x32_bf16 v[48:51], v[174:177], v[182:185], v[48:51]
	v_mfma_f32_16x16x32_bf16 v[32:35], v[174:177], v[190:193], v[32:35]
	v_mfma_f32_16x16x32_bf16 v[40:43], v[166:169], v[190:193], v[40:43]
	v_mfma_f32_16x16x32_bf16 v[24:27], v[166:169], v[206:209], v[24:27]
	v_mfma_f32_16x16x32_bf16 v[16:19], v[174:177], v[206:209], v[16:19]
	v_mfma_f32_16x16x32_bf16 v[0:3], v[174:177], v[214:217], v[0:3]
	v_mfma_f32_16x16x32_bf16 v[8:11], v[166:169], v[214:217], v[8:11]
	s_setprio 0
	s_barrier
	s_add_i32 s56, 0, 0x18000
	s_add_i32 s57, 0, 0x1c000
	v_add_u32_e32 v158, s56, v144
	v_add_u32_e32 v174, s57, v144
	ds_read_b128 v[146:149], v158
	ds_read_b128 v[150:153], v158 offset:1024
	ds_read_b128 v[154:157], v158 offset:2048
	ds_read_b128 v[158:161], v158 offset:3072
	ds_read_b128 v[162:165], v174
	ds_read_b128 v[166:169], v174 offset:1024
	ds_read_b128 v[170:173], v174 offset:2048
	ds_read_b128 v[174:177], v174 offset:3072
	s_add_u32 s50, s52, 0x40000
	s_addc_u32 s51, s53, 0
	s_mov_b32 m0, s81
	v_lshl_add_u64 v[222:223], s[50:51], 0, v[132:133]
	ds_read_b128 v[178:181], v145 offset:32768
	ds_read_b128 v[182:185], v145 offset:33792
	ds_read_b128 v[186:189], v145 offset:34816
	ds_read_b128 v[190:193], v145 offset:35840
	ds_read_b128 v[202:205], v145 offset:36864
	ds_read_b128 v[206:209], v145 offset:37888
	ds_read_b128 v[210:213], v145 offset:38912
	ds_read_b128 v[214:217], v145 offset:39936
	global_load_lds_dwordx4 v[222:223], off
	v_lshl_add_u64 v[222:223], s[50:51], 0, v[134:135]
	s_mov_b32 m0, s82
	s_nop 0
	global_load_lds_dwordx4 v[222:223], off
	s_waitcnt vmcnt(8)
	s_waitcnt lgkmcnt(0)
	s_barrier
	s_setprio 1
	s_waitcnt lgkmcnt(0)
	v_mfma_f32_16x16x32_bf16 v[126:129], v[146:149], v[178:181], v[126:129]
	v_mfma_f32_16x16x32_bf16 v[118:121], v[154:157], v[178:181], v[118:121]
	v_mfma_f32_16x16x32_bf16 v[102:105], v[154:157], v[186:189], v[102:105]
	v_mfma_f32_16x16x32_bf16 v[110:113], v[146:149], v[186:189], v[110:113]
	v_mfma_f32_16x16x32_bf16 v[92:95], v[146:149], v[202:205], v[92:95]
	v_mfma_f32_16x16x32_bf16 v[84:87], v[154:157], v[202:205], v[84:87]
	v_mfma_f32_16x16x32_bf16 v[68:71], v[154:157], v[210:213], v[68:71]
	v_mfma_f32_16x16x32_bf16 v[76:79], v[146:149], v[210:213], v[76:79]
	v_mfma_f32_16x16x32_bf16 v[126:129], v[150:153], v[182:185], v[126:129]
	v_mfma_f32_16x16x32_bf16 v[118:121], v[158:161], v[182:185], v[118:121]
	v_mfma_f32_16x16x32_bf16 v[102:105], v[158:161], v[190:193], v[102:105]
	v_mfma_f32_16x16x32_bf16 v[110:113], v[150:153], v[190:193], v[110:113]
	v_mfma_f32_16x16x32_bf16 v[92:95], v[150:153], v[206:209], v[92:95]
	v_mfma_f32_16x16x32_bf16 v[84:87], v[158:161], v[206:209], v[84:87]
	v_mfma_f32_16x16x32_bf16 v[68:71], v[158:161], v[214:217], v[68:71]
	v_mfma_f32_16x16x32_bf16 v[76:79], v[150:153], v[214:217], v[76:79]
	s_setprio 0
	s_setprio 1
	v_mfma_f32_16x16x32_bf16 v[122:125], v[162:165], v[178:181], v[122:125]
	v_mfma_f32_16x16x32_bf16 v[114:117], v[170:173], v[178:181], v[114:117]
	v_mfma_f32_16x16x32_bf16 v[98:101], v[170:173], v[186:189], v[98:101]
	v_mfma_f32_16x16x32_bf16 v[106:109], v[162:165], v[186:189], v[106:109]
	v_mfma_f32_16x16x32_bf16 v[88:91], v[162:165], v[202:205], v[88:91]
	v_mfma_f32_16x16x32_bf16 v[80:83], v[170:173], v[202:205], v[80:83]
	v_mfma_f32_16x16x32_bf16 v[64:67], v[170:173], v[210:213], v[64:67]
	v_mfma_f32_16x16x32_bf16 v[72:75], v[162:165], v[210:213], v[72:75]
	v_mfma_f32_16x16x32_bf16 v[122:125], v[166:169], v[182:185], v[122:125]
	v_mfma_f32_16x16x32_bf16 v[114:117], v[174:177], v[182:185], v[114:117]
	v_mfma_f32_16x16x32_bf16 v[98:101], v[174:177], v[190:193], v[98:101]
	v_mfma_f32_16x16x32_bf16 v[106:109], v[166:169], v[190:193], v[106:109]
	v_mfma_f32_16x16x32_bf16 v[88:91], v[166:169], v[206:209], v[88:91]
	v_mfma_f32_16x16x32_bf16 v[80:83], v[174:177], v[206:209], v[80:83]
	v_mfma_f32_16x16x32_bf16 v[64:67], v[174:177], v[214:217], v[64:67]
	v_mfma_f32_16x16x32_bf16 v[72:75], v[166:169], v[214:217], v[72:75]
	s_setprio 0
	s_barrier
; #define PG8_STAGE(bufoff, gbase, V0, V1) do { \
;         __builtin_amdgcn_global_load_lds((const unsigned*)((const char*)(gbase) + (V0)), (LAS unsigned*)(lds + (bufoff) + ldsw), 16, 0, 0); \
;         __builtin_amdgcn_global_load_lds((const unsigned*)((const char*)(gbase) + (V1)), (LAS unsigned*)(lds + (bufoff) + ldsw + 8192), 16, 0, 0); } while (0)
; #define PG8_LDA(dst, b, h) do { _Pragma("unroll") for (int m = 0; m < 4; ++m) _Pragma("unroll") for (int k = 0; k < 2; ++k) dst[m][k] = *(const LAS bf16x8*)(lds + PG8_SA(b, h) + aoff + m * 2048 + k * 1024); } while (0)
; #define PG8_LDB(dst, b, h) do { _Pragma("unroll") for (int n = 0; n < 2; ++n) _Pragma("unroll") for (int k = 0; k < 2; ++k) dst[n][k] = *(const LAS bf16x8*)(lds + PG8_SB(b, h) + boff + n * 2048 + k * 1024); } while (0)
; #define PG8_WAIT_V(n) asm volatile("s_waitcnt vmcnt(" #n ")" ::: "memory")
; #define PG8_WAIT_L(n) asm volatile("s_waitcnt lgkmcnt(" #n ")" ::: "memory")
; #define PG8_BAR __builtin_amdgcn_s_barrier()
; #define PG8_SCHED __builtin_amdgcn_sched_barrier(0)
; template <class Epi, class Sched>
; DI void gemm_phase(LAS unsigned char* lds, const int lda2, const int ldb2, const int nt, const Sched& S, const Epi& E) {
;     ...
;         for (int t = 0; t < nt; t += 2) {
;             const bool last = (t == nt - 2);
;             const char* a1 = cA + (size_t)(t + 1) * kstep;
;             const char* a2 = last ? nA : cA + (size_t)(t + 2) * kstep; const char* b2 = last ? nB : cB + (size_t)(t + 2) * kstep;
;             const char* a3 = a2 + kstep; const char* b3 = b2 + kstep;
;             PG8_LDB(B0, 0, 0); PG8_LDB(B1, 0, 1); PG8_SCHED; PG8_LDA(At, 0, 0); PG8_STAGE(PG8_SA(1, 1), a1 + hstepA, vA0, vA1);
;             PG8_WAIT_V(8); PG8_WAIT_L(0); PG8_BAR; PG8_MMA(0, 0, At, B0); PG8_MMA(0, 1, At, B1); PG8_BAR; PG8_SCHED;
;     ...
;             PG8_LDB(B0, 1, 0); PG8_LDB(B1, 1, 1); PG8_SCHED; PG8_LDA(At, 1, 0); PG8_STAGE(PG8_SA(0, 1), a2 + hstepA, vA0, vA1);
;             PG8_WAIT_V(8); PG8_WAIT_L(0); PG8_BAR; PG8_MMA(0, 0, At, B0); PG8_MMA(0, 1, At, B1); PG8_BAR; PG8_SCHED;
;             PG8_LDA(At, 1, 1); PG8_STAGE(PG8_SB(1, 0), b3, vB0, vB1); PG8_STAGE(PG8_SB(1, 1), b3 + hstepB, vB0, vB1); PG8_STAGE(PG8_SA(1, 0), a3, vA0, vA1);
;             PG8_WAIT_V(8); PG8_WAIT_L(0); PG8_BAR; PG8_MMA(1, 0, At, B0); PG8_MMA(1, 1, At, B1); PG8_BAR; PG8_SCHED;
	s_add_i32 s50, s56, s75
	v_lshl_add_u64 v[140:141], v[140:141], 0, s[86:87]
	s_mov_b32 m0, s50
	ds_read_b128 v[178:181], v145 offset:49152
	ds_read_b128 v[182:185], v145 offset:50176
	ds_read_b128 v[186:189], v145 offset:51200
	ds_read_b128 v[190:193], v145 offset:52224
	ds_read_b128 v[202:205], v145 offset:53248
	ds_read_b128 v[206:209], v145 offset:54272
	ds_read_b128 v[210:213], v145 offset:55296
	ds_read_b128 v[214:217], v145 offset:56320
	global_load_lds_dwordx4 v[140:141], off
	s_add_i32 m0, s50, 0x2000
	s_add_u32 s30, s30, 0x40080
	v_lshl_add_u64 v[140:141], v[194:195], 0, s[86:87]
	s_addc_u32 s31, s31, 0
	s_add_i32 s50, s57, s75
	global_load_lds_dwordx4 v[140:141], off
	v_lshl_add_u64 v[140:141], s[30:31], 0, v[96:97]
	s_mov_b32 m0, s50
	s_nop 0
	global_load_lds_dwordx4 v[140:141], off
	v_lshl_add_u64 v[140:141], s[30:31], 0, v[130:131]
	s_add_i32 m0, s50, 0x2000
	s_nop 0
	global_load_lds_dwordx4 v[140:141], off
	v_lshl_add_u64 v[140:141], v[218:219], 0, s[86:87]
	s_mov_b32 m0, s85
	s_nop 0
	global_load_lds_dwordx4 v[140:141], off
	v_lshl_add_u64 v[140:141], v[220:221], 0, s[86:87]
	s_mov_b32 m0, s14
	s_nop 0
	global_load_lds_dwordx4 v[140:141], off
	s_waitcnt vmcnt(8)
	s_waitcnt lgkmcnt(0)
	s_barrier
	s_setprio 1
	s_waitcnt lgkmcnt(0)
	v_mfma_f32_16x16x32_bf16 v[60:63], v[146:149], v[178:181], v[60:63]
	v_mfma_f32_16x16x32_bf16 v[52:55], v[154:157], v[178:181], v[52:55]
	v_mfma_f32_16x16x32_bf16 v[36:39], v[154:157], v[186:189], v[36:39]
	v_mfma_f32_16x16x32_bf16 v[44:47], v[146:149], v[186:189], v[44:47]
	v_mfma_f32_16x16x32_bf16 v[28:31], v[146:149], v[202:205], v[28:31]
	v_mfma_f32_16x16x32_bf16 v[20:23], v[154:157], v[202:205], v[20:23]
	v_mfma_f32_16x16x32_bf16 v[4:7], v[154:157], v[210:213], v[4:7]
	v_mfma_f32_16x16x32_bf16 v[12:15], v[146:149], v[210:213], v[12:15]
	v_mfma_f32_16x16x32_bf16 v[60:63], v[150:153], v[182:185], v[60:63]
	v_mfma_f32_16x16x32_bf16 v[52:55], v[158:161], v[182:185], v[52:55]
	v_mfma_f32_16x16x32_bf16 v[36:39], v[158:161], v[190:193], v[36:39]
	v_mfma_f32_16x16x32_bf16 v[44:47], v[150:153], v[190:193], v[44:47]
	v_mfma_f32_16x16x32_bf16 v[28:31], v[150:153], v[206:209], v[28:31]
	v_mfma_f32_16x16x32_bf16 v[20:23], v[158:161], v[206:209], v[20:23]
	v_mfma_f32_16x16x32_bf16 v[4:7], v[158:161], v[214:217], v[4:7]
	v_mfma_f32_16x16x32_bf16 v[12:15], v[150:153], v[214:217], v[12:15]
	s_setprio 0
	s_setprio 1
	v_mfma_f32_16x16x32_bf16 v[56:59], v[162:165], v[178:181], v[56:59]
	v_mfma_f32_16x16x32_bf16 v[48:51], v[170:173], v[178:181], v[48:51]
	v_mfma_f32_16x16x32_bf16 v[32:35], v[170:173], v[186:189], v[32:35]
	v_mfma_f32_16x16x32_bf16 v[40:43], v[162:165], v[186:189], v[40:43]
	v_mfma_f32_16x16x32_bf16 v[24:27], v[162:165], v[202:205], v[24:27]
	v_mfma_f32_16x16x32_bf16 v[16:19], v[170:173], v[202:205], v[16:19]
	v_mfma_f32_16x16x32_bf16 v[0:3], v[170:173], v[210:213], v[0:3]
	v_mfma_f32_16x16x32_bf16 v[8:11], v[162:165], v[210:213], v[8:11]
	v_mfma_f32_16x16x32_bf16 v[56:59], v[166:169], v[182:185], v[56:59]
	v_mfma_f32_16x16x32_bf16 v[48:51], v[174:177], v[182:185], v[48:51]
	v_mfma_f32_16x16x32_bf16 v[32:35], v[174:177], v[190:193], v[32:35]
	v_mfma_f32_16x16x32_bf16 v[40:43], v[166:169], v[190:193], v[40:43]
	v_mfma_f32_16x16x32_bf16 v[24:27], v[166:169], v[206:209], v[24:27]
	v_mfma_f32_16x16x32_bf16 v[16:19], v[174:177], v[206:209], v[16:19]
	v_mfma_f32_16x16x32_bf16 v[0:3], v[174:177], v[214:217], v[0:3]
	v_mfma_f32_16x16x32_bf16 v[8:11], v[166:169], v[214:217], v[8:11]
	s_setprio 0
	s_barrier
	s_add_i32 s27, s27, 2
	s_add_u32 s28, s28, 0x100
	s_addc_u32 s29, s29, 0
	s_add_u32 s19, s19, 0x100
	s_addc_u32 s21, s21, 0
.LBB0_1053:
	s_add_u32 s30, s28, 0xfffc0080
	s_addc_u32 s31, s29, -1
	s_add_i32 s50, 0, 0x10000
	s_cmp_eq_u32 s27, 12
	s_cselect_b32 s53, s23, s31
	s_cselect_b32 s52, s22, s30
	v_add_u32_e32 v140, s50, v144
	s_cselect_b32 s31, s25, s21
	s_cselect_b32 s30, s24, s19
	s_add_i32 s56, 0, 0x14000
	ds_read_b128 v[146:149], v140
	ds_read_b128 v[150:153], v140 offset:1024
	ds_read_b128 v[154:157], v140 offset:2048
	ds_read_b128 v[158:161], v140 offset:3072
	v_add_u32_e32 v140, s56, v144
	ds_read_b128 v[162:165], v140
	ds_read_b128 v[166:169], v140 offset:1024
	ds_read_b128 v[170:173], v140 offset:2048
	ds_read_b128 v[174:177], v140 offset:3072
	v_lshl_add_u64 v[140:141], s[28:29], 0, v[136:137]
	s_add_i32 m0, s79, 0xc000
	ds_read_b128 v[178:181], v145
	ds_read_b128 v[182:185], v145 offset:1024
	ds_read_b128 v[186:189], v145 offset:2048
	ds_read_b128 v[190:193], v145 offset:3072
	ds_read_b128 v[202:205], v145 offset:4096
	ds_read_b128 v[206:209], v145 offset:5120
	ds_read_b128 v[210:213], v145 offset:6144
	ds_read_b128 v[214:217], v145 offset:7168
	global_load_lds_dwordx4 v[140:141], off
	v_lshl_add_u64 v[140:141], s[28:29], 0, v[138:139]
	s_add_i32 m0, s79, 0xe000
	s_nop 0
	global_load_lds_dwordx4 v[140:141], off
	s_waitcnt vmcnt(8)
	s_waitcnt lgkmcnt(0)
	s_barrier
; #define PG8_STAGE(bufoff, gbase, V0, V1) do { \
;         __builtin_amdgcn_global_load_lds((const unsigned*)((const char*)(gbase) + (V0)), (LAS unsigned*)(lds + (bufoff) + ldsw), 16, 0, 0); \
;         __builtin_amdgcn_global_load_lds((const unsigned*)((const char*)(gbase) + (V1)), (LAS unsigned*)(lds + (bufoff) + ldsw + 8192), 16, 0, 0); } while (0)
; #define PG8_LDA(dst, b, h) do { _Pragma("unroll") for (int m = 0; m < 4; ++m) _Pragma("unroll") for (int k = 0; k < 2; ++k) dst[m][k] = *(const LAS bf16x8*)(lds + PG8_SA(b, h) + aoff + m * 2048 + k * 1024); } while (0)
; #define PG8_LDB(dst, b, h) do { _Pragma("unroll") for (int n = 0; n < 2; ++n) _Pragma("unroll") for (int k = 0; k < 2; ++k) dst[n][k] = *(const LAS bf16x8*)(lds + PG8_SB(b, h) + boff + n * 2048 + k * 1024); } while (0)
; #define PG8_MMA(ai, bj, At, Bt) do { __builtin_amdgcn_s_setprio(1); _Pragma("unroll") for (int m = 0; m < 4; ++m) _Pragma("unroll") for (int n = 0; n < 2; ++n) _Pragma("unroll") for (int k = 0; k < 2; ++k) \
;         acc[ai][bj][m][n] = __builtin_amdgcn_mfma_f32_16x16x32_bf16(Bt[n][k], At[m][k], acc[ai][bj][m][n], 0, 0, 0); __builtin_amdgcn_s_setprio(0); } while (0)
; #define PG8_WAIT_V(n) asm volatile("s_waitcnt vmcnt(" #n ")" ::: "memory")
; #define PG8_WAIT_L(n) asm volatile("s_waitcnt lgkmcnt(" #n ")" ::: "memory")
; #define PG8_BAR __builtin_amdgcn_s_barrier()
; #define PG8_SCHED __builtin_amdgcn_sched_barrier(0)
; template <class Epi, class Sched>
; DI void gemm_phase(LAS unsigned char* lds, const int lda2, const int ldb2, const int nt, const Sched& S, const Epi& E) {
;     ...
;             PG8_WAIT_V(8); PG8_WAIT_L(0); PG8_BAR; PG8_MMA(0, 0, At, B0); PG8_MMA(0, 1, At, B1); PG8_BAR; PG8_SCHED;
;             PG8_LDA(At, 0, 1); PG8_STAGE(PG8_SB(0, 0), b2, vB0, vB1); PG8_STAGE(PG8_SB(0, 1), b2 + hstepB, vB0, vB1); PG8_STAGE(PG8_SA(0, 0), a2, vA0, vA1);
;             PG8_WAIT_V(8); PG8_WAIT_L(0); PG8_BAR; PG8_MMA(1, 0, At, B0); PG8_MMA(1, 1, At, B1); PG8_BAR; PG8_SCHED;
;             PG8_LDB(B0, 1, 0); PG8_LDB(B1, 1, 1); PG8_SCHED; PG8_LDA(At, 1, 0); PG8_STAGE(PG8_SA(0, 1), a2 + hstepA, vA0, vA1);
;             PG8_WAIT_V(8); PG8_WAIT_L(0); PG8_BAR; PG8_MMA(0, 0, At, B0); PG8_MMA(0, 1, At, B1); PG8_BAR; PG8_SCHED;
	s_setprio 1
	s_waitcnt lgkmcnt(0)
	v_mfma_f32_16x16x32_bf16 v[126:129], v[146:149], v[178:181], v[126:129]
	v_mfma_f32_16x16x32_bf16 v[118:121], v[154:157], v[178:181], v[118:121]
	v_mfma_f32_16x16x32_bf16 v[102:105], v[154:157], v[186:189], v[102:105]
	v_mfma_f32_16x16x32_bf16 v[110:113], v[146:149], v[186:189], v[110:113]
	v_mfma_f32_16x16x32_bf16 v[92:95], v[146:149], v[202:205], v[92:95]
	v_mfma_f32_16x16x32_bf16 v[84:87], v[154:157], v[202:205], v[84:87]
	v_mfma_f32_16x16x32_bf16 v[68:71], v[154:157], v[210:213], v[68:71]
	v_mfma_f32_16x16x32_bf16 v[76:79], v[146:149], v[210:213], v[76:79]
	v_mfma_f32_16x16x32_bf16 v[126:129], v[150:153], v[182:185], v[126:129]
	v_mfma_f32_16x16x32_bf16 v[118:121], v[158:161], v[182:185], v[118:121]
	v_mfma_f32_16x16x32_bf16 v[102:105], v[158:161], v[190:193], v[102:105]
	v_mfma_f32_16x16x32_bf16 v[110:113], v[150:153], v[190:193], v[110:113]
	v_mfma_f32_16x16x32_bf16 v[92:95], v[150:153], v[206:209], v[92:95]
	v_mfma_f32_16x16x32_bf16 v[84:87], v[158:161], v[206:209], v[84:87]
	v_mfma_f32_16x16x32_bf16 v[68:71], v[158:161], v[214:217], v[68:71]
	v_mfma_f32_16x16x32_bf16 v[76:79], v[150:153], v[214:217], v[76:79]
	s_setprio 0
	s_setprio 1
	v_mfma_f32_16x16x32_bf16 v[122:125], v[162:165], v[178:181], v[122:125]
	v_mfma_f32_16x16x32_bf16 v[114:117], v[170:173], v[178:181], v[114:117]
	v_mfma_f32_16x16x32_bf16 v[98:101], v[170:173], v[186:189], v[98:101]
	v_mfma_f32_16x16x32_bf16 v[106:109], v[162:165], v[186:189], v[106:109]
	v_mfma_f32_16x16x32_bf16 v[88:91], v[162:165], v[202:205], v[88:91]
	v_mfma_f32_16x16x32_bf16 v[80:83], v[170:173], v[202:205], v[80:83]
	v_mfma_f32_16x16x32_bf16 v[64:67], v[170:173], v[210:213], v[64:67]
	v_mfma_f32_16x16x32_bf16 v[72:75], v[162:165], v[210:213], v[72:75]
	v_mfma_f32_16x16x32_bf16 v[122:125], v[166:169], v[182:185], v[122:125]
	v_mfma_f32_16x16x32_bf16 v[114:117], v[174:177], v[182:185], v[114:117]
	v_mfma_f32_16x16x32_bf16 v[98:101], v[174:177], v[190:193], v[98:101]
	v_mfma_f32_16x16x32_bf16 v[106:109], v[166:169], v[190:193], v[106:109]
	v_mfma_f32_16x16x32_bf16 v[88:91], v[166:169], v[206:209], v[88:91]
	v_mfma_f32_16x16x32_bf16 v[80:83], v[174:177], v[206:209], v[80:83]
	v_mfma_f32_16x16x32_bf16 v[64:67], v[174:177], v[214:217], v[64:67]
	v_mfma_f32_16x16x32_bf16 v[72:75], v[166:169], v[214:217], v[72:75]
	s_setprio 0
	s_barrier
	s_add_i32 s50, s50, s75
	v_lshl_add_u64 v[140:141], s[30:31], 0, v[96:97]
	s_mov_b32 m0, s50
	ds_read_b128 v[178:181], v145 offset:16384
	ds_read_b128 v[182:185], v145 offset:17408
	ds_read_b128 v[186:189], v145 offset:18432
	ds_read_b128 v[190:193], v145 offset:19456
	ds_read_b128 v[202:205], v145 offset:20480
	ds_read_b128 v[206:209], v145 offset:21504
	ds_read_b128 v[210:213], v145 offset:22528
	ds_read_b128 v[214:217], v145 offset:23552
	global_load_lds_dwordx4 v[140:141], off
	s_add_i32 m0, s50, 0x2000
	s_add_u32 s50, s30, 0x40000
	v_lshl_add_u64 v[194:195], s[30:31], 0, v[130:131]
	s_addc_u32 s51, s31, 0
	s_add_i32 s56, s56, s75
	global_load_lds_dwordx4 v[194:195], off
	v_lshl_add_u64 v[218:219], s[50:51], 0, v[96:97]
	s_mov_b32 m0, s56
	v_lshl_add_u64 v[220:221], s[52:53], 0, v[134:135]
	global_load_lds_dwordx4 v[218:219], off
	v_lshl_add_u64 v[218:219], s[50:51], 0, v[130:131]
	s_add_i32 m0, s56, 0x2000
	s_nop 0
	global_load_lds_dwordx4 v[218:219], off
	v_lshl_add_u64 v[218:219], s[52:53], 0, v[132:133]
	s_mov_b32 m0, s79
	s_nop 0
	global_load_lds_dwordx4 v[218:219], off
	s_mov_b32 m0, s80
	s_nop 0
	global_load_lds_dwordx4 v[220:221], off
	s_waitcnt vmcnt(8)
	s_waitcnt lgkmcnt(0)
	s_barrier
	s_setprio 1
	s_waitcnt lgkmcnt(0)
	v_mfma_f32_16x16x32_bf16 v[60:63], v[146:149], v[178:181], v[60:63]
	v_mfma_f32_16x16x32_bf16 v[52:55], v[154:157], v[178:181], v[52:55]
	v_mfma_f32_16x16x32_bf16 v[36:39], v[154:157], v[186:189], v[36:39]
	v_mfma_f32_16x16x32_bf16 v[44:47], v[146:149], v[186:189], v[44:47]
	v_mfma_f32_16x16x32_bf16 v[28:31], v[146:149], v[202:205], v[28:31]
	v_mfma_f32_16x16x32_bf16 v[20:23], v[154:157], v[202:205], v[20:23]
	v_mfma_f32_16x16x32_bf16 v[4:7], v[154:157], v[210:213], v[4:7]
	v_mfma_f32_16x16x32_bf16 v[12:15], v[146:149], v[210:213], v[12:15]
	v_mfma_f32_16x16x32_bf16 v[60:63], v[150:153], v[182:185], v[60:63]
	v_mfma_f32_16x16x32_bf16 v[52:55], v[158:161], v[182:185], v[52:55]
	v_mfma_f32_16x16x32_bf16 v[36:39], v[158:161], v[190:193], v[36:39]
	v_mfma_f32_16x16x32_bf16 v[44:47], v[150:153], v[190:193], v[44:47]
	v_mfma_f32_16x16x32_bf16 v[28:31], v[150:153], v[206:209], v[28:31]
	v_mfma_f32_16x16x32_bf16 v[20:23], v[158:161], v[206:209], v[20:23]
	v_mfma_f32_16x16x32_bf16 v[4:7], v[158:161], v[214:217], v[4:7]
	v_mfma_f32_16x16x32_bf16 v[12:15], v[150:153], v[214:217], v[12:15]
	s_setprio 0
	s_setprio 1
	v_mfma_f32_16x16x32_bf16 v[56:59], v[162:165], v[178:181], v[56:59]
	v_mfma_f32_16x16x32_bf16 v[48:51], v[170:173], v[178:181], v[48:51]
	v_mfma_f32_16x16x32_bf16 v[32:35], v[170:173], v[186:189], v[32:35]
	v_mfma_f32_16x16x32_bf16 v[40:43], v[162:165], v[186:189], v[40:43]
	v_mfma_f32_16x16x32_bf16 v[24:27], v[162:165], v[202:205], v[24:27]
	v_mfma_f32_16x16x32_bf16 v[16:19], v[170:173], v[202:205], v[16:19]
	v_mfma_f32_16x16x32_bf16 v[0:3], v[170:173], v[210:213], v[0:3]
	v_mfma_f32_16x16x32_bf16 v[8:11], v[162:165], v[210:213], v[8:11]
	v_mfma_f32_16x16x32_bf16 v[56:59], v[166:169], v[182:185], v[56:59]
	v_mfma_f32_16x16x32_bf16 v[48:51], v[174:177], v[182:185], v[48:51]
	v_mfma_f32_16x16x32_bf16 v[32:35], v[174:177], v[190:193], v[32:35]
	v_mfma_f32_16x16x32_bf16 v[40:43], v[166:169], v[190:193], v[40:43]
	v_mfma_f32_16x16x32_bf16 v[24:27], v[166:169], v[206:209], v[24:27]
	v_mfma_f32_16x16x32_bf16 v[16:19], v[174:177], v[206:209], v[16:19]
	v_mfma_f32_16x16x32_bf16 v[0:3], v[174:177], v[214:217], v[0:3]
	v_mfma_f32_16x16x32_bf16 v[8:11], v[166:169], v[214:217], v[8:11]
	s_setprio 0
	s_barrier
; #define PG8_STAGE(bufoff, gbase, V0, V1) do { \
;         __builtin_amdgcn_global_load_lds((const unsigned*)((const char*)(gbase) + (V0)), (LAS unsigned*)(lds + (bufoff) + ldsw), 16, 0, 0); \
;         __builtin_amdgcn_global_load_lds((const unsigned*)((const char*)(gbase) + (V1)), (LAS unsigned*)(lds + (bufoff) + ldsw + 8192), 16, 0, 0); } while (0)
; #define PG8_LDA(dst, b, h) do { _Pragma("unroll") for (int m = 0; m < 4; ++m) _Pragma("unroll") for (int k = 0; k < 2; ++k) dst[m][k] = *(const LAS bf16x8*)(lds + PG8_SA(b, h) + aoff + m * 2048 + k * 1024); } while (0)
; #define PG8_LDB(dst, b, h) do { _Pragma("unroll") for (int n = 0; n < 2; ++n) _Pragma("unroll") for (int k = 0; k < 2; ++k) dst[n][k] = *(const LAS bf16x8*)(lds + PG8_SB(b, h) + boff + n * 2048 + k * 1024); } while (0)
; #define PG8_MMA(ai, bj, At, Bt) do { __builtin_amdgcn_s_setprio(1); _Pragma("unroll") for (int m = 0; m < 4; ++m) _Pragma("unroll") for (int n = 0; n < 2; ++n) _Pragma("unroll") for (int k = 0; k < 2; ++k) \
;         acc[ai][bj][m][n] = __builtin_amdgcn_mfma_f32_16x16x32_bf16(Bt[n][k], At[m][k], acc[ai][bj][m][n], 0, 0, 0); __builtin_amdgcn_s_setprio(0); } while (0)
; #define PG8_WAIT_V(n) asm volatile("s_waitcnt vmcnt(" #n ")" ::: "memory")
; #define PG8_WAIT_L(n) asm volatile("s_waitcnt lgkmcnt(" #n ")" ::: "memory")
; #define PG8_BAR __builtin_amdgcn_s_barrier()
; #define PG8_SCHED __builtin_amdgcn_sched_barrier(0)
; template <class Epi, class Sched>
; DI void gemm_phase(LAS unsigned char* lds, const int lda2, const int ldb2, const int nt, const Sched& S, const Epi& E) {
;     ...
;             PG8_LDB(B0, 1, 0); PG8_LDB(B1, 1, 1); PG8_SCHED; PG8_LDA(At, 1, 0); PG8_STAGE(PG8_SA(0, 1), a2 + hstepA, vA0, vA1);
;             PG8_WAIT_V(8); PG8_WAIT_L(0); PG8_BAR; PG8_MMA(0, 0, At, B0); PG8_MMA(0, 1, At, B1); PG8_BAR; PG8_SCHED;
	s_add_i32 s56, 0, 0x18000
	s_add_i32 s57, 0, 0x1c000
	v_add_u32_e32 v158, s56, v144
	v_add_u32_e32 v174, s57, v144
	ds_read_b128 v[146:149], v158
	ds_read_b128 v[150:153], v158 offset:1024
	ds_read_b128 v[154:157], v158 offset:2048
	ds_read_b128 v[158:161], v158 offset:3072
	ds_read_b128 v[162:165], v174
	ds_read_b128 v[166:169], v174 offset:1024
	ds_read_b128 v[170:173], v174 offset:2048
	ds_read_b128 v[174:177], v174 offset:3072
	s_add_u32 s50, s52, 0x40000
	s_addc_u32 s51, s53, 0
	s_mov_b32 m0, s81
	v_lshl_add_u64 v[222:223], s[50:51], 0, v[132:133]
	ds_read_b128 v[178:181], v145 offset:32768
	ds_read_b128 v[182:185], v145 offset:33792
	ds_read_b128 v[186:189], v145 offset:34816
	ds_read_b128 v[190:193], v145 offset:35840
	ds_read_b128 v[202:205], v145 offset:36864
	ds_read_b128 v[206:209], v145 offset:37888
	ds_read_b128 v[210:213], v145 offset:38912
	ds_read_b128 v[214:217], v145 offset:39936
	global_load_lds_dwordx4 v[222:223], off
	v_lshl_add_u64 v[222:223], s[50:51], 0, v[134:135]
	s_mov_b32 m0, s82
	s_nop 0
	global_load_lds_dwordx4 v[222:223], off
	s_waitcnt vmcnt(8)
	s_waitcnt lgkmcnt(0)
	s_barrier
	s_setprio 1
	s_waitcnt lgkmcnt(0)
	v_mfma_f32_16x16x32_bf16 v[126:129], v[146:149], v[178:181], v[126:129]
	v_mfma_f32_16x16x32_bf16 v[118:121], v[154:157], v[178:181], v[118:121]
	v_mfma_f32_16x16x32_bf16 v[102:105], v[154:157], v[186:189], v[102:105]
	v_mfma_f32_16x16x32_bf16 v[110:113], v[146:149], v[186:189], v[110:113]
	v_mfma_f32_16x16x32_bf16 v[92:95], v[146:149], v[202:205], v[92:95]
	v_mfma_f32_16x16x32_bf16 v[84:87], v[154:157], v[202:205], v[84:87]
	v_mfma_f32_16x16x32_bf16 v[68:71], v[154:157], v[210:213], v[68:71]
	v_mfma_f32_16x16x32_bf16 v[76:79], v[146:149], v[210:213], v[76:79]
	v_mfma_f32_16x16x32_bf16 v[126:129], v[150:153], v[182:185], v[126:129]
	v_mfma_f32_16x16x32_bf16 v[118:121], v[158:161], v[182:185], v[118:121]
	v_mfma_f32_16x16x32_bf16 v[102:105], v[158:161], v[190:193], v[102:105]
	v_mfma_f32_16x16x32_bf16 v[110:113], v[150:153], v[190:193], v[110:113]
	v_mfma_f32_16x16x32_bf16 v[92:95], v[150:153], v[206:209], v[92:95]
	v_mfma_f32_16x16x32_bf16 v[84:87], v[158:161], v[206:209], v[84:87]
	v_mfma_f32_16x16x32_bf16 v[68:71], v[158:161], v[214:217], v[68:71]
	v_mfma_f32_16x16x32_bf16 v[76:79], v[150:153], v[214:217], v[76:79]
	s_setprio 0
	s_setprio 1
	v_mfma_f32_16x16x32_bf16 v[122:125], v[162:165], v[178:181], v[122:125]
	v_mfma_f32_16x16x32_bf16 v[114:117], v[170:173], v[178:181], v[114:117]
	v_mfma_f32_16x16x32_bf16 v[98:101], v[170:173], v[186:189], v[98:101]
	v_mfma_f32_16x16x32_bf16 v[106:109], v[162:165], v[186:189], v[106:109]
	v_mfma_f32_16x16x32_bf16 v[88:91], v[162:165], v[202:205], v[88:91]
	v_mfma_f32_16x16x32_bf16 v[80:83], v[170:173], v[202:205], v[80:83]
	v_mfma_f32_16x16x32_bf16 v[64:67], v[170:173], v[210:213], v[64:67]
	v_mfma_f32_16x16x32_bf16 v[72:75], v[162:165], v[210:213], v[72:75]
	v_mfma_f32_16x16x32_bf16 v[122:125], v[166:169], v[182:185], v[122:125]
	v_mfma_f32_16x16x32_bf16 v[114:117], v[174:177], v[182:185], v[114:117]
	v_mfma_f32_16x16x32_bf16 v[98:101], v[174:177], v[190:193], v[98:101]
	v_mfma_f32_16x16x32_bf16 v[106:109], v[166:169], v[190:193], v[106:109]
	v_mfma_f32_16x16x32_bf16 v[88:91], v[166:169], v[206:209], v[88:91]
	v_mfma_f32_16x16x32_bf16 v[80:83], v[174:177], v[206:209], v[80:83]
	v_mfma_f32_16x16x32_bf16 v[64:67], v[174:177], v[214:217], v[64:67]
	v_mfma_f32_16x16x32_bf16 v[72:75], v[166:169], v[214:217], v[72:75]
	s_setprio 0
	s_barrier
; #define PG8_STAGE(bufoff, gbase, V0, V1) do { \
;         __builtin_amdgcn_global_load_lds((const unsigned*)((const char*)(gbase) + (V0)), (LAS unsigned*)(lds + (bufoff) + ldsw), 16, 0, 0); \
;         __builtin_amdgcn_global_load_lds((const unsigned*)((const char*)(gbase) + (V1)), (LAS unsigned*)(lds + (bufoff) + ldsw + 8192), 16, 0, 0); } while (0)
; #define PG8_LDA(dst, b, h) do { _Pragma("unroll") for (int m = 0; m < 4; ++m) _Pragma("unroll") for (int k = 0; k < 2; ++k) dst[m][k] = *(const LAS bf16x8*)(lds + PG8_SA(b, h) + aoff + m * 2048 + k * 1024); } while (0)
; #define PG8_MMA(ai, bj, At, Bt) do { __builtin_amdgcn_s_setprio(1); _Pragma("unroll") for (int m = 0; m < 4; ++m) _Pragma("unroll") for (int n = 0; n < 2; ++n) _Pragma("unroll") for (int k = 0; k < 2; ++k) \
;         acc[ai][bj][m][n] = __builtin_amdgcn_mfma_f32_16x16x32_bf16(Bt[n][k], At[m][k], acc[ai][bj][m][n], 0, 0, 0); __builtin_amdgcn_s_setprio(0); } while (0)
; #define PG8_WAIT_V(n) asm volatile("s_waitcnt vmcnt(" #n ")" ::: "memory")
; #define PG8_WAIT_L(n) asm volatile("s_waitcnt lgkmcnt(" #n ")" ::: "memory")
; #define PG8_BAR __builtin_amdgcn_s_barrier()
; #define PG8_SCHED __builtin_amdgcn_sched_barrier(0)
; template <class Epi, class Sched>
; DI void gemm_phase(LAS unsigned char* lds, const int lda2, const int ldb2, const int nt, const Sched& S, const Epi& E) {
;     ...
;             PG8_LDA(At, 1, 1); PG8_STAGE(PG8_SB(1, 0), b3, vB0, vB1); PG8_STAGE(PG8_SB(1, 1), b3 + hstepB, vB0, vB1); PG8_STAGE(PG8_SA(1, 0), a3, vA0, vA1);
;             PG8_WAIT_V(8); PG8_WAIT_L(0); PG8_BAR; PG8_MMA(1, 0, At, B0); PG8_MMA(1, 1, At, B1); PG8_BAR; PG8_SCHED;
;         }
;         if (wr == 0) PG8_BAR;
	s_add_i32 s50, s56, s75
	v_lshl_add_u64 v[140:141], v[140:141], 0, s[86:87]
	s_mov_b32 m0, s50
	ds_read_b128 v[178:181], v145 offset:49152
	ds_read_b128 v[182:185], v145 offset:50176
	ds_read_b128 v[186:189], v145 offset:51200
	ds_read_b128 v[190:193], v145 offset:52224
	ds_read_b128 v[202:205], v145 offset:53248
	ds_read_b128 v[206:209], v145 offset:54272
	ds_read_b128 v[210:213], v145 offset:55296
	ds_read_b128 v[214:217], v145 offset:56320
	global_load_lds_dwordx4 v[140:141], off
	s_add_i32 m0, s50, 0x2000
	s_add_u32 s30, s30, 0x40080
	v_lshl_add_u64 v[140:141], v[194:195], 0, s[86:87]
	s_addc_u32 s31, s31, 0
	s_add_i32 s50, s57, s75
	global_load_lds_dwordx4 v[140:141], off
	v_lshl_add_u64 v[140:141], s[30:31], 0, v[96:97]
	s_mov_b32 m0, s50
	s_nop 0
	global_load_lds_dwordx4 v[140:141], off
	v_lshl_add_u64 v[140:141], s[30:31], 0, v[130:131]
	s_add_i32 m0, s50, 0x2000
	s_nop 0
	global_load_lds_dwordx4 v[140:141], off
	v_lshl_add_u64 v[140:141], v[218:219], 0, s[86:87]
	s_mov_b32 m0, s85
	s_nop 0
	global_load_lds_dwordx4 v[140:141], off
	v_lshl_add_u64 v[140:141], v[220:221], 0, s[86:87]
	s_mov_b32 m0, s14
	s_nop 0
	global_load_lds_dwordx4 v[140:141], off
	s_waitcnt vmcnt(8)
	s_waitcnt lgkmcnt(0)
	s_barrier
	s_setprio 1
	s_waitcnt lgkmcnt(0)
	v_mfma_f32_16x16x32_bf16 v[60:63], v[146:149], v[178:181], v[60:63]
	v_mfma_f32_16x16x32_bf16 v[52:55], v[154:157], v[178:181], v[52:55]
	v_mfma_f32_16x16x32_bf16 v[36:39], v[154:157], v[186:189], v[36:39]
	v_mfma_f32_16x16x32_bf16 v[44:47], v[146:149], v[186:189], v[44:47]
	v_mfma_f32_16x16x32_bf16 v[28:31], v[146:149], v[202:205], v[28:31]
	v_mfma_f32_16x16x32_bf16 v[20:23], v[154:157], v[202:205], v[20:23]
	v_mfma_f32_16x16x32_bf16 v[4:7], v[154:157], v[210:213], v[4:7]
	v_mfma_f32_16x16x32_bf16 v[12:15], v[146:149], v[210:213], v[12:15]
	v_mfma_f32_16x16x32_bf16 v[60:63], v[150:153], v[182:185], v[60:63]
	v_mfma_f32_16x16x32_bf16 v[52:55], v[158:161], v[182:185], v[52:55]
	v_mfma_f32_16x16x32_bf16 v[36:39], v[158:161], v[190:193], v[36:39]
	v_mfma_f32_16x16x32_bf16 v[44:47], v[150:153], v[190:193], v[44:47]
	v_mfma_f32_16x16x32_bf16 v[28:31], v[150:153], v[206:209], v[28:31]
	v_mfma_f32_16x16x32_bf16 v[20:23], v[158:161], v[206:209], v[20:23]
	v_mfma_f32_16x16x32_bf16 v[4:7], v[158:161], v[214:217], v[4:7]
	v_mfma_f32_16x16x32_bf16 v[12:15], v[150:153], v[214:217], v[12:15]
	s_setprio 0
	s_setprio 1
	v_mfma_f32_16x16x32_bf16 v[56:59], v[162:165], v[178:181], v[56:59]
	v_mfma_f32_16x16x32_bf16 v[48:51], v[170:173], v[178:181], v[48:51]
	v_mfma_f32_16x16x32_bf16 v[32:35], v[170:173], v[186:189], v[32:35]
	v_mfma_f32_16x16x32_bf16 v[40:43], v[162:165], v[186:189], v[40:43]
	v_mfma_f32_16x16x32_bf16 v[24:27], v[162:165], v[202:205], v[24:27]
	v_mfma_f32_16x16x32_bf16 v[16:19], v[170:173], v[202:205], v[16:19]
	v_mfma_f32_16x16x32_bf16 v[0:3], v[170:173], v[210:213], v[0:3]
	v_mfma_f32_16x16x32_bf16 v[8:11], v[162:165], v[210:213], v[8:11]
	v_mfma_f32_16x16x32_bf16 v[56:59], v[166:169], v[182:185], v[56:59]
	v_mfma_f32_16x16x32_bf16 v[48:51], v[174:177], v[182:185], v[48:51]
	v_mfma_f32_16x16x32_bf16 v[32:35], v[174:177], v[190:193], v[32:35]
	v_mfma_f32_16x16x32_bf16 v[40:43], v[166:169], v[190:193], v[40:43]
	v_mfma_f32_16x16x32_bf16 v[24:27], v[166:169], v[206:209], v[24:27]
	v_mfma_f32_16x16x32_bf16 v[16:19], v[174:177], v[206:209], v[16:19]
	v_mfma_f32_16x16x32_bf16 v[0:3], v[174:177], v[214:217], v[0:3]
	v_mfma_f32_16x16x32_bf16 v[8:11], v[166:169], v[214:217], v[8:11]
	s_setprio 0
	s_barrier
	s_add_i32 s27, s27, 2
	s_add_u32 s28, s28, 0x100
	s_addc_u32 s29, s29, 0
	s_add_u32 s19, s19, 0x100
	s_addc_u32 s21, s21, 0
	s_cmp_gt_u32 s27, 13
	s_cbranch_scc0 .LBB0_1053
	s_and_b64 vcc, exec, s[16:17]
	s_cbranch_vccz .LBB0_1056
	s_barrier

; #define PG8_STAGE(bufoff, gbase, V0, V1) do { \
;         __builtin_amdgcn_global_load_lds((const unsigned*)((const char*)(gbase) + (V0)), (LAS unsigned*)(lds + (bufoff) + ldsw), 16, 0, 0); \
;         __builtin_amdgcn_global_load_lds((const unsigned*)((const char*)(gbase) + (V1)), (LAS unsigned*)(lds + (bufoff) + ldsw + 8192), 16, 0, 0); } while (0)
; #define PG8_LDA(dst, b, h) do { _Pragma("unroll") for (int m = 0; m < 4; ++m) _Pragma("unroll") for (int k = 0; k < 2; ++k) dst[m][k] = *(const LAS bf16x8*)(lds + PG8_SA(b, h) + aoff + m * 2048 + k * 1024); } while (0)
; #define PG8_LDB(dst, b, h) do { _Pragma("unroll") for (int n = 0; n < 2; ++n) _Pragma("unroll") for (int k = 0; k < 2; ++k) dst[n][k] = *(const LAS bf16x8*)(lds + PG8_SB(b, h) + boff + n * 2048 + k * 1024); } while (0)
; #define PG8_WAIT_V(n) asm volatile("s_waitcnt vmcnt(" #n ")" ::: "memory")
; template <class Epi, class Sched>
; DI void gemm_phase(LAS unsigned char* lds, const int lda2, const int ldb2, const int nt, const Sched& S, const Epi& E) {
;     ...
;     f32x4 acc[2][2][4][2];
; #pragma unroll
;     for (int a = 0; a < 2; ++a)
; #pragma unroll
;         for (int b = 0; b < 2; ++b)
; #pragma unroll
;             for (int m = 0; m < 4; ++m)
; #pragma unroll
;                 for (int n = 0; n < 2; ++n) acc[a][b][m][n] = (f32x4){0.f, 0.f, 0.f, 0.f};
;     ...
;     for (;;) {
;         const bool has_next = S.next(ui + 1, nxt);
;         const char* nA = has_next ? nxt.A : cA; const char* nB = has_next ? nxt.B : cB;
;         for (int t = 0; t < nt; t += 2) {
;             const bool last = (t == nt - 2);
;             const char* a1 = cA + (size_t)(t + 1) * kstep;
;             const char* a2 = last ? nA : cA + (size_t)(t + 2) * kstep; const char* b2 = last ? nB : cB + (size_t)(t + 2) * kstep;
;             const char* a3 = a2 + kstep; const char* b3 = b2 + kstep;
;             PG8_LDB(B0, 0, 0); PG8_LDB(B1, 0, 1); PG8_SCHED; PG8_LDA(At, 0, 0); PG8_STAGE(PG8_SA(1, 1), a1 + hstepA, vA0, vA1);
;             PG8_WAIT_V(8); PG8_WAIT_L(0); PG8_BAR; PG8_MMA(0, 0, At, B0); PG8_MMA(0, 1, At, B1); PG8_BAR; PG8_SCHED;
;             PG8_LDA(At, 0, 1); PG8_STAGE(PG8_SB(0, 0), b2, vB0, vB1); PG8_STAGE(PG8_SB(0, 1), b2 + hstepB, vB0, vB1); PG8_STAGE(PG8_SA(0, 0), a2, vA0, vA1);
;             PG8_WAIT_V(8); PG8_WAIT_L(0); PG8_BAR; PG8_MMA(1, 0, At, B0); PG8_MMA(1, 1, At, B1); PG8_BAR; PG8_SCHED;
.LBB0_1123:
	s_add_u32 s28, s28, 0xb0080
	s_addc_u32 s29, s29, 0
	s_add_u32 s1, s30, 0x100
	s_addc_u32 s10, s31, 0
	s_mov_b32 s57, -2
	s_waitcnt lgkmcnt(0)
	s_add_u32 s30, s28, 0xfff50080
	s_addc_u32 s31, s29, -1
	s_add_i32 vcc_lo, 0, 0x10000
	s_cmp_eq_u32 s57, 40
	s_cselect_b32 s53, s25, s31
	s_cselect_b32 s52, s24, s30
	v_add_u32_e32 v144, vcc_lo, v148
	s_cselect_b32 s31, s27, s10
	s_cselect_b32 s30, s26, s1
	s_add_i32 s58, 0, 0x14000
	ds_read_b128 v[140:143], v144
	ds_read_b128 v[150:153], v144 offset:1024
	ds_read_b128 v[154:157], v144 offset:2048
	ds_read_b128 v[158:161], v144 offset:3072
	v_add_u32_e32 v144, s58, v148
	ds_read_b128 v[162:165], v144
	ds_read_b128 v[166:169], v144 offset:1024
	ds_read_b128 v[170:173], v144 offset:2048
	ds_read_b128 v[174:177], v144 offset:3072
	v_lshl_add_u64 v[144:145], s[28:29], 0, v[136:137]
	s_add_i32 m0, s74, 0xc000
	ds_read_b128 v[178:181], v149
	ds_read_b128 v[182:185], v149 offset:1024
	ds_read_b128 v[186:189], v149 offset:2048
	ds_read_b128 v[190:193], v149 offset:3072
	ds_read_b128 v[202:205], v149 offset:4096
	ds_read_b128 v[206:209], v149 offset:5120
	ds_read_b128 v[210:213], v149 offset:6144
	ds_read_b128 v[214:217], v149 offset:7168
	global_load_lds_dwordx4 v[144:145], off
	v_lshl_add_u64 v[144:145], s[28:29], 0, v[138:139]
	s_add_i32 m0, s74, 0xe000
	s_nop 0
	global_load_lds_dwordx4 v[144:145], off
	s_waitcnt vmcnt(8)
	s_waitcnt lgkmcnt(0)
	s_barrier
	s_setprio 1
	s_waitcnt lgkmcnt(0)
	v_mfma_f32_16x16x32_bf16 v[126:129], v[140:143], v[178:181], 0
	v_mfma_f32_16x16x32_bf16 v[122:125], v[154:157], v[178:181], 0
	v_mfma_f32_16x16x32_bf16 v[106:109], v[154:157], v[186:189], 0
	v_mfma_f32_16x16x32_bf16 v[110:113], v[140:143], v[186:189], 0
	v_mfma_f32_16x16x32_bf16 v[92:95], v[140:143], v[202:205], 0
	v_mfma_f32_16x16x32_bf16 v[88:91], v[154:157], v[202:205], 0
	v_mfma_f32_16x16x32_bf16 v[72:75], v[154:157], v[210:213], 0
	v_mfma_f32_16x16x32_bf16 v[76:79], v[140:143], v[210:213], 0
	v_mfma_f32_16x16x32_bf16 v[126:129], v[150:153], v[182:185], v[126:129]
	v_mfma_f32_16x16x32_bf16 v[122:125], v[158:161], v[182:185], v[122:125]
	v_mfma_f32_16x16x32_bf16 v[106:109], v[158:161], v[190:193], v[106:109]
	v_mfma_f32_16x16x32_bf16 v[110:113], v[150:153], v[190:193], v[110:113]
	v_mfma_f32_16x16x32_bf16 v[92:95], v[150:153], v[206:209], v[92:95]
	v_mfma_f32_16x16x32_bf16 v[88:91], v[158:161], v[206:209], v[88:91]
	v_mfma_f32_16x16x32_bf16 v[72:75], v[158:161], v[214:217], v[72:75]
	v_mfma_f32_16x16x32_bf16 v[76:79], v[150:153], v[214:217], v[76:79]
	s_setprio 0
	s_setprio 1
	v_mfma_f32_16x16x32_bf16 v[118:121], v[162:165], v[178:181], 0
	v_mfma_f32_16x16x32_bf16 v[114:117], v[170:173], v[178:181], 0
	v_mfma_f32_16x16x32_bf16 v[98:101], v[170:173], v[186:189], 0
	v_mfma_f32_16x16x32_bf16 v[102:105], v[162:165], v[186:189], 0
	v_mfma_f32_16x16x32_bf16 v[84:87], v[162:165], v[202:205], 0
	v_mfma_f32_16x16x32_bf16 v[80:83], v[170:173], v[202:205], 0
	v_mfma_f32_16x16x32_bf16 v[64:67], v[170:173], v[210:213], 0
	v_mfma_f32_16x16x32_bf16 v[68:71], v[162:165], v[210:213], 0
	v_mfma_f32_16x16x32_bf16 v[118:121], v[166:169], v[182:185], v[118:121]
	v_mfma_f32_16x16x32_bf16 v[114:117], v[174:177], v[182:185], v[114:117]
	v_mfma_f32_16x16x32_bf16 v[98:101], v[174:177], v[190:193], v[98:101]
	v_mfma_f32_16x16x32_bf16 v[102:105], v[166:169], v[190:193], v[102:105]
	v_mfma_f32_16x16x32_bf16 v[84:87], v[166:169], v[206:209], v[84:87]
	v_mfma_f32_16x16x32_bf16 v[80:83], v[174:177], v[206:209], v[80:83]
	v_mfma_f32_16x16x32_bf16 v[64:67], v[174:177], v[214:217], v[64:67]
	v_mfma_f32_16x16x32_bf16 v[68:71], v[166:169], v[214:217], v[68:71]
	s_setprio 0
	s_barrier
	s_add_i32 s59, vcc_lo, s73
	v_lshl_add_u64 v[144:145], s[30:31], 0, v[96:97]
	s_mov_b32 m0, s59
	ds_read_b128 v[178:181], v149 offset:16384
	ds_read_b128 v[182:185], v149 offset:17408
	ds_read_b128 v[186:189], v149 offset:18432
	ds_read_b128 v[190:193], v149 offset:19456
	ds_read_b128 v[202:205], v149 offset:20480
	ds_read_b128 v[206:209], v149 offset:21504
	ds_read_b128 v[210:213], v149 offset:22528
	ds_read_b128 v[214:217], v149 offset:23552
	global_load_lds_dwordx4 v[144:145], off
	s_add_i32 m0, s59, 0x2000
	s_add_u32 vcc_lo, s30, 0xb0000
	v_lshl_add_u64 v[194:195], s[30:31], 0, v[130:131]
	s_addc_u32 vcc_hi, s31, 0
	s_add_i32 s58, s58, s73
	global_load_lds_dwordx4 v[194:195], off
	v_lshl_add_u64 v[218:219], vcc, 0, v[96:97]
	s_mov_b32 m0, s58
	v_lshl_add_u64 v[220:221], s[52:53], 0, v[134:135]
	global_load_lds_dwordx4 v[218:219], off
	v_lshl_add_u64 v[218:219], vcc, 0, v[130:131]
	s_add_i32 m0, s58, 0x2000
	s_nop 0
	global_load_lds_dwordx4 v[218:219], off
	v_lshl_add_u64 v[218:219], s[52:53], 0, v[132:133]
	s_mov_b32 m0, s74
	s_nop 0
	global_load_lds_dwordx4 v[218:219], off
	s_mov_b32 m0, s75
	s_nop 0
	global_load_lds_dwordx4 v[220:221], off
	s_waitcnt vmcnt(8)
	s_waitcnt lgkmcnt(0)
	s_barrier
; #define PG8_STAGE(bufoff, gbase, V0, V1) do { \
;         __builtin_amdgcn_global_load_lds((const unsigned*)((const char*)(gbase) + (V0)), (LAS unsigned*)(lds + (bufoff) + ldsw), 16, 0, 0); \
;         __builtin_amdgcn_global_load_lds((const unsigned*)((const char*)(gbase) + (V1)), (LAS unsigned*)(lds + (bufoff) + ldsw + 8192), 16, 0, 0); } while (0)
; #define PG8_LDA(dst, b, h) do { _Pragma("unroll") for (int m = 0; m < 4; ++m) _Pragma("unroll") for (int k = 0; k < 2; ++k) dst[m][k] = *(const LAS bf16x8*)(lds + PG8_SA(b, h) + aoff + m * 2048 + k * 1024); } while (0)
; #define PG8_LDB(dst, b, h) do { _Pragma("unroll") for (int n = 0; n < 2; ++n) _Pragma("unroll") for (int k = 0; k < 2; ++k) dst[n][k] = *(const LAS bf16x8*)(lds + PG8_SB(b, h) + boff + n * 2048 + k * 1024); } while (0)
; template <class Epi, class Sched>
; DI void gemm_phase(LAS unsigned char* lds, const int lda2, const int ldb2, const int nt, const Sched& S, const Epi& E) {
;     ...
;         for (int t = 0; t < nt; t += 2) {
;             const bool last = (t == nt - 2);
;             const char* a1 = cA + (size_t)(t + 1) * kstep;
;             const char* a2 = last ? nA : cA + (size_t)(t + 2) * kstep; const char* b2 = last ? nB : cB + (size_t)(t + 2) * kstep;
;             const char* a3 = a2 + kstep; const char* b3 = b2 + kstep;
;             PG8_LDB(B0, 0, 0); PG8_LDB(B1, 0, 1); PG8_SCHED; PG8_LDA(At, 0, 0); PG8_STAGE(PG8_SA(1, 1), a1 + hstepA, vA0, vA1);
;             PG8_WAIT_V(8); PG8_WAIT_L(0); PG8_BAR; PG8_MMA(0, 0, At, B0); PG8_MMA(0, 1, At, B1); PG8_BAR; PG8_SCHED;
;             PG8_LDA(At, 0, 1); PG8_STAGE(PG8_SB(0, 0), b2, vB0, vB1); PG8_STAGE(PG8_SB(0, 1), b2 + hstepB, vB0, vB1); PG8_STAGE(PG8_SA(0, 0), a2, vA0, vA1);
;             PG8_WAIT_V(8); PG8_WAIT_L(0); PG8_BAR; PG8_MMA(1, 0, At, B0); PG8_MMA(1, 1, At, B1); PG8_BAR; PG8_SCHED;
;             PG8_LDB(B0, 1, 0); PG8_LDB(B1, 1, 1); PG8_SCHED; PG8_LDA(At, 1, 0); PG8_STAGE(PG8_SA(0, 1), a2 + hstepA, vA0, vA1);
;             PG8_WAIT_V(8); PG8_WAIT_L(0); PG8_BAR; PG8_MMA(0, 0, At, B0); PG8_MMA(0, 1, At, B1); PG8_BAR; PG8_SCHED;
;             PG8_LDA(At, 1, 1); PG8_STAGE(PG8_SB(1, 0), b3, vB0, vB1); PG8_STAGE(PG8_SB(1, 1), b3 + hstepB, vB0, vB1); PG8_STAGE(PG8_SA(1, 0), a3, vA0, vA1);
;             PG8_WAIT_V(8); PG8_WAIT_L(0); PG8_BAR; PG8_MMA(1, 0, At, B0); PG8_MMA(1, 1, At, B1); PG8_BAR; PG8_SCHED;
	s_setprio 1
	s_waitcnt lgkmcnt(0)
	v_mfma_f32_16x16x32_bf16 v[60:63], v[140:143], v[178:181], 0
	v_mfma_f32_16x16x32_bf16 v[56:59], v[154:157], v[178:181], 0
	v_mfma_f32_16x16x32_bf16 v[40:43], v[154:157], v[186:189], 0
	v_mfma_f32_16x16x32_bf16 v[44:47], v[140:143], v[186:189], 0
	v_mfma_f32_16x16x32_bf16 v[28:31], v[140:143], v[202:205], 0
	v_mfma_f32_16x16x32_bf16 v[24:27], v[154:157], v[202:205], 0
	v_mfma_f32_16x16x32_bf16 v[8:11], v[154:157], v[210:213], 0
	v_mfma_f32_16x16x32_bf16 v[12:15], v[140:143], v[210:213], 0
	v_mfma_f32_16x16x32_bf16 v[60:63], v[150:153], v[182:185], v[60:63]
	v_mfma_f32_16x16x32_bf16 v[56:59], v[158:161], v[182:185], v[56:59]
	v_mfma_f32_16x16x32_bf16 v[40:43], v[158:161], v[190:193], v[40:43]
	v_mfma_f32_16x16x32_bf16 v[44:47], v[150:153], v[190:193], v[44:47]
	v_mfma_f32_16x16x32_bf16 v[28:31], v[150:153], v[206:209], v[28:31]
	v_mfma_f32_16x16x32_bf16 v[24:27], v[158:161], v[206:209], v[24:27]
	v_mfma_f32_16x16x32_bf16 v[8:11], v[158:161], v[214:217], v[8:11]
	v_mfma_f32_16x16x32_bf16 v[12:15], v[150:153], v[214:217], v[12:15]
	s_setprio 0
	s_setprio 1
	v_mfma_f32_16x16x32_bf16 v[52:55], v[162:165], v[178:181], 0
	v_mfma_f32_16x16x32_bf16 v[48:51], v[170:173], v[178:181], 0
	v_mfma_f32_16x16x32_bf16 v[32:35], v[170:173], v[186:189], 0
	v_mfma_f32_16x16x32_bf16 v[36:39], v[162:165], v[186:189], 0
	v_mfma_f32_16x16x32_bf16 v[20:23], v[162:165], v[202:205], 0
	v_mfma_f32_16x16x32_bf16 v[16:19], v[170:173], v[202:205], 0
	v_mfma_f32_16x16x32_bf16 v[0:3], v[170:173], v[210:213], 0
	v_mfma_f32_16x16x32_bf16 v[4:7], v[162:165], v[210:213], 0
	v_mfma_f32_16x16x32_bf16 v[52:55], v[166:169], v[182:185], v[52:55]
	v_mfma_f32_16x16x32_bf16 v[48:51], v[174:177], v[182:185], v[48:51]
	v_mfma_f32_16x16x32_bf16 v[32:35], v[174:177], v[190:193], v[32:35]
	v_mfma_f32_16x16x32_bf16 v[36:39], v[166:169], v[190:193], v[36:39]
	v_mfma_f32_16x16x32_bf16 v[20:23], v[166:169], v[206:209], v[20:23]
	v_mfma_f32_16x16x32_bf16 v[16:19], v[174:177], v[206:209], v[16:19]
	v_mfma_f32_16x16x32_bf16 v[0:3], v[174:177], v[214:217], v[0:3]
	v_mfma_f32_16x16x32_bf16 v[4:7], v[166:169], v[214:217], v[4:7]
	s_setprio 0
	s_barrier
	s_add_i32 s58, 0, 0x18000
	s_add_i32 s59, 0, 0x1c000
	v_add_u32_e32 v158, s58, v148
	v_add_u32_e32 v174, s59, v148
	ds_read_b128 v[140:143], v158
	ds_read_b128 v[150:153], v158 offset:1024
	ds_read_b128 v[154:157], v158 offset:2048
	ds_read_b128 v[158:161], v158 offset:3072
	ds_read_b128 v[162:165], v174
	ds_read_b128 v[166:169], v174 offset:1024
	ds_read_b128 v[170:173], v174 offset:2048
	ds_read_b128 v[174:177], v174 offset:3072
	s_add_u32 s52, s52, 0xb0000
	s_addc_u32 s53, s53, 0
	s_mov_b32 m0, s76
	v_lshl_add_u64 v[222:223], s[52:53], 0, v[132:133]
	ds_read_b128 v[178:181], v149 offset:32768
	ds_read_b128 v[182:185], v149 offset:33792
	ds_read_b128 v[186:189], v149 offset:34816
	ds_read_b128 v[190:193], v149 offset:35840
	ds_read_b128 v[202:205], v149 offset:36864
	ds_read_b128 v[206:209], v149 offset:37888
	ds_read_b128 v[210:213], v149 offset:38912
	ds_read_b128 v[214:217], v149 offset:39936
	global_load_lds_dwordx4 v[222:223], off
	v_lshl_add_u64 v[222:223], s[52:53], 0, v[134:135]
	s_mov_b32 m0, s77
	s_nop 0
	global_load_lds_dwordx4 v[222:223], off
	s_waitcnt vmcnt(8)
	s_waitcnt lgkmcnt(0)
	s_barrier
	s_setprio 1
	s_waitcnt lgkmcnt(0)
	v_mfma_f32_16x16x32_bf16 v[126:129], v[140:143], v[178:181], v[126:129]
	v_mfma_f32_16x16x32_bf16 v[122:125], v[154:157], v[178:181], v[122:125]
	v_mfma_f32_16x16x32_bf16 v[106:109], v[154:157], v[186:189], v[106:109]
	v_mfma_f32_16x16x32_bf16 v[110:113], v[140:143], v[186:189], v[110:113]
	v_mfma_f32_16x16x32_bf16 v[92:95], v[140:143], v[202:205], v[92:95]
	v_mfma_f32_16x16x32_bf16 v[88:91], v[154:157], v[202:205], v[88:91]
	v_mfma_f32_16x16x32_bf16 v[72:75], v[154:157], v[210:213], v[72:75]
	v_mfma_f32_16x16x32_bf16 v[76:79], v[140:143], v[210:213], v[76:79]
	v_mfma_f32_16x16x32_bf16 v[126:129], v[150:153], v[182:185], v[126:129]
	v_mfma_f32_16x16x32_bf16 v[122:125], v[158:161], v[182:185], v[122:125]
	v_mfma_f32_16x16x32_bf16 v[106:109], v[158:161], v[190:193], v[106:109]
	v_mfma_f32_16x16x32_bf16 v[110:113], v[150:153], v[190:193], v[110:113]
	v_mfma_f32_16x16x32_bf16 v[92:95], v[150:153], v[206:209], v[92:95]
	v_mfma_f32_16x16x32_bf16 v[88:91], v[158:161], v[206:209], v[88:91]
	v_mfma_f32_16x16x32_bf16 v[72:75], v[158:161], v[214:217], v[72:75]
	v_mfma_f32_16x16x32_bf16 v[76:79], v[150:153], v[214:217], v[76:79]
	s_setprio 0
	s_setprio 1
	v_mfma_f32_16x16x32_bf16 v[118:121], v[162:165], v[178:181], v[118:121]
	v_mfma_f32_16x16x32_bf16 v[114:117], v[170:173], v[178:181], v[114:117]
	v_mfma_f32_16x16x32_bf16 v[98:101], v[170:173], v[186:189], v[98:101]
	v_mfma_f32_16x16x32_bf16 v[102:105], v[162:165], v[186:189], v[102:105]
	v_mfma_f32_16x16x32_bf16 v[84:87], v[162:165], v[202:205], v[84:87]
	v_mfma_f32_16x16x32_bf16 v[80:83], v[170:173], v[202:205], v[80:83]
	v_mfma_f32_16x16x32_bf16 v[64:67], v[170:173], v[210:213], v[64:67]
	v_mfma_f32_16x16x32_bf16 v[68:71], v[162:165], v[210:213], v[68:71]
	v_mfma_f32_16x16x32_bf16 v[118:121], v[166:169], v[182:185], v[118:121]
	v_mfma_f32_16x16x32_bf16 v[114:117], v[174:177], v[182:185], v[114:117]
	v_mfma_f32_16x16x32_bf16 v[98:101], v[174:177], v[190:193], v[98:101]
	v_mfma_f32_16x16x32_bf16 v[102:105], v[166:169], v[190:193], v[102:105]
	v_mfma_f32_16x16x32_bf16 v[84:87], v[166:169], v[206:209], v[84:87]
	v_mfma_f32_16x16x32_bf16 v[80:83], v[174:177], v[206:209], v[80:83]
	v_mfma_f32_16x16x32_bf16 v[64:67], v[174:177], v[214:217], v[64:67]
	v_mfma_f32_16x16x32_bf16 v[68:71], v[166:169], v[214:217], v[68:71]
	s_setprio 0
	s_barrier
; #define PG8_STAGE(bufoff, gbase, V0, V1) do { \
;         __builtin_amdgcn_global_load_lds((const unsigned*)((const char*)(gbase) + (V0)), (LAS unsigned*)(lds + (bufoff) + ldsw), 16, 0, 0); \
;         __builtin_amdgcn_global_load_lds((const unsigned*)((const char*)(gbase) + (V1)), (LAS unsigned*)(lds + (bufoff) + ldsw + 8192), 16, 0, 0); } while (0)
; #define PG8_LDA(dst, b, h) do { _Pragma("unroll") for (int m = 0; m < 4; ++m) _Pragma("unroll") for (int k = 0; k < 2; ++k) dst[m][k] = *(const LAS bf16x8*)(lds + PG8_SA(b, h) + aoff + m * 2048 + k * 1024); } while (0)
; #define PG8_LDB(dst, b, h) do { _Pragma("unroll") for (int n = 0; n < 2; ++n) _Pragma("unroll") for (int k = 0; k < 2; ++k) dst[n][k] = *(const LAS bf16x8*)(lds + PG8_SB(b, h) + boff + n * 2048 + k * 1024); } while (0)
; #define PG8_MMA(ai, bj, At, Bt) do { __builtin_amdgcn_s_setprio(1); _Pragma("unroll") for (int m = 0; m < 4; ++m) _Pragma("unroll") for (int n = 0; n < 2; ++n) _Pragma("unroll") for (int k = 0; k < 2; ++k) \
;         acc[ai][bj][m][n] = __builtin_amdgcn_mfma_f32_16x16x32_bf16(Bt[n][k], At[m][k], acc[ai][bj][m][n], 0, 0, 0); __builtin_amdgcn_s_setprio(0); } while (0)
; template <class Epi, class Sched>
; DI void gemm_phase(LAS unsigned char* lds, const int lda2, const int ldb2, const int nt, const Sched& S, const Epi& E) {
;     ...
;         const bool has_next = S.next(ui + 1, nxt);
;         const char* nA = has_next ? nxt.A : cA; const char* nB = has_next ? nxt.B : cB;
;         for (int t = 0; t < nt; t += 2) {
;             const bool last = (t == nt - 2);
;             const char* a1 = cA + (size_t)(t + 1) * kstep;
;             const char* a2 = last ? nA : cA + (size_t)(t + 2) * kstep; const char* b2 = last ? nB : cB + (size_t)(t + 2) * kstep;
;             const char* a3 = a2 + kstep; const char* b3 = b2 + kstep;
;             PG8_LDB(B0, 0, 0); PG8_LDB(B1, 0, 1); PG8_SCHED; PG8_LDA(At, 0, 0); PG8_STAGE(PG8_SA(1, 1), a1 + hstepA, vA0, vA1);
;     ...
;             PG8_WAIT_V(8); PG8_WAIT_L(0); PG8_BAR; PG8_MMA(0, 0, At, B0); PG8_MMA(0, 1, At, B1); PG8_BAR; PG8_SCHED;
;             PG8_LDA(At, 1, 1); PG8_STAGE(PG8_SB(1, 0), b3, vB0, vB1); PG8_STAGE(PG8_SB(1, 1), b3 + hstepB, vB0, vB1); PG8_STAGE(PG8_SA(1, 0), a3, vA0, vA1);
;             PG8_WAIT_V(8); PG8_WAIT_L(0); PG8_BAR; PG8_MMA(1, 0, At, B0); PG8_MMA(1, 1, At, B1); PG8_BAR; PG8_SCHED;
	s_add_i32 s52, s58, s73
	v_lshl_add_u64 v[144:145], v[144:145], 0, s[86:87]
	s_mov_b32 m0, s52
	ds_read_b128 v[178:181], v149 offset:49152
	ds_read_b128 v[182:185], v149 offset:50176
	ds_read_b128 v[186:189], v149 offset:51200
	ds_read_b128 v[190:193], v149 offset:52224
	ds_read_b128 v[202:205], v149 offset:53248
	ds_read_b128 v[206:209], v149 offset:54272
	ds_read_b128 v[210:213], v149 offset:55296
	ds_read_b128 v[214:217], v149 offset:56320
	global_load_lds_dwordx4 v[144:145], off
	s_add_i32 m0, s52, 0x2000
	s_add_u32 s30, s30, 0xb0080
	v_lshl_add_u64 v[144:145], v[194:195], 0, s[86:87]
	s_addc_u32 s31, s31, 0
	s_add_i32 s52, s59, s73
	global_load_lds_dwordx4 v[144:145], off
	v_lshl_add_u64 v[144:145], s[30:31], 0, v[96:97]
	s_mov_b32 m0, s52
	s_nop 0
	global_load_lds_dwordx4 v[144:145], off
	v_lshl_add_u64 v[144:145], s[30:31], 0, v[130:131]
	s_add_i32 m0, s52, 0x2000
	s_nop 0
	global_load_lds_dwordx4 v[144:145], off
	v_lshl_add_u64 v[144:145], v[218:219], 0, s[86:87]
	s_mov_b32 m0, s81
	s_nop 0
	global_load_lds_dwordx4 v[144:145], off
	v_lshl_add_u64 v[144:145], v[220:221], 0, s[86:87]
	s_mov_b32 m0, s82
	s_nop 0
	global_load_lds_dwordx4 v[144:145], off
	s_waitcnt vmcnt(8)
	s_waitcnt lgkmcnt(0)
	s_barrier
	s_setprio 1
	s_waitcnt lgkmcnt(0)
	v_mfma_f32_16x16x32_bf16 v[60:63], v[140:143], v[178:181], v[60:63]
	v_mfma_f32_16x16x32_bf16 v[56:59], v[154:157], v[178:181], v[56:59]
	v_mfma_f32_16x16x32_bf16 v[40:43], v[154:157], v[186:189], v[40:43]
	v_mfma_f32_16x16x32_bf16 v[44:47], v[140:143], v[186:189], v[44:47]
	v_mfma_f32_16x16x32_bf16 v[28:31], v[140:143], v[202:205], v[28:31]
	v_mfma_f32_16x16x32_bf16 v[24:27], v[154:157], v[202:205], v[24:27]
	v_mfma_f32_16x16x32_bf16 v[8:11], v[154:157], v[210:213], v[8:11]
	v_mfma_f32_16x16x32_bf16 v[12:15], v[140:143], v[210:213], v[12:15]
	v_mfma_f32_16x16x32_bf16 v[60:63], v[150:153], v[182:185], v[60:63]
	v_mfma_f32_16x16x32_bf16 v[56:59], v[158:161], v[182:185], v[56:59]
	v_mfma_f32_16x16x32_bf16 v[40:43], v[158:161], v[190:193], v[40:43]
	v_mfma_f32_16x16x32_bf16 v[44:47], v[150:153], v[190:193], v[44:47]
	v_mfma_f32_16x16x32_bf16 v[28:31], v[150:153], v[206:209], v[28:31]
	v_mfma_f32_16x16x32_bf16 v[24:27], v[158:161], v[206:209], v[24:27]
	v_mfma_f32_16x16x32_bf16 v[8:11], v[158:161], v[214:217], v[8:11]
	v_mfma_f32_16x16x32_bf16 v[12:15], v[150:153], v[214:217], v[12:15]
	s_setprio 0
	s_setprio 1
	v_mfma_f32_16x16x32_bf16 v[52:55], v[162:165], v[178:181], v[52:55]
	v_mfma_f32_16x16x32_bf16 v[48:51], v[170:173], v[178:181], v[48:51]
	v_mfma_f32_16x16x32_bf16 v[32:35], v[170:173], v[186:189], v[32:35]
	v_mfma_f32_16x16x32_bf16 v[36:39], v[162:165], v[186:189], v[36:39]
	v_mfma_f32_16x16x32_bf16 v[20:23], v[162:165], v[202:205], v[20:23]
	v_mfma_f32_16x16x32_bf16 v[16:19], v[170:173], v[202:205], v[16:19]
	v_mfma_f32_16x16x32_bf16 v[0:3], v[170:173], v[210:213], v[0:3]
	v_mfma_f32_16x16x32_bf16 v[4:7], v[162:165], v[210:213], v[4:7]
	v_mfma_f32_16x16x32_bf16 v[52:55], v[166:169], v[182:185], v[52:55]
	v_mfma_f32_16x16x32_bf16 v[48:51], v[174:177], v[182:185], v[48:51]
	v_mfma_f32_16x16x32_bf16 v[32:35], v[174:177], v[190:193], v[32:35]
	v_mfma_f32_16x16x32_bf16 v[36:39], v[166:169], v[190:193], v[36:39]
	v_mfma_f32_16x16x32_bf16 v[20:23], v[166:169], v[206:209], v[20:23]
	v_mfma_f32_16x16x32_bf16 v[16:19], v[174:177], v[206:209], v[16:19]
	v_mfma_f32_16x16x32_bf16 v[0:3], v[174:177], v[214:217], v[0:3]
	v_mfma_f32_16x16x32_bf16 v[4:7], v[166:169], v[214:217], v[4:7]
	s_setprio 0
	s_barrier
	s_add_i32 s57, s57, 2
	s_add_u32 s28, s28, 0x100
	s_addc_u32 s29, s29, 0
	s_add_u32 s1, s1, 0x100
	s_addc_u32 s10, s10, 0
.LBB0_1124:
	s_add_u32 s30, s28, 0xfff50080
	s_addc_u32 s31, s29, -1
	s_add_i32 vcc_lo, 0, 0x10000
	s_cmp_eq_u32 s57, 40
	s_cselect_b32 s53, s25, s31
	s_cselect_b32 s52, s24, s30
	v_add_u32_e32 v144, vcc_lo, v148
	s_cselect_b32 s31, s27, s10
	s_cselect_b32 s30, s26, s1
	s_add_i32 s58, 0, 0x14000
	ds_read_b128 v[140:143], v144
	ds_read_b128 v[150:153], v144 offset:1024
	ds_read_b128 v[154:157], v144 offset:2048
	ds_read_b128 v[158:161], v144 offset:3072
	v_add_u32_e32 v144, s58, v148
	ds_read_b128 v[162:165], v144
	ds_read_b128 v[166:169], v144 offset:1024
	ds_read_b128 v[170:173], v144 offset:2048
	ds_read_b128 v[174:177], v144 offset:3072
	v_lshl_add_u64 v[144:145], s[28:29], 0, v[136:137]
	s_add_i32 m0, s74, 0xc000
	ds_read_b128 v[178:181], v149
	ds_read_b128 v[182:185], v149 offset:1024
	ds_read_b128 v[186:189], v149 offset:2048
	ds_read_b128 v[190:193], v149 offset:3072
	ds_read_b128 v[202:205], v149 offset:4096
	ds_read_b128 v[206:209], v149 offset:5120
	ds_read_b128 v[210:213], v149 offset:6144
	ds_read_b128 v[214:217], v149 offset:7168
	global_load_lds_dwordx4 v[144:145], off
	v_lshl_add_u64 v[144:145], s[28:29], 0, v[138:139]
	s_add_i32 m0, s74, 0xe000
	s_nop 0
	global_load_lds_dwordx4 v[144:145], off
	s_waitcnt vmcnt(8)
	s_waitcnt lgkmcnt(0)
	s_barrier
; #define PG8_STAGE(bufoff, gbase, V0, V1) do { \
;         __builtin_amdgcn_global_load_lds((const unsigned*)((const char*)(gbase) + (V0)), (LAS unsigned*)(lds + (bufoff) + ldsw), 16, 0, 0); \
;         __builtin_amdgcn_global_load_lds((const unsigned*)((const char*)(gbase) + (V1)), (LAS unsigned*)(lds + (bufoff) + ldsw + 8192), 16, 0, 0); } while (0)
; #define PG8_LDA(dst, b, h) do { _Pragma("unroll") for (int m = 0; m < 4; ++m) _Pragma("unroll") for (int k = 0; k < 2; ++k) dst[m][k] = *(const LAS bf16x8*)(lds + PG8_SA(b, h) + aoff + m * 2048 + k * 1024); } while (0)
; #define PG8_LDB(dst, b, h) do { _Pragma("unroll") for (int n = 0; n < 2; ++n) _Pragma("unroll") for (int k = 0; k < 2; ++k) dst[n][k] = *(const LAS bf16x8*)(lds + PG8_SB(b, h) + boff + n * 2048 + k * 1024); } while (0)
; #define PG8_MMA(ai, bj, At, Bt) do { __builtin_amdgcn_s_setprio(1); _Pragma("unroll") for (int m = 0; m < 4; ++m) _Pragma("unroll") for (int n = 0; n < 2; ++n) _Pragma("unroll") for (int k = 0; k < 2; ++k) \
;         acc[ai][bj][m][n] = __builtin_amdgcn_mfma_f32_16x16x32_bf16(Bt[n][k], At[m][k], acc[ai][bj][m][n], 0, 0, 0); __builtin_amdgcn_s_setprio(0); } while (0)
; #define PG8_WAIT_V(n) asm volatile("s_waitcnt vmcnt(" #n ")" ::: "memory")
; #define PG8_WAIT_L(n) asm volatile("s_waitcnt lgkmcnt(" #n ")" ::: "memory")
; #define PG8_BAR __builtin_amdgcn_s_barrier()
; #define PG8_SCHED __builtin_amdgcn_sched_barrier(0)
; template <class Epi, class Sched>
; DI void gemm_phase(LAS unsigned char* lds, const int lda2, const int ldb2, const int nt, const Sched& S, const Epi& E) {
;     ...
;             PG8_LDB(B0, 0, 0); PG8_LDB(B1, 0, 1); PG8_SCHED; PG8_LDA(At, 0, 0); PG8_STAGE(PG8_SA(1, 1), a1 + hstepA, vA0, vA1);
;             PG8_WAIT_V(8); PG8_WAIT_L(0); PG8_BAR; PG8_MMA(0, 0, At, B0); PG8_MMA(0, 1, At, B1); PG8_BAR; PG8_SCHED;
;             PG8_LDA(At, 0, 1); PG8_STAGE(PG8_SB(0, 0), b2, vB0, vB1); PG8_STAGE(PG8_SB(0, 1), b2 + hstepB, vB0, vB1); PG8_STAGE(PG8_SA(0, 0), a2, vA0, vA1);
;             PG8_WAIT_V(8); PG8_WAIT_L(0); PG8_BAR; PG8_MMA(1, 0, At, B0); PG8_MMA(1, 1, At, B1); PG8_BAR; PG8_SCHED;
	s_setprio 1
	s_waitcnt lgkmcnt(0)
	v_mfma_f32_16x16x32_bf16 v[126:129], v[140:143], v[178:181], v[126:129]
	v_mfma_f32_16x16x32_bf16 v[122:125], v[154:157], v[178:181], v[122:125]
	v_mfma_f32_16x16x32_bf16 v[106:109], v[154:157], v[186:189], v[106:109]
	v_mfma_f32_16x16x32_bf16 v[110:113], v[140:143], v[186:189], v[110:113]
	v_mfma_f32_16x16x32_bf16 v[92:95], v[140:143], v[202:205], v[92:95]
	v_mfma_f32_16x16x32_bf16 v[88:91], v[154:157], v[202:205], v[88:91]
	v_mfma_f32_16x16x32_bf16 v[72:75], v[154:157], v[210:213], v[72:75]
	v_mfma_f32_16x16x32_bf16 v[76:79], v[140:143], v[210:213], v[76:79]
	v_mfma_f32_16x16x32_bf16 v[126:129], v[150:153], v[182:185], v[126:129]
	v_mfma_f32_16x16x32_bf16 v[122:125], v[158:161], v[182:185], v[122:125]
	v_mfma_f32_16x16x32_bf16 v[106:109], v[158:161], v[190:193], v[106:109]
	v_mfma_f32_16x16x32_bf16 v[110:113], v[150:153], v[190:193], v[110:113]
	v_mfma_f32_16x16x32_bf16 v[92:95], v[150:153], v[206:209], v[92:95]
	v_mfma_f32_16x16x32_bf16 v[88:91], v[158:161], v[206:209], v[88:91]
	v_mfma_f32_16x16x32_bf16 v[72:75], v[158:161], v[214:217], v[72:75]
	v_mfma_f32_16x16x32_bf16 v[76:79], v[150:153], v[214:217], v[76:79]
	s_setprio 0
	s_setprio 1
	v_mfma_f32_16x16x32_bf16 v[118:121], v[162:165], v[178:181], v[118:121]
	v_mfma_f32_16x16x32_bf16 v[114:117], v[170:173], v[178:181], v[114:117]
	v_mfma_f32_16x16x32_bf16 v[98:101], v[170:173], v[186:189], v[98:101]
	v_mfma_f32_16x16x32_bf16 v[102:105], v[162:165], v[186:189], v[102:105]
	v_mfma_f32_16x16x32_bf16 v[84:87], v[162:165], v[202:205], v[84:87]
	v_mfma_f32_16x16x32_bf16 v[80:83], v[170:173], v[202:205], v[80:83]
	v_mfma_f32_16x16x32_bf16 v[64:67], v[170:173], v[210:213], v[64:67]
	v_mfma_f32_16x16x32_bf16 v[68:71], v[162:165], v[210:213], v[68:71]
	v_mfma_f32_16x16x32_bf16 v[118:121], v[166:169], v[182:185], v[118:121]
	v_mfma_f32_16x16x32_bf16 v[114:117], v[174:177], v[182:185], v[114:117]
	v_mfma_f32_16x16x32_bf16 v[98:101], v[174:177], v[190:193], v[98:101]
	v_mfma_f32_16x16x32_bf16 v[102:105], v[166:169], v[190:193], v[102:105]
	v_mfma_f32_16x16x32_bf16 v[84:87], v[166:169], v[206:209], v[84:87]
	v_mfma_f32_16x16x32_bf16 v[80:83], v[174:177], v[206:209], v[80:83]
	v_mfma_f32_16x16x32_bf16 v[64:67], v[174:177], v[214:217], v[64:67]
	v_mfma_f32_16x16x32_bf16 v[68:71], v[166:169], v[214:217], v[68:71]
	s_setprio 0
	s_barrier
	s_add_i32 s59, vcc_lo, s73
	v_lshl_add_u64 v[144:145], s[30:31], 0, v[96:97]
	s_mov_b32 m0, s59
	ds_read_b128 v[178:181], v149 offset:16384
	ds_read_b128 v[182:185], v149 offset:17408
	ds_read_b128 v[186:189], v149 offset:18432
	ds_read_b128 v[190:193], v149 offset:19456
	ds_read_b128 v[202:205], v149 offset:20480
	ds_read_b128 v[206:209], v149 offset:21504
	ds_read_b128 v[210:213], v149 offset:22528
	ds_read_b128 v[214:217], v149 offset:23552
	global_load_lds_dwordx4 v[144:145], off
	s_add_i32 m0, s59, 0x2000
	s_add_u32 vcc_lo, s30, 0xb0000
	v_lshl_add_u64 v[194:195], s[30:31], 0, v[130:131]
	s_addc_u32 vcc_hi, s31, 0
	s_add_i32 s58, s58, s73
	global_load_lds_dwordx4 v[194:195], off
	v_lshl_add_u64 v[218:219], vcc, 0, v[96:97]
	s_mov_b32 m0, s58
	v_lshl_add_u64 v[220:221], s[52:53], 0, v[134:135]
	global_load_lds_dwordx4 v[218:219], off
	v_lshl_add_u64 v[218:219], vcc, 0, v[130:131]
	s_add_i32 m0, s58, 0x2000
	s_nop 0
	global_load_lds_dwordx4 v[218:219], off
	v_lshl_add_u64 v[218:219], s[52:53], 0, v[132:133]
	s_mov_b32 m0, s74
	s_nop 0
	global_load_lds_dwordx4 v[218:219], off
	s_mov_b32 m0, s75
	s_nop 0
	global_load_lds_dwordx4 v[220:221], off
	s_waitcnt vmcnt(8)
	s_waitcnt lgkmcnt(0)
	s_barrier
	s_setprio 1
	s_waitcnt lgkmcnt(0)
	v_mfma_f32_16x16x32_bf16 v[60:63], v[140:143], v[178:181], v[60:63]
	v_mfma_f32_16x16x32_bf16 v[56:59], v[154:157], v[178:181], v[56:59]
	v_mfma_f32_16x16x32_bf16 v[40:43], v[154:157], v[186:189], v[40:43]
	v_mfma_f32_16x16x32_bf16 v[44:47], v[140:143], v[186:189], v[44:47]
	v_mfma_f32_16x16x32_bf16 v[28:31], v[140:143], v[202:205], v[28:31]
	v_mfma_f32_16x16x32_bf16 v[24:27], v[154:157], v[202:205], v[24:27]
	v_mfma_f32_16x16x32_bf16 v[8:11], v[154:157], v[210:213], v[8:11]
	v_mfma_f32_16x16x32_bf16 v[12:15], v[140:143], v[210:213], v[12:15]
	v_mfma_f32_16x16x32_bf16 v[60:63], v[150:153], v[182:185], v[60:63]
	v_mfma_f32_16x16x32_bf16 v[56:59], v[158:161], v[182:185], v[56:59]
	v_mfma_f32_16x16x32_bf16 v[40:43], v[158:161], v[190:193], v[40:43]
	v_mfma_f32_16x16x32_bf16 v[44:47], v[150:153], v[190:193], v[44:47]
	v_mfma_f32_16x16x32_bf16 v[28:31], v[150:153], v[206:209], v[28:31]
	v_mfma_f32_16x16x32_bf16 v[24:27], v[158:161], v[206:209], v[24:27]
	v_mfma_f32_16x16x32_bf16 v[8:11], v[158:161], v[214:217], v[8:11]
	v_mfma_f32_16x16x32_bf16 v[12:15], v[150:153], v[214:217], v[12:15]
	s_setprio 0
	s_setprio 1
	v_mfma_f32_16x16x32_bf16 v[52:55], v[162:165], v[178:181], v[52:55]
	v_mfma_f32_16x16x32_bf16 v[48:51], v[170:173], v[178:181], v[48:51]
	v_mfma_f32_16x16x32_bf16 v[32:35], v[170:173], v[186:189], v[32:35]
	v_mfma_f32_16x16x32_bf16 v[36:39], v[162:165], v[186:189], v[36:39]
	v_mfma_f32_16x16x32_bf16 v[20:23], v[162:165], v[202:205], v[20:23]
	v_mfma_f32_16x16x32_bf16 v[16:19], v[170:173], v[202:205], v[16:19]
	v_mfma_f32_16x16x32_bf16 v[0:3], v[170:173], v[210:213], v[0:3]
	v_mfma_f32_16x16x32_bf16 v[4:7], v[162:165], v[210:213], v[4:7]
	v_mfma_f32_16x16x32_bf16 v[52:55], v[166:169], v[182:185], v[52:55]
	v_mfma_f32_16x16x32_bf16 v[48:51], v[174:177], v[182:185], v[48:51]
	v_mfma_f32_16x16x32_bf16 v[32:35], v[174:177], v[190:193], v[32:35]
	v_mfma_f32_16x16x32_bf16 v[36:39], v[166:169], v[190:193], v[36:39]
	v_mfma_f32_16x16x32_bf16 v[20:23], v[166:169], v[206:209], v[20:23]
	v_mfma_f32_16x16x32_bf16 v[16:19], v[174:177], v[206:209], v[16:19]
	v_mfma_f32_16x16x32_bf16 v[0:3], v[174:177], v[214:217], v[0:3]
	v_mfma_f32_16x16x32_bf16 v[4:7], v[166:169], v[214:217], v[4:7]
	s_setprio 0
	s_barrier
; #define PG8_STAGE(bufoff, gbase, V0, V1) do { \
;         __builtin_amdgcn_global_load_lds((const unsigned*)((const char*)(gbase) + (V0)), (LAS unsigned*)(lds + (bufoff) + ldsw), 16, 0, 0); \
;         __builtin_amdgcn_global_load_lds((const unsigned*)((const char*)(gbase) + (V1)), (LAS unsigned*)(lds + (bufoff) + ldsw + 8192), 16, 0, 0); } while (0)
; #define PG8_LDA(dst, b, h) do { _Pragma("unroll") for (int m = 0; m < 4; ++m) _Pragma("unroll") for (int k = 0; k < 2; ++k) dst[m][k] = *(const LAS bf16x8*)(lds + PG8_SA(b, h) + aoff + m * 2048 + k * 1024); } while (0)
; #define PG8_LDB(dst, b, h) do { _Pragma("unroll") for (int n = 0; n < 2; ++n) _Pragma("unroll") for (int k = 0; k < 2; ++k) dst[n][k] = *(const LAS bf16x8*)(lds + PG8_SB(b, h) + boff + n * 2048 + k * 1024); } while (0)
; #define PG8_MMA(ai, bj, At, Bt) do { __builtin_amdgcn_s_setprio(1); _Pragma("unroll") for (int m = 0; m < 4; ++m) _Pragma("unroll") for (int n = 0; n < 2; ++n) _Pragma("unroll") for (int k = 0; k < 2; ++k) \
;         acc[ai][bj][m][n] = __builtin_amdgcn_mfma_f32_16x16x32_bf16(Bt[n][k], At[m][k], acc[ai][bj][m][n], 0, 0, 0); __builtin_amdgcn_s_setprio(0); } while (0)
; #define PG8_WAIT_V(n) asm volatile("s_waitcnt vmcnt(" #n ")" ::: "memory")
; #define PG8_WAIT_L(n) asm volatile("s_waitcnt lgkmcnt(" #n ")" ::: "memory")
; #define PG8_BAR __builtin_amdgcn_s_barrier()
; #define PG8_SCHED __builtin_amdgcn_sched_barrier(0)
; template <class Epi, class Sched>
; DI void gemm_phase(LAS unsigned char* lds, const int lda2, const int ldb2, const int nt, const Sched& S, const Epi& E) {
;     ...
;             PG8_LDB(B0, 1, 0); PG8_LDB(B1, 1, 1); PG8_SCHED; PG8_LDA(At, 1, 0); PG8_STAGE(PG8_SA(0, 1), a2 + hstepA, vA0, vA1);
;             PG8_WAIT_V(8); PG8_WAIT_L(0); PG8_BAR; PG8_MMA(0, 0, At, B0); PG8_MMA(0, 1, At, B1); PG8_BAR; PG8_SCHED;
	s_add_i32 s58, 0, 0x18000
	s_add_i32 s59, 0, 0x1c000
	v_add_u32_e32 v158, s58, v148
	v_add_u32_e32 v174, s59, v148
	ds_read_b128 v[140:143], v158
	ds_read_b128 v[150:153], v158 offset:1024
	ds_read_b128 v[154:157], v158 offset:2048
	ds_read_b128 v[158:161], v158 offset:3072
	ds_read_b128 v[162:165], v174
	ds_read_b128 v[166:169], v174 offset:1024
	ds_read_b128 v[170:173], v174 offset:2048
	ds_read_b128 v[174:177], v174 offset:3072
	s_add_u32 s52, s52, 0xb0000
	s_addc_u32 s53, s53, 0
	s_mov_b32 m0, s76
	v_lshl_add_u64 v[222:223], s[52:53], 0, v[132:133]
	ds_read_b128 v[178:181], v149 offset:32768
	ds_read_b128 v[182:185], v149 offset:33792
	ds_read_b128 v[186:189], v149 offset:34816
	ds_read_b128 v[190:193], v149 offset:35840
	ds_read_b128 v[202:205], v149 offset:36864
	ds_read_b128 v[206:209], v149 offset:37888
	ds_read_b128 v[210:213], v149 offset:38912
	ds_read_b128 v[214:217], v149 offset:39936
	global_load_lds_dwordx4 v[222:223], off
	v_lshl_add_u64 v[222:223], s[52:53], 0, v[134:135]
	s_mov_b32 m0, s77
	s_nop 0
	global_load_lds_dwordx4 v[222:223], off
	s_waitcnt vmcnt(8)
	s_waitcnt lgkmcnt(0)
	s_barrier
	s_setprio 1
	s_waitcnt lgkmcnt(0)
	v_mfma_f32_16x16x32_bf16 v[126:129], v[140:143], v[178:181], v[126:129]
	v_mfma_f32_16x16x32_bf16 v[122:125], v[154:157], v[178:181], v[122:125]
	v_mfma_f32_16x16x32_bf16 v[106:109], v[154:157], v[186:189], v[106:109]
	v_mfma_f32_16x16x32_bf16 v[110:113], v[140:143], v[186:189], v[110:113]
	v_mfma_f32_16x16x32_bf16 v[92:95], v[140:143], v[202:205], v[92:95]
	v_mfma_f32_16x16x32_bf16 v[88:91], v[154:157], v[202:205], v[88:91]
	v_mfma_f32_16x16x32_bf16 v[72:75], v[154:157], v[210:213], v[72:75]
	v_mfma_f32_16x16x32_bf16 v[76:79], v[140:143], v[210:213], v[76:79]
	v_mfma_f32_16x16x32_bf16 v[126:129], v[150:153], v[182:185], v[126:129]
	v_mfma_f32_16x16x32_bf16 v[122:125], v[158:161], v[182:185], v[122:125]
	v_mfma_f32_16x16x32_bf16 v[106:109], v[158:161], v[190:193], v[106:109]
	v_mfma_f32_16x16x32_bf16 v[110:113], v[150:153], v[190:193], v[110:113]
	v_mfma_f32_16x16x32_bf16 v[92:95], v[150:153], v[206:209], v[92:95]
	v_mfma_f32_16x16x32_bf16 v[88:91], v[158:161], v[206:209], v[88:91]
	v_mfma_f32_16x16x32_bf16 v[72:75], v[158:161], v[214:217], v[72:75]
	v_mfma_f32_16x16x32_bf16 v[76:79], v[150:153], v[214:217], v[76:79]
	s_setprio 0
	s_setprio 1
	v_mfma_f32_16x16x32_bf16 v[118:121], v[162:165], v[178:181], v[118:121]
	v_mfma_f32_16x16x32_bf16 v[114:117], v[170:173], v[178:181], v[114:117]
	v_mfma_f32_16x16x32_bf16 v[98:101], v[170:173], v[186:189], v[98:101]
	v_mfma_f32_16x16x32_bf16 v[102:105], v[162:165], v[186:189], v[102:105]
	v_mfma_f32_16x16x32_bf16 v[84:87], v[162:165], v[202:205], v[84:87]
	v_mfma_f32_16x16x32_bf16 v[80:83], v[170:173], v[202:205], v[80:83]
	v_mfma_f32_16x16x32_bf16 v[64:67], v[170:173], v[210:213], v[64:67]
	v_mfma_f32_16x16x32_bf16 v[68:71], v[162:165], v[210:213], v[68:71]
	v_mfma_f32_16x16x32_bf16 v[118:121], v[166:169], v[182:185], v[118:121]
	v_mfma_f32_16x16x32_bf16 v[114:117], v[174:177], v[182:185], v[114:117]
	v_mfma_f32_16x16x32_bf16 v[98:101], v[174:177], v[190:193], v[98:101]
	v_mfma_f32_16x16x32_bf16 v[102:105], v[166:169], v[190:193], v[102:105]
	v_mfma_f32_16x16x32_bf16 v[84:87], v[166:169], v[206:209], v[84:87]
	v_mfma_f32_16x16x32_bf16 v[80:83], v[174:177], v[206:209], v[80:83]
	v_mfma_f32_16x16x32_bf16 v[64:67], v[174:177], v[214:217], v[64:67]
	v_mfma_f32_16x16x32_bf16 v[68:71], v[166:169], v[214:217], v[68:71]
	s_setprio 0
	s_barrier
; #define PG8_STAGE(bufoff, gbase, V0, V1) do { \
;         __builtin_amdgcn_global_load_lds((const unsigned*)((const char*)(gbase) + (V0)), (LAS unsigned*)(lds + (bufoff) + ldsw), 16, 0, 0); \
;         __builtin_amdgcn_global_load_lds((const unsigned*)((const char*)(gbase) + (V1)), (LAS unsigned*)(lds + (bufoff) + ldsw + 8192), 16, 0, 0); } while (0)
; #define PG8_LDA(dst, b, h) do { _Pragma("unroll") for (int m = 0; m < 4; ++m) _Pragma("unroll") for (int k = 0; k < 2; ++k) dst[m][k] = *(const LAS bf16x8*)(lds + PG8_SA(b, h) + aoff + m * 2048 + k * 1024); } while (0)
; #define PG8_MMA(ai, bj, At, Bt) do { __builtin_amdgcn_s_setprio(1); _Pragma("unroll") for (int m = 0; m < 4; ++m) _Pragma("unroll") for (int n = 0; n < 2; ++n) _Pragma("unroll") for (int k = 0; k < 2; ++k) \
;         acc[ai][bj][m][n] = __builtin_amdgcn_mfma_f32_16x16x32_bf16(Bt[n][k], At[m][k], acc[ai][bj][m][n], 0, 0, 0); __builtin_amdgcn_s_setprio(0); } while (0)
; #define PG8_WAIT_V(n) asm volatile("s_waitcnt vmcnt(" #n ")" ::: "memory")
; #define PG8_WAIT_L(n) asm volatile("s_waitcnt lgkmcnt(" #n ")" ::: "memory")
; #define PG8_BAR __builtin_amdgcn_s_barrier()
; #define PG8_SCHED __builtin_amdgcn_sched_barrier(0)
; template <class Epi, class Sched>
; DI void gemm_phase(LAS unsigned char* lds, const int lda2, const int ldb2, const int nt, const Sched& S, const Epi& E) {
;     ...
;             PG8_LDA(At, 1, 1); PG8_STAGE(PG8_SB(1, 0), b3, vB0, vB1); PG8_STAGE(PG8_SB(1, 1), b3 + hstepB, vB0, vB1); PG8_STAGE(PG8_SA(1, 0), a3, vA0, vA1);
;             PG8_WAIT_V(8); PG8_WAIT_L(0); PG8_BAR; PG8_MMA(1, 0, At, B0); PG8_MMA(1, 1, At, B1); PG8_BAR; PG8_SCHED;
;         }
;         if (wr == 0) PG8_BAR;
	s_add_i32 s52, s58, s73
	v_lshl_add_u64 v[144:145], v[144:145], 0, s[86:87]
	s_mov_b32 m0, s52
	ds_read_b128 v[178:181], v149 offset:49152
	ds_read_b128 v[182:185], v149 offset:50176
	ds_read_b128 v[186:189], v149 offset:51200
	ds_read_b128 v[190:193], v149 offset:52224
	ds_read_b128 v[202:205], v149 offset:53248
	ds_read_b128 v[206:209], v149 offset:54272
	ds_read_b128 v[210:213], v149 offset:55296
	ds_read_b128 v[214:217], v149 offset:56320
	global_load_lds_dwordx4 v[144:145], off
	s_add_i32 m0, s52, 0x2000
	s_add_u32 s30, s30, 0xb0080
	v_lshl_add_u64 v[144:145], v[194:195], 0, s[86:87]
	s_addc_u32 s31, s31, 0
	s_add_i32 s52, s59, s73
	global_load_lds_dwordx4 v[144:145], off
	v_lshl_add_u64 v[144:145], s[30:31], 0, v[96:97]
	s_mov_b32 m0, s52
	s_nop 0
	global_load_lds_dwordx4 v[144:145], off
	v_lshl_add_u64 v[144:145], s[30:31], 0, v[130:131]
	s_add_i32 m0, s52, 0x2000
	s_nop 0
	global_load_lds_dwordx4 v[144:145], off
	v_lshl_add_u64 v[144:145], v[218:219], 0, s[86:87]
	s_mov_b32 m0, s81
	s_nop 0
	global_load_lds_dwordx4 v[144:145], off
	v_lshl_add_u64 v[144:145], v[220:221], 0, s[86:87]
	s_mov_b32 m0, s82
	s_nop 0
	global_load_lds_dwordx4 v[144:145], off
	s_waitcnt vmcnt(8)
	s_waitcnt lgkmcnt(0)
	s_barrier
	s_setprio 1
	s_waitcnt lgkmcnt(0)
	v_mfma_f32_16x16x32_bf16 v[60:63], v[140:143], v[178:181], v[60:63]
	v_mfma_f32_16x16x32_bf16 v[56:59], v[154:157], v[178:181], v[56:59]
	v_mfma_f32_16x16x32_bf16 v[40:43], v[154:157], v[186:189], v[40:43]
	v_mfma_f32_16x16x32_bf16 v[44:47], v[140:143], v[186:189], v[44:47]
	v_mfma_f32_16x16x32_bf16 v[28:31], v[140:143], v[202:205], v[28:31]
	v_mfma_f32_16x16x32_bf16 v[24:27], v[154:157], v[202:205], v[24:27]
	v_mfma_f32_16x16x32_bf16 v[8:11], v[154:157], v[210:213], v[8:11]
	v_mfma_f32_16x16x32_bf16 v[12:15], v[140:143], v[210:213], v[12:15]
	v_mfma_f32_16x16x32_bf16 v[60:63], v[150:153], v[182:185], v[60:63]
	v_mfma_f32_16x16x32_bf16 v[56:59], v[158:161], v[182:185], v[56:59]
	v_mfma_f32_16x16x32_bf16 v[40:43], v[158:161], v[190:193], v[40:43]
	v_mfma_f32_16x16x32_bf16 v[44:47], v[150:153], v[190:193], v[44:47]
	v_mfma_f32_16x16x32_bf16 v[28:31], v[150:153], v[206:209], v[28:31]
	v_mfma_f32_16x16x32_bf16 v[24:27], v[158:161], v[206:209], v[24:27]
	v_mfma_f32_16x16x32_bf16 v[8:11], v[158:161], v[214:217], v[8:11]
	v_mfma_f32_16x16x32_bf16 v[12:15], v[150:153], v[214:217], v[12:15]
	s_setprio 0
	s_setprio 1
	v_mfma_f32_16x16x32_bf16 v[52:55], v[162:165], v[178:181], v[52:55]
	v_mfma_f32_16x16x32_bf16 v[48:51], v[170:173], v[178:181], v[48:51]
	v_mfma_f32_16x16x32_bf16 v[32:35], v[170:173], v[186:189], v[32:35]
	v_mfma_f32_16x16x32_bf16 v[36:39], v[162:165], v[186:189], v[36:39]
	v_mfma_f32_16x16x32_bf16 v[20:23], v[162:165], v[202:205], v[20:23]
	v_mfma_f32_16x16x32_bf16 v[16:19], v[170:173], v[202:205], v[16:19]
	v_mfma_f32_16x16x32_bf16 v[0:3], v[170:173], v[210:213], v[0:3]
	v_mfma_f32_16x16x32_bf16 v[4:7], v[162:165], v[210:213], v[4:7]
	v_mfma_f32_16x16x32_bf16 v[52:55], v[166:169], v[182:185], v[52:55]
	v_mfma_f32_16x16x32_bf16 v[48:51], v[174:177], v[182:185], v[48:51]
	v_mfma_f32_16x16x32_bf16 v[32:35], v[174:177], v[190:193], v[32:35]
	v_mfma_f32_16x16x32_bf16 v[36:39], v[166:169], v[190:193], v[36:39]
	v_mfma_f32_16x16x32_bf16 v[20:23], v[166:169], v[206:209], v[20:23]
	v_mfma_f32_16x16x32_bf16 v[16:19], v[174:177], v[206:209], v[16:19]
	v_mfma_f32_16x16x32_bf16 v[0:3], v[174:177], v[214:217], v[0:3]
	v_mfma_f32_16x16x32_bf16 v[4:7], v[166:169], v[214:217], v[4:7]
	s_setprio 0
	s_barrier
	s_add_i32 s57, s57, 2
	s_add_u32 s28, s28, 0x100
	s_addc_u32 s29, s29, 0
	s_add_u32 s1, s1, 0x100
	s_addc_u32 s10, s10, 0
	s_cmp_gt_u32 s57, 41
	s_cbranch_scc0 .LBB0_1124
	s_and_b64 vcc, exec, s[22:23]
	s_cbranch_vccz .LBB0_1127
	s_barrier
